# sc1 write-through on all 16-byte global stores (cleaner L2 at grid barriers)
# speedup vs baseline: 1.0164x; 1.0164x over previous
; #define LAS __attribute__((address_space(3)))
; #define GAS __attribute__((address_space(1)))
; #define LDS_WAIT() asm volatile("s_waitcnt lgkmcnt(0)" ::: "memory")
; __device__ __forceinline__ unsigned pkh(float lo, float hi) { f32x2 v = {lo, hi}; h16x2 h = __builtin_convertvector(v, h16x2); return __builtin_bit_cast(unsigned, h); }
; __device__ __forceinline__ unsigned pk8(float a, float b, float c, float d) { int w = __builtin_amdgcn_cvt_pk_fp8_f32(a, b, 0, false); w = __builtin_amdgcn_cvt_pk_fp8_f32(c, d, w, true); return (unsigned)w; }
; template <bool FP8>
; __device__ __forceinline__ void p0_transpose_item(const float* W, int K, int N, f16_t* WT, const float* gain, LAS float* scr, int k0, int n0, int dst0, int lane) {
;     ...
;         for (int i = 0; i < 8; ++i) { const int kk = (lane >> 3) + 8 * i; const float gsc = (gain ? gain[k0 + kk] : 1.0f) * (FP8 ? F8_SW : 1.0f);
; #pragma unroll
;             for (int e = 0; e < 4; ++e) scr[kk * 33 + 4 * (lane & 7) + e] = v[i][e] * gsc; } }
;     LDS_WAIT(); asm volatile("" ::: "memory");
;     const int c = lane & 7;
; #pragma unroll
;     for (int j = 0; j < 4; ++j) { const int n = (lane >> 3) + 8 * j; const LAS float* s = scr + (8 * c) * 33 + n;
;         if constexpr (FP8) { u32x2 o; o.x = pk8(s[0 * 33], s[1 * 33], s[2 * 33], s[3 * 33]); o.y = pk8(s[4 * 33], s[5 * 33], s[6 * 33], s[7 * 33]);
;             *(GAS u32x2*)((unsigned char*)WT + (size_t)(dst0 + n) * K + k0 + 8 * c) = o; }
;         else { u32x4 o; o.x = pkh(s[0 * 33], s[1 * 33]); o.y = pkh(s[2 * 33], s[3 * 33]); o.z = pkh(s[4 * 33], s[5 * 33]); o.w = pkh(s[6 * 33], s[7 * 33]);
;             *(GAS u32x4*)(WT + (size_t)(dst0 + n) * K + k0 + 8 * c) = o; } }
;     LDS_WAIT(); asm volatile("" ::: "memory");
.LBB0_11:
	v_add_u32_e32 v11, 0x18c0, v37
	ds_write2_b32 v11, v6, v7 offset1:1
	v_add_u32_e32 v6, 0x18c8, v37
	ds_write2_b32 v6, v8, v9 offset1:1
	s_waitcnt vmcnt(0)
	v_pk_mul_f32 v[2:3], v[2:3], v[10:11] op_sel_hi:[1,0]
	v_add_u32_e32 v6, 0x1ce0, v37
	ds_write2_b32 v6, v2, v3 offset1:1
	v_pk_mul_f32 v[2:3], v[4:5], v[10:11] op_sel_hi:[1,0]
	v_add_u32_e32 v4, 0x1ce8, v37
	ds_write2_b32 v4, v2, v3 offset1:1
	s_waitcnt lgkmcnt(0)
	ds_read2_b32 v[6:7], v47 offset0:33 offset1:41
	ds_read2_b32 v[8:9], v47 offset1:8
	ds_read2_b32 v[10:11], v47 offset0:66 offset1:74
	ds_read2_b32 v[12:13], v47 offset0:99 offset1:107
	ds_read2_b32 v[14:15], v47 offset0:132 offset1:140
	ds_read2_b32 v[16:17], v47 offset0:165 offset1:173
	ds_read2_b32 v[18:19], v47 offset0:198 offset1:206
	ds_read2_b32 v[20:21], v47 offset0:231 offset1:239
	v_add_u32_e32 v24, s12, v34
	v_ashrrev_i32_e32 v25, 31, v24
	v_lshl_add_u64 v[22:23], s[28:29], 1, v[44:45]
	v_lshlrev_b64 v[26:27], 11, v[24:25]
	s_waitcnt lgkmcnt(0)
	v_cvt_pk_f16_f32 v2, v8, v6
	v_cvt_pk_f16_f32 v3, v10, v12
	v_cvt_pk_f16_f32 v4, v14, v16
	v_cvt_pk_f16_f32 v5, v18, v20
	v_lshl_add_u64 v[26:27], v[22:23], 0, v[26:27]
	v_add_u32_e32 v6, 8, v24
	global_store_dwordx4 v[26:27], v[2:5], off sc1
	s_add_i32 s25, s25, s24
	s_add_i32 s34, s34, s35
	v_cvt_pk_f16_f32 v2, v9, v7
	v_ashrrev_i32_e32 v7, 31, v6
	v_cvt_pk_f16_f32 v3, v11, v13
	v_cvt_pk_f16_f32 v4, v15, v17
	v_cvt_pk_f16_f32 v5, v19, v21
	v_lshlrev_b64 v[6:7], 11, v[6:7]
	ds_read2_b32 v[8:9], v47 offset0:49 offset1:57
	ds_read2_b32 v[10:11], v47 offset0:16 offset1:24
	ds_read2_b32 v[12:13], v47 offset0:82 offset1:90
	ds_read2_b32 v[14:15], v47 offset0:115 offset1:123
	ds_read2_b32 v[16:17], v47 offset0:148 offset1:156
	ds_read2_b32 v[18:19], v47 offset0:181 offset1:189
	ds_read2_b32 v[20:21], v47 offset0:214 offset1:222
	ds_read2_b32 v[26:27], v47 offset0:247 offset1:255
	v_lshl_add_u64 v[6:7], v[22:23], 0, v[6:7]
	global_store_dwordx4 v[6:7], v[2:5], off sc1
	v_add_u32_e32 v6, 16, v24
	v_ashrrev_i32_e32 v7, 31, v6
	v_lshlrev_b64 v[6:7], 11, v[6:7]
	s_waitcnt lgkmcnt(6)
	v_cvt_pk_f16_f32 v2, v10, v8
	s_waitcnt lgkmcnt(4)
	v_cvt_pk_f16_f32 v3, v12, v14
	s_waitcnt lgkmcnt(2)
	v_cvt_pk_f16_f32 v4, v16, v18
	s_waitcnt lgkmcnt(0)
	v_cvt_pk_f16_f32 v5, v20, v26
	v_lshl_add_u64 v[6:7], v[22:23], 0, v[6:7]
	global_store_dwordx4 v[6:7], v[2:5], off sc1
	v_add_u32_e32 v6, 24, v24
	v_ashrrev_i32_e32 v7, 31, v6
	v_lshlrev_b64 v[6:7], 11, v[6:7]
	v_cvt_pk_f16_f32 v2, v11, v9
	v_cvt_pk_f16_f32 v3, v13, v15
	v_cvt_pk_f16_f32 v4, v17, v19
	v_cvt_pk_f16_f32 v5, v21, v27
	v_lshl_add_u64 v[6:7], v[22:23], 0, v[6:7]
	global_store_dwordx4 v[6:7], v[2:5], off sc1
	s_waitcnt lgkmcnt(0)
	s_cmpk_lt_i32 s25, 0x380
	s_cbranch_scc0 .LBB0_23

; #define LAS __attribute__((address_space(3)))
; #define GAS __attribute__((address_space(1)))
; #define LDS_WAIT() asm volatile("s_waitcnt lgkmcnt(0)" ::: "memory")
; __device__ __forceinline__ unsigned pkh(float lo, float hi) { f32x2 v = {lo, hi}; h16x2 h = __builtin_convertvector(v, h16x2); return __builtin_bit_cast(unsigned, h); }
; __device__ __forceinline__ int map_heads(int n0) { const int t = n0 >> 8, l = n0 & 255, wc = l >> 6, bj = (l >> 5) & 1; return (t << 8) + 128 * bj + 32 * wc; }
; template <bool FP8>
; __device__ __forceinline__ void p0_transpose_item(const float* W, int K, int N, f16_t* WT, const float* gain, LAS float* scr, int k0, int n0, int dst0, int lane) {
;     ...
;         for (int i = 0; i < 8; ++i) v[i] = __builtin_nontemporal_load((const f32x4*)(W + (size_t)(k0 + (lane >> 3) + 8 * i) * N + n0 + 4 * (lane & 7)));
; #pragma unroll
;         for (int i = 0; i < 8; ++i) { const int kk = (lane >> 3) + 8 * i; const float gsc = (gain ? gain[k0 + kk] : 1.0f) * (FP8 ? F8_SW : 1.0f);
; #pragma unroll
;             for (int e = 0; e < 4; ++e) scr[kk * 33 + 4 * (lane & 7) + e] = v[i][e] * gsc; } }
;     LDS_WAIT(); asm volatile("" ::: "memory");
;     const int c = lane & 7;
; #pragma unroll
;     for (int j = 0; j < 4; ++j) { const int n = (lane >> 3) + 8 * j; const LAS float* s = scr + (8 * c) * 33 + n;
;         if constexpr (FP8) { u32x2 o; o.x = pk8(s[0 * 33], s[1 * 33], s[2 * 33], s[3 * 33]); o.y = pk8(s[4 * 33], s[5 * 33], s[6 * 33], s[7 * 33]);
;             *(GAS u32x2*)((unsigned char*)WT + (size_t)(dst0 + n) * K + k0 + 8 * c) = o; }
;         else { u32x4 o; o.x = pkh(s[0 * 33], s[1 * 33]); o.y = pkh(s[2 * 33], s[3 * 33]); o.z = pkh(s[4 * 33], s[5 * 33]); o.w = pkh(s[6 * 33], s[7 * 33]);
;             *(GAS u32x4*)(WT + (size_t)(dst0 + n) * K + k0 + 8 * c) = o; } }
;     LDS_WAIT(); asm volatile("" ::: "memory");
; template <int MAP, bool FP8 = false>
; __device__ __forceinline__ void p0_matrix(const Frame& F, const float* W, int K, int N, f16_t* WT, const float* gain, int& base, int gw, int NGW, LAS float* scr) {
;     ...
;     for (int it = first; it < items; it += NGW) {
;         const int kb = it / nblk, nb = it % nblk, n0 = 32 * nb;
;         const int d0 = (MAP == 0) ? map_ident(n0) : (MAP == 1) ? map_heads(n0) : map_up(n0);
;         p0_transpose_item<FP8>(W, K, N, WT, gain, scr, 64 * kb, n0, d0, F.lane);
.LBB0_31:
	s_mul_hi_i32 s8, s27, 0x2e8ba2e9
	s_lshr_b32 s9, s8, 31
	s_ashr_i32 s8, s8, 5
	s_add_i32 s8, s8, s9
	s_mul_i32 s9, s8, 0xffffff50
	s_mul_i32 s12, s8, 0xffffea00
	s_add_i32 s9, s27, s9
	s_add_i32 s12, s28, s12
	s_cmpk_gt_i32 s9, 0x57
	s_cselect_b32 s9, 0xfffff500, 0
	s_cselect_b32 s31, 0x80, 0
	s_lshl_b32 s8, s8, 6
	s_ashr_i32 s13, s12, 31
	v_or_b32_e32 v28, s8, v34
	v_lshl_add_u64 v[30:31], s[12:13], 2, v[2:3]
	v_or_b32_e32 v32, s8, v45
	v_or_b32_e32 v40, s8, v46
	v_or_b32_e32 v42, s8, v48
	v_or_b32_e32 v50, s8, v8
	v_or_b32_e32 v52, s8, v9
	v_or_b32_e32 v54, s8, v10
	s_and_b32 s34, s12, 0x60
	s_add_i32 s35, s12, s9
	v_or_b32_e32 v56, s8, v11
	v_ashrrev_i32_e32 v29, 31, v28
	v_mad_i64_i32 v[24:25], s[12:13], v28, s30, v[30:31]
	v_or_b32_e32 v35, 8, v28
	v_or_b32_e32 v37, 16, v28
	v_or_b32_e32 v39, 24, v28
	v_or_b32_e32 v44, 32, v28
	v_or_b32_e32 v66, 40, v28
	v_or_b32_e32 v68, 48, v28
	v_or_b32_e32 v70, 56, v28
	v_ashrrev_i32_e32 v33, 31, v32
	v_ashrrev_i32_e32 v41, 31, v40
	v_ashrrev_i32_e32 v43, 31, v42
	v_ashrrev_i32_e32 v51, 31, v50
	v_ashrrev_i32_e32 v53, 31, v52
	v_ashrrev_i32_e32 v55, 31, v54
	v_ashrrev_i32_e32 v57, 31, v56
	global_load_dwordx4 v[24:27], v[24:25], off nt
	v_mad_i64_i32 v[58:59], s[12:13], v35, s30, v[30:31]
	v_mad_i64_i32 v[60:61], s[12:13], v37, s30, v[30:31]
	v_mad_i64_i32 v[62:63], s[12:13], v39, s30, v[30:31]
	v_mad_i64_i32 v[64:65], s[12:13], v44, s30, v[30:31]
	v_mad_i64_i32 v[66:67], s[12:13], v66, s30, v[30:31]
	v_mad_i64_i32 v[68:69], s[12:13], v68, s30, v[30:31]
	v_mad_i64_i32 v[70:71], s[12:13], v70, s30, v[30:31]
	v_lshl_add_u64 v[28:29], v[28:29], 2, s[0:1]
	v_lshl_add_u64 v[32:33], v[32:33], 2, s[0:1]
	v_lshl_add_u64 v[40:41], v[40:41], 2, s[0:1]
	v_lshl_add_u64 v[72:73], v[42:43], 2, s[0:1]
	v_lshl_add_u64 v[74:75], v[50:51], 2, s[0:1]
	v_lshl_add_u64 v[76:77], v[52:53], 2, s[0:1]
	v_lshl_add_u64 v[78:79], v[54:55], 2, s[0:1]
	v_lshl_add_u64 v[80:81], v[56:57], 2, s[0:1]
	global_load_dword v44, v[28:29], off
	s_nop 0
	global_load_dwordx4 v[28:31], v[58:59], off nt
	s_nop 0
	global_load_dword v32, v[32:33], off
	s_nop 0
	global_load_dword v82, v[40:41], off
	s_nop 0
	global_load_dwordx4 v[40:43], v[60:61], off nt
	global_load_dwordx4 v[50:53], v[62:63], off nt
	s_nop 0
	global_load_dword v72, v[72:73], off
	s_nop 0
	global_load_dword v74, v[74:75], off
	s_nop 0
	global_load_dwordx4 v[54:57], v[64:65], off nt
	global_load_dwordx4 v[58:61], v[66:67], off nt
	s_nop 0
	global_load_dword v76, v[76:77], off
	s_nop 0
	global_load_dword v78, v[78:79], off
	s_nop 0
	global_load_dwordx4 v[62:65], v[68:69], off nt
	s_nop 0
	global_load_dwordx4 v[66:69], v[70:71], off nt
	s_nop 0
	global_load_dword v70, v[80:81], off
	s_ashr_i32 s9, s8, 31
	s_lshl_b32 s12, s35, 1
	s_or_b32 s31, s31, s34
	v_lshl_add_u64 v[80:81], s[8:9], 1, v[4:5]
	s_and_b32 s8, s12, 0xffffff00
	s_or_b32 s8, s31, s8
	v_or_b32_e32 v84, s8, v34
	v_or_b32_e32 v86, s8, v45
	v_or_b32_e32 v88, s8, v46
	v_or_b32_e32 v90, s8, v48
	v_ashrrev_i32_e32 v85, 31, v84
	v_ashrrev_i32_e32 v87, 31, v86
	v_ashrrev_i32_e32 v89, 31, v88
	v_ashrrev_i32_e32 v91, 31, v90
	v_lshlrev_b64 v[84:85], 11, v[84:85]
	v_lshlrev_b64 v[86:87], 11, v[86:87]
	v_lshlrev_b64 v[88:89], 11, v[88:89]
	v_lshlrev_b64 v[90:91], 11, v[90:91]
	v_lshl_add_u64 v[84:85], v[80:81], 0, v[84:85]
	v_lshl_add_u64 v[86:87], v[80:81], 0, v[86:87]
	v_lshl_add_u64 v[88:89], v[80:81], 0, v[88:89]
	v_lshl_add_u64 v[80:81], v[80:81], 0, v[90:91]
	s_add_i32 s27, s27, s24
	s_add_i32 s28, s28, s29
	s_cmpk_lt_i32 s27, 0xb00
	s_waitcnt vmcnt(14)
	v_pk_mul_f32 v[24:25], v[24:25], v[44:45] op_sel_hi:[1,0]
	v_pk_mul_f32 v[26:27], v[26:27], v[44:45] op_sel_hi:[1,0]
	s_waitcnt vmcnt(12)
	v_pk_mul_f32 v[28:29], v[28:29], v[32:33] op_sel_hi:[1,0]
	v_pk_mul_f32 v[30:31], v[30:31], v[32:33] op_sel_hi:[1,0]
	s_waitcnt vmcnt(10)
	v_pk_mul_f32 v[32:33], v[40:41], v[82:83] op_sel_hi:[1,0]
	v_pk_mul_f32 v[40:41], v[42:43], v[82:83] op_sel_hi:[1,0]
	s_waitcnt vmcnt(8)
	v_pk_mul_f32 v[42:43], v[50:51], v[72:73] op_sel_hi:[1,0]
	v_pk_mul_f32 v[50:51], v[52:53], v[72:73] op_sel_hi:[1,0]
	s_waitcnt vmcnt(6)
	v_pk_mul_f32 v[52:53], v[54:55], v[74:75] op_sel_hi:[1,0]
	v_pk_mul_f32 v[54:55], v[56:57], v[74:75] op_sel_hi:[1,0]
	s_waitcnt vmcnt(4)
	v_pk_mul_f32 v[56:57], v[58:59], v[76:77] op_sel_hi:[1,0]
	v_pk_mul_f32 v[58:59], v[60:61], v[76:77] op_sel_hi:[1,0]
	s_waitcnt vmcnt(2)
	v_pk_mul_f32 v[60:61], v[62:63], v[78:79] op_sel_hi:[1,0]
	v_pk_mul_f32 v[62:63], v[64:65], v[78:79] op_sel_hi:[1,0]
	s_waitcnt vmcnt(0)
	v_pk_mul_f32 v[64:65], v[66:67], v[70:71] op_sel_hi:[1,0]
	v_pk_mul_f32 v[66:67], v[68:69], v[70:71] op_sel_hi:[1,0]
	ds_write2_b32 v49, v24, v25 offset1:1
	ds_write2_b32 v49, v26, v27 offset0:2 offset1:3
	ds_write2_b32 v6, v28, v29 offset1:1
	ds_write2_b32 v7, v30, v31 offset1:1
	ds_write2_b32 v12, v32, v33 offset1:1
	ds_write2_b32 v13, v40, v41 offset1:1
	ds_write2_b32 v14, v42, v43 offset1:1
	ds_write2_b32 v15, v50, v51 offset1:1
	ds_write2_b32 v16, v52, v53 offset1:1
	ds_write2_b32 v17, v54, v55 offset1:1
	ds_write2_b32 v18, v56, v57 offset1:1
	ds_write2_b32 v19, v58, v59 offset1:1
	ds_write2_b32 v20, v60, v61 offset1:1
	ds_write2_b32 v21, v62, v63 offset1:1
	ds_write2_b32 v22, v64, v65 offset1:1
	ds_write2_b32 v23, v66, v67 offset1:1
	s_waitcnt lgkmcnt(0)
	ds_read2_b32 v[28:29], v47 offset0:33 offset1:41
	ds_read2_b32 v[30:31], v47 offset1:8
	ds_read2_b32 v[32:33], v47 offset0:66 offset1:74
	ds_read2_b32 v[40:41], v47 offset0:99 offset1:107
	ds_read2_b32 v[42:43], v47 offset0:132 offset1:140
	ds_read2_b32 v[50:51], v47 offset0:165 offset1:173
	ds_read2_b32 v[52:53], v47 offset0:198 offset1:206
	ds_read2_b32 v[54:55], v47 offset0:231 offset1:239
	ds_read2_b32 v[56:57], v47 offset0:49 offset1:57
	ds_read2_b32 v[58:59], v47 offset0:16 offset1:24
	ds_read2_b32 v[60:61], v47 offset0:82 offset1:90
	ds_read2_b32 v[62:63], v47 offset0:115 offset1:123
	ds_read2_b32 v[64:65], v47 offset0:148 offset1:156
	ds_read2_b32 v[66:67], v47 offset0:181 offset1:189
	ds_read2_b32 v[68:69], v47 offset0:214 offset1:222
	ds_read2_b32 v[70:71], v47 offset0:247 offset1:255
	s_waitcnt lgkmcnt(0)
	v_cvt_pk_f16_f32 v24, v30, v28
	v_cvt_pk_f16_f32 v25, v32, v40
	v_cvt_pk_f16_f32 v26, v42, v50
	v_cvt_pk_f16_f32 v27, v52, v54
	v_cvt_pk_f16_f32 v28, v31, v29
	v_cvt_pk_f16_f32 v29, v33, v41
	v_cvt_pk_f16_f32 v30, v43, v51
	v_cvt_pk_f16_f32 v31, v53, v55
	v_cvt_pk_f16_f32 v40, v58, v56
	v_cvt_pk_f16_f32 v41, v60, v62
	v_cvt_pk_f16_f32 v42, v64, v66
	v_cvt_pk_f16_f32 v43, v68, v70
	v_cvt_pk_f16_f32 v50, v59, v57
	v_cvt_pk_f16_f32 v51, v61, v63
	v_cvt_pk_f16_f32 v52, v65, v67
	v_cvt_pk_f16_f32 v53, v69, v71
	global_store_dwordx4 v[84:85], v[24:27], off sc1
	global_store_dwordx4 v[86:87], v[28:31], off sc1
	global_store_dwordx4 v[88:89], v[40:43], off sc1
	global_store_dwordx4 v[80:81], v[50:53], off sc1
	s_waitcnt lgkmcnt(0)
	s_cbranch_scc1 .LBB0_31

; #define LAS __attribute__((address_space(3)))
; #define GAS __attribute__((address_space(1)))
; #define LDS_WAIT() asm volatile("s_waitcnt lgkmcnt(0)" ::: "memory")
; __device__ __forceinline__ unsigned pkh(float lo, float hi) { f32x2 v = {lo, hi}; h16x2 h = __builtin_convertvector(v, h16x2); return __builtin_bit_cast(unsigned, h); }
; __device__ __forceinline__ unsigned pk8(float a, float b, float c, float d) { int w = __builtin_amdgcn_cvt_pk_fp8_f32(a, b, 0, false); w = __builtin_amdgcn_cvt_pk_fp8_f32(c, d, w, true); return (unsigned)w; }
; template <bool FP8>
; __device__ __forceinline__ void p0_transpose_item(const float* W, int K, int N, f16_t* WT, const float* gain, LAS float* scr, int k0, int n0, int dst0, int lane) {
;     ...
;         for (int i = 0; i < 8; ++i) v[i] = __builtin_nontemporal_load((const f32x4*)(W + (size_t)(k0 + (lane >> 3) + 8 * i) * N + n0 + 4 * (lane & 7)));
; #pragma unroll
;         for (int i = 0; i < 8; ++i) { const int kk = (lane >> 3) + 8 * i; const float gsc = (gain ? gain[k0 + kk] : 1.0f) * (FP8 ? F8_SW : 1.0f);
; #pragma unroll
;             for (int e = 0; e < 4; ++e) scr[kk * 33 + 4 * (lane & 7) + e] = v[i][e] * gsc; } }
;     LDS_WAIT(); asm volatile("" ::: "memory");
;     const int c = lane & 7;
; #pragma unroll
;     for (int j = 0; j < 4; ++j) { const int n = (lane >> 3) + 8 * j; const LAS float* s = scr + (8 * c) * 33 + n;
;         if constexpr (FP8) { u32x2 o; o.x = pk8(s[0 * 33], s[1 * 33], s[2 * 33], s[3 * 33]); o.y = pk8(s[4 * 33], s[5 * 33], s[6 * 33], s[7 * 33]);
;             *(GAS u32x2*)((unsigned char*)WT + (size_t)(dst0 + n) * K + k0 + 8 * c) = o; }
;         else { u32x4 o; o.x = pkh(s[0 * 33], s[1 * 33]); o.y = pkh(s[2 * 33], s[3 * 33]); o.z = pkh(s[4 * 33], s[5 * 33]); o.w = pkh(s[6 * 33], s[7 * 33]);
;             *(GAS u32x4*)(WT + (size_t)(dst0 + n) * K + k0 + 8 * c) = o; } }
;     LDS_WAIT(); asm volatile("" ::: "memory");
.LBB0_34:
	s_ashr_i32 s0, s8, 31
	s_lshr_b32 s0, s0, 27
	s_add_i32 s0, s8, s0
	s_ashr_i32 s1, s0, 5
	s_lshl_b32 s0, s1, 6
	s_lshl_b32 s27, s1, 10
	v_or_b32_e32 v22, s0, v34
	s_sub_i32 s28, s12, s27
	v_or_b32_e32 v24, 8, v22
	v_or_b32_e32 v26, 16, v22
	v_or_b32_e32 v28, 24, v22
	v_or_b32_e32 v30, 32, v22
	v_or_b32_e32 v32, 40, v22
	v_or_b32_e32 v40, 48, v22
	v_or_b32_e32 v42, 56, v22
	s_ashr_i32 s29, s28, 31
	v_ashrrev_i32_e32 v23, 31, v22
	v_ashrrev_i32_e32 v25, 31, v24
	v_ashrrev_i32_e32 v27, 31, v26
	v_ashrrev_i32_e32 v29, 31, v28
	v_ashrrev_i32_e32 v31, 31, v30
	v_ashrrev_i32_e32 v33, 31, v32
	v_ashrrev_i32_e32 v41, 31, v40
	v_ashrrev_i32_e32 v43, 31, v42
	v_lshl_add_u64 v[50:51], s[28:29], 2, v[2:3]
	v_lshlrev_b64 v[22:23], 12, v[22:23]
	v_lshlrev_b64 v[52:53], 12, v[24:25]
	v_lshlrev_b64 v[26:27], 12, v[26:27]
	v_lshlrev_b64 v[28:29], 12, v[28:29]
	v_lshlrev_b64 v[30:31], 12, v[30:31]
	v_lshlrev_b64 v[32:33], 12, v[32:33]
	v_lshlrev_b64 v[40:41], 12, v[40:41]
	v_lshlrev_b64 v[42:43], 12, v[42:43]
	v_lshl_add_u64 v[22:23], v[50:51], 0, v[22:23]
	v_lshl_add_u64 v[52:53], v[50:51], 0, v[52:53]
	v_lshl_add_u64 v[54:55], v[50:51], 0, v[26:27]
	v_lshl_add_u64 v[56:57], v[50:51], 0, v[28:29]
	v_lshl_add_u64 v[58:59], v[50:51], 0, v[30:31]
	v_lshl_add_u64 v[60:61], v[50:51], 0, v[32:33]
	v_lshl_add_u64 v[62:63], v[50:51], 0, v[40:41]
	v_lshl_add_u64 v[64:65], v[50:51], 0, v[42:43]
	global_load_dwordx4 v[22:25], v[22:23], off nt
	s_nop 0
	global_load_dwordx4 v[26:29], v[52:53], off nt
	global_load_dwordx4 v[30:33], v[54:55], off nt
	global_load_dwordx4 v[40:43], v[56:57], off nt
	s_nop 0
	global_load_dwordx4 v[50:53], v[58:59], off nt
	global_load_dwordx4 v[54:57], v[60:61], off nt
	s_nop 0
	global_load_dwordx4 v[58:61], v[62:63], off nt
	s_nop 0
	global_load_dwordx4 v[62:65], v[64:65], off nt
	s_mul_i32 s27, s1, 0xffa80000
	v_add_u32_e32 v66, s27, v6
	s_ashr_i32 s1, s0, 31
	v_add_u32_e32 v70, 0xb000, v66
	v_add_u32_e32 v72, 0x16000, v66
	v_add_u32_e32 v74, 0x21000, v66
	v_lshl_add_u64 v[68:69], s[0:1], 1, v[4:5]
	v_ashrrev_i32_e32 v67, 31, v66
	v_ashrrev_i32_e32 v71, 31, v70
	v_ashrrev_i32_e32 v73, 31, v72
	v_ashrrev_i32_e32 v75, 31, v74
	v_lshl_add_u64 v[66:67], v[68:69], 0, v[66:67]
	v_lshl_add_u64 v[70:71], v[68:69], 0, v[70:71]
	v_lshl_add_u64 v[72:73], v[68:69], 0, v[72:73]
	v_lshl_add_u64 v[68:69], v[68:69], 0, v[74:75]
	s_add_i32 s8, s8, s24
	s_add_i32 s12, s12, s13
	s_cmpk_lt_i32 s8, 0x580
	v_add_u32_e32 v6, s9, v6
	s_waitcnt vmcnt(7)
	ds_write2_b32 v49, v22, v23 offset1:1
	ds_write2_b32 v49, v24, v25 offset0:2 offset1:3
	s_waitcnt vmcnt(6)
	ds_write2_b32 v7, v26, v27 offset1:1
	ds_write2_b32 v8, v28, v29 offset1:1
	s_waitcnt vmcnt(5)
	ds_write2_b32 v9, v30, v31 offset1:1
	ds_write2_b32 v10, v32, v33 offset1:1
	s_waitcnt vmcnt(4)
	ds_write2_b32 v11, v40, v41 offset1:1
	ds_write2_b32 v12, v42, v43 offset1:1
	s_waitcnt vmcnt(3)
	ds_write2_b32 v13, v50, v51 offset1:1
	ds_write2_b32 v14, v52, v53 offset1:1
	s_waitcnt vmcnt(2)
	ds_write2_b32 v15, v54, v55 offset1:1
	ds_write2_b32 v16, v56, v57 offset1:1
	s_waitcnt vmcnt(1)
	ds_write2_b32 v17, v58, v59 offset1:1
	ds_write2_b32 v18, v60, v61 offset1:1
	s_waitcnt vmcnt(0)
	ds_write2_b32 v19, v62, v63 offset1:1
	ds_write2_b32 v20, v64, v65 offset1:1
	s_waitcnt lgkmcnt(0)
	ds_read2_b32 v[26:27], v47 offset0:33 offset1:41
	ds_read2_b32 v[28:29], v47 offset1:8
	ds_read2_b32 v[30:31], v47 offset0:66 offset1:74
	ds_read2_b32 v[32:33], v47 offset0:99 offset1:107
	ds_read2_b32 v[40:41], v47 offset0:132 offset1:140
	ds_read2_b32 v[42:43], v47 offset0:165 offset1:173
	ds_read2_b32 v[50:51], v47 offset0:198 offset1:206
	ds_read2_b32 v[52:53], v47 offset0:231 offset1:239
	ds_read2_b32 v[54:55], v47 offset0:49 offset1:57
	ds_read2_b32 v[56:57], v47 offset0:16 offset1:24
	ds_read2_b32 v[58:59], v47 offset0:82 offset1:90
	ds_read2_b32 v[60:61], v47 offset0:115 offset1:123
	ds_read2_b32 v[62:63], v47 offset0:148 offset1:156
	ds_read2_b32 v[64:65], v47 offset0:181 offset1:189
	ds_read2_b32 v[74:75], v47 offset0:214 offset1:222
	ds_read2_b32 v[76:77], v47 offset0:247 offset1:255
	s_waitcnt lgkmcnt(0)
	v_cvt_pk_f16_f32 v22, v28, v26
	v_cvt_pk_f16_f32 v23, v30, v32
	v_cvt_pk_f16_f32 v24, v40, v42
	v_cvt_pk_f16_f32 v25, v50, v52
	v_cvt_pk_f16_f32 v26, v29, v27
	v_cvt_pk_f16_f32 v27, v31, v33
	v_cvt_pk_f16_f32 v28, v41, v43
	v_cvt_pk_f16_f32 v29, v51, v53
	v_cvt_pk_f16_f32 v30, v56, v54
	v_cvt_pk_f16_f32 v31, v58, v60
	v_cvt_pk_f16_f32 v32, v62, v64
	v_cvt_pk_f16_f32 v33, v74, v76
	v_cvt_pk_f16_f32 v40, v57, v55
	v_cvt_pk_f16_f32 v41, v59, v61
	v_cvt_pk_f16_f32 v42, v63, v65
	v_cvt_pk_f16_f32 v43, v75, v77
	global_store_dwordx4 v[66:67], v[22:25], off sc1
	global_store_dwordx4 v[70:71], v[26:29], off sc1
	global_store_dwordx4 v[72:73], v[30:33], off sc1
	global_store_dwordx4 v[68:69], v[40:43], off sc1
	s_waitcnt lgkmcnt(0)
	s_cbranch_scc1 .LBB0_34

; #define LAS __attribute__((address_space(3)))
; #define GAS __attribute__((address_space(1)))
; #define LDS_WAIT() asm volatile("s_waitcnt lgkmcnt(0)" ::: "memory")
; __device__ __forceinline__ unsigned pkh(float lo, float hi) { f32x2 v = {lo, hi}; h16x2 h = __builtin_convertvector(v, h16x2); return __builtin_bit_cast(unsigned, h); }
; __device__ __forceinline__ unsigned pk8(float a, float b, float c, float d) { int w = __builtin_amdgcn_cvt_pk_fp8_f32(a, b, 0, false); w = __builtin_amdgcn_cvt_pk_fp8_f32(c, d, w, true); return (unsigned)w; }
; template <bool FP8>
; __device__ __forceinline__ void p0_transpose_item(const float* W, int K, int N, f16_t* WT, const float* gain, LAS float* scr, int k0, int n0, int dst0, int lane) {
;     ...
;         for (int i = 0; i < 8; ++i) { const int kk = (lane >> 3) + 8 * i; const float gsc = (gain ? gain[k0 + kk] : 1.0f) * (FP8 ? F8_SW : 1.0f);
; #pragma unroll
;             for (int e = 0; e < 4; ++e) scr[kk * 33 + 4 * (lane & 7) + e] = v[i][e] * gsc; } }
;     LDS_WAIT(); asm volatile("" ::: "memory");
;     const int c = lane & 7;
; #pragma unroll
;     for (int j = 0; j < 4; ++j) { const int n = (lane >> 3) + 8 * j; const LAS float* s = scr + (8 * c) * 33 + n;
;         if constexpr (FP8) { u32x2 o; o.x = pk8(s[0 * 33], s[1 * 33], s[2 * 33], s[3 * 33]); o.y = pk8(s[4 * 33], s[5 * 33], s[6 * 33], s[7 * 33]);
;             *(GAS u32x2*)((unsigned char*)WT + (size_t)(dst0 + n) * K + k0 + 8 * c) = o; }
;         else { u32x4 o; o.x = pkh(s[0 * 33], s[1 * 33]); o.y = pkh(s[2 * 33], s[3 * 33]); o.z = pkh(s[4 * 33], s[5 * 33]); o.w = pkh(s[6 * 33], s[7 * 33]);
;             *(GAS u32x4*)(WT + (size_t)(dst0 + n) * K + k0 + 8 * c) = o; } }
;     LDS_WAIT(); asm volatile("" ::: "memory");
.LBB0_37:
	v_add_u32_e32 v11, 0x18c0, v49
	ds_write2_b32 v11, v6, v7 offset1:1
	v_add_u32_e32 v6, 0x18c8, v49
	ds_write2_b32 v6, v8, v9 offset1:1
	s_waitcnt vmcnt(0)
	v_pk_mul_f32 v[2:3], v[2:3], v[10:11] op_sel_hi:[1,0]
	v_add_u32_e32 v6, 0x1ce0, v49
	ds_write2_b32 v6, v2, v3 offset1:1
	v_pk_mul_f32 v[2:3], v[4:5], v[10:11] op_sel_hi:[1,0]
	v_add_u32_e32 v4, 0x1ce8, v49
	ds_write2_b32 v4, v2, v3 offset1:1
	s_waitcnt lgkmcnt(0)
	s_and_b32 s27, s26, 0xffffff00
	s_and_b32 s28, s34, 0x80
	s_lshr_b32 s26, s26, 1
	s_or_b32 s27, s28, s27
	s_and_b32 s26, s26, 0x60
	ds_read2_b32 v[6:7], v47 offset0:33 offset1:41
	ds_read2_b32 v[8:9], v47 offset1:8
	ds_read2_b32 v[10:11], v47 offset0:66 offset1:74
	ds_read2_b32 v[12:13], v47 offset0:99 offset1:107
	ds_read2_b32 v[14:15], v47 offset0:132 offset1:140
	ds_read2_b32 v[16:17], v47 offset0:165 offset1:173
	ds_read2_b32 v[18:19], v47 offset0:198 offset1:206
	ds_read2_b32 v[20:21], v47 offset0:231 offset1:239
	s_or_b32 s26, s27, s26
	v_or_b32_e32 v24, s26, v34
	v_ashrrev_i32_e32 v25, 31, v24
	v_lshl_add_u64 v[22:23], s[12:13], 1, v[38:39]
	v_lshlrev_b64 v[24:25], 11, v[24:25]
	s_waitcnt lgkmcnt(6)
	v_cvt_pk_f16_f32 v2, v8, v6
	s_waitcnt lgkmcnt(4)
	v_cvt_pk_f16_f32 v3, v10, v12
	s_waitcnt lgkmcnt(2)
	v_cvt_pk_f16_f32 v4, v14, v16
	s_waitcnt lgkmcnt(0)
	v_cvt_pk_f16_f32 v5, v18, v20
	v_lshl_add_u64 v[24:25], v[22:23], 0, v[24:25]
	v_or_b32_e32 v6, s26, v45
	global_store_dwordx4 v[24:25], v[2:5], off sc1
	s_add_i32 s25, s25, s24
	s_add_i32 s30, s30, s31
	v_cvt_pk_f16_f32 v2, v9, v7
	v_ashrrev_i32_e32 v7, 31, v6
	v_cvt_pk_f16_f32 v3, v11, v13
	v_cvt_pk_f16_f32 v4, v15, v17
	v_cvt_pk_f16_f32 v5, v19, v21
	v_lshlrev_b64 v[6:7], 11, v[6:7]
	ds_read2_b32 v[8:9], v47 offset0:49 offset1:57
	ds_read2_b32 v[10:11], v47 offset0:16 offset1:24
	ds_read2_b32 v[12:13], v47 offset0:82 offset1:90
	ds_read2_b32 v[14:15], v47 offset0:115 offset1:123
	ds_read2_b32 v[16:17], v47 offset0:148 offset1:156
	ds_read2_b32 v[18:19], v47 offset0:181 offset1:189
	ds_read2_b32 v[20:21], v47 offset0:214 offset1:222
	ds_read2_b32 v[24:25], v47 offset0:247 offset1:255
	v_lshl_add_u64 v[6:7], v[22:23], 0, v[6:7]
	global_store_dwordx4 v[6:7], v[2:5], off sc1
	v_or_b32_e32 v6, s26, v46
	v_ashrrev_i32_e32 v7, 31, v6
	v_lshlrev_b64 v[6:7], 11, v[6:7]
	s_waitcnt lgkmcnt(6)
	v_cvt_pk_f16_f32 v2, v10, v8
	s_waitcnt lgkmcnt(4)
	v_cvt_pk_f16_f32 v3, v12, v14
	s_waitcnt lgkmcnt(2)
	v_cvt_pk_f16_f32 v4, v16, v18
	s_waitcnt lgkmcnt(0)
	v_cvt_pk_f16_f32 v5, v20, v24
	v_lshl_add_u64 v[6:7], v[22:23], 0, v[6:7]
	global_store_dwordx4 v[6:7], v[2:5], off sc1
	v_or_b32_e32 v6, s26, v48
	v_ashrrev_i32_e32 v7, 31, v6
	v_lshlrev_b64 v[6:7], 11, v[6:7]
	v_cvt_pk_f16_f32 v2, v11, v9
	v_cvt_pk_f16_f32 v3, v13, v15
	v_cvt_pk_f16_f32 v4, v17, v19
	v_cvt_pk_f16_f32 v5, v21, v25
	v_lshl_add_u64 v[6:7], v[22:23], 0, v[6:7]
	global_store_dwordx4 v[6:7], v[2:5], off sc1
	s_waitcnt lgkmcnt(0)
	s_add_i32 s34, s34, s35
	s_cmpk_lt_i32 s25, 0x100
	s_cbranch_scc0 .LBB0_49

; __device__ __forceinline__ unsigned pkh(float lo, float hi) { f32x2 v = {lo, hi}; h16x2 h = __builtin_convertvector(v, h16x2); return __builtin_bit_cast(unsigned, h); }
; __device__ __forceinline__ void p0_prologue(const Frame& F, const Args& a) {
;     ...
;     for (int ci = F.vcu * 512 + F.tid; ci < NGRP * CHUNK * 16; ci += F.G * 512) { const int g = ci / (CHUNK * 16), t = (ci >> 4) & (CHUNK - 1), c = ci & 15;
;         const float* src = a.in[7] + (size_t)g * CHUNK * CHUNK + t * CHUNK + 8 * c; u32x4 o = {0u, 0u, 0u, 0u};
;         if (8 * c <= t) { const f32x4 x0 = *(const f32x4*)src, x1 = *(const f32x4*)(src + 4); float v[8] = {x0[0], x0[1], x0[2], x0[3], x1[0], x1[1], x1[2], x1[3]};
; #pragma unroll
;             for (int j = 0; j < 8; ++j) v[j] = (8 * c + j <= t) ? v[j] : 0.f;
;             o.x = pkh(v[0], v[1]); o.y = pkh(v[2], v[3]); o.z = pkh(v[4], v[5]); o.w = pkh(v[6], v[7]); }
;         *(u32x4*)(ws + WS_W16S + (size_t)g * 32768 + t * 256 + ((c ^ (t & 15)) << 4)) = o; }
.LBB0_51:
	s_or_b64 exec, exec, s[26:27]
	v_lshlrev_b64 v[8:9], 15, v[8:9]
	v_lshrrev_b32_e32 v12, 4, v10
	v_lshl_add_u64 v[8:9], s[8:9], 0, v[8:9]
	v_lshlrev_b32_e32 v6, 8, v11
	v_lshl_add_u64 v[8:9], v[8:9], 0, v[6:7]
	v_xor_b32_e32 v6, v12, v10
	v_lshlrev_b32_e32 v6, 4, v6
	v_add_u32_e32 v10, s25, v10
	v_and_b32_e32 v6, 0xf0, v6
	v_cmp_lt_i32_e32 vcc, s29, v10
	v_lshl_add_u64 v[8:9], v[8:9], 0, v[6:7]
	s_or_b64 s[12:13], vcc, s[12:13]
	v_add_u32_e32 v1, s28, v1
	global_store_dwordx4 v[8:9], v[2:5], off sc1
	s_andn2_b64 exec, exec, s[12:13]
	s_cbranch_execz .LBB0_54

; __device__ __forceinline__ unsigned pkh(float lo, float hi) { f32x2 v = {lo, hi}; h16x2 h = __builtin_convertvector(v, h16x2); return __builtin_bit_cast(unsigned, h); }
;     __device__ __forceinline__ void operator()(f32x4 (&acc)[2][2][4][2], const Unit& u, const Order& S, int wr, int wc, int fr_, int fq_, LAS unsigned char*, int) const {
;     ...
;         f16_t* dst = (isk ? KM : VM) + (size_t)(u.pm * 4 + wc) * NMEM * HD;
;         f32x4 gv[2][2];
; #pragma unroll
;         for (int bj = 0; bj < 2; ++bj)
; #pragma unroll
;             for (int n = 0; n < 2; ++n) gv[bj][n] = isk ? *(const f32x4*)(gkm + 32 * bj + 8 * fq + 4 * n) : (f32x4){1.f, 1.f, 1.f, 1.f};
; #pragma unroll
;         for (int ai = 0; ai < 2; ++ai)
; #pragma unroll
;             for (int m = 0; m < 4; ++m) {
;                 const int key = ai * HALF + wr * 64 + m * 16 + fr;
;                 const float sc = __builtin_amdgcn_rsqf(ss_in[u.pm * BM + key] * (1.0f / DM) + EPS);
;                 f32x4 v[2][2]; float sq = 0.f;
; #pragma unroll
;                 for (int bj = 0; bj < 2; ++bj)
; #pragma unroll
;                     for (int n = 0; n < 2; ++n) { v[bj][n] = acc[ai][bj][m][n] * sc; const f32x4 t = v[bj][n]; sq += (t[0] * t[0] + t[1] * t[1]) + (t[2] * t[2] + t[3] * t[3]); }
;                 float rn = 1.f;
;                 if (isk) { sq += __shfl_xor(sq, 16); sq += __shfl_xor(sq, 32); rn = __builtin_amdgcn_rsqf(sq * (1.0f / HD) + EPS); }
; #pragma unroll
;                 for (int bj = 0; bj < 2; ++bj) {
;                     const f32x4 a = v[bj][0] * rn * gv[bj][0], b = v[bj][1] * rn * gv[bj][1];
;                     u32x4 w; w.x = pkh(a[0], a[1]); w.y = pkh(a[2], a[3]); w.z = pkh(b[0], b[1]); w.w = pkh(b[2], b[3]);
;                     *(u32x4*)(dst + (size_t)key * HD + 32 * bj + 8 * fq) = w;
.LBB0_150:
	s_and_b64 s[30:31], s[30:31], exec
	s_mov_b32 s30, 0x3200000
	s_cselect_b32 s30, s30, 0x3300000
	s_add_u32 s34, s76, s30
	s_addc_u32 s35, s77, 0
	s_lshl_b32 s30, s67, 2
	s_or_b32 s30, s30, s51
	s_ashr_i32 s31, s30, 31
	s_lshl_b64 s[30:31], s[30:31], 15
	s_add_u32 s30, s34, s30
	s_addc_u32 s31, s35, s31
	v_ashrrev_i32_e32 v159, 31, v158
	v_pk_mul_f32 v[144:145], v[144:145], v[166:167] op_sel_hi:[1,0]
	v_pk_mul_f32 v[164:165], v[164:165], v[166:167] op_sel_hi:[1,0]
	v_pk_mul_f32 v[140:141], v[140:141], v[166:167] op_sel_hi:[1,0]
	v_pk_mul_f32 v[142:143], v[142:143], v[166:167] op_sel_hi:[1,0]
	v_lshl_add_u64 v[130:131], v[162:163], 1, s[30:31]
	v_lshlrev_b64 v[162:163], 7, v[158:159]
	v_pk_mul_f32 v[144:145], v[88:89], v[144:145]
	v_pk_mul_f32 v[164:165], v[86:87], v[164:165]
	v_pk_mul_f32 v[176:177], v[84:85], v[140:141]
	v_pk_mul_f32 v[142:143], v[82:83], v[142:143]
	v_lshl_add_u64 v[162:163], v[130:131], 0, v[162:163]
	v_cvt_pk_f16_f32 v140, v164, v165
	v_cvt_pk_f16_f32 v141, v144, v145
	v_cvt_pk_f16_f32 v142, v142, v143
	v_cvt_pk_f16_f32 v143, v176, v177
	v_pk_mul_f32 v[136:137], v[136:137], v[166:167] op_sel_hi:[1,0]
	v_pk_mul_f32 v[138:139], v[138:139], v[166:167] op_sel_hi:[1,0]
	v_pk_mul_f32 v[132:133], v[132:133], v[166:167] op_sel_hi:[1,0]
	v_pk_mul_f32 v[134:135], v[134:135], v[166:167] op_sel_hi:[1,0]
	global_store_dwordx4 v[162:163], v[140:143], off sc1
	v_pk_mul_f32 v[136:137], v[96:97], v[136:137]
	v_pk_mul_f32 v[138:139], v[94:95], v[138:139]
	v_pk_mul_f32 v[140:141], v[92:93], v[132:133]
	v_pk_mul_f32 v[134:135], v[90:91], v[134:135]
	v_cvt_pk_f16_f32 v132, v138, v139
	v_cvt_pk_f16_f32 v133, v136, v137
	v_cvt_pk_f16_f32 v134, v134, v135
	v_cvt_pk_f16_f32 v135, v140, v141
	global_store_dwordx4 v[162:163], v[132:135], off offset:64 sc1
	s_and_b64 vcc, exec, s[0:1]
	s_nop 0
	v_add_u32_e32 v132, 16, v158
	v_add_u32_e32 v134, s23, v132
	v_ashrrev_i32_e32 v135, 31, v134
	v_lshl_add_u64 v[134:135], v[134:135], 2, s[4:5]
	global_load_dword v133, v[134:135], off
	s_waitcnt vmcnt(0)
	v_fmamk_f32 v133, v133, 0x3a800000, v174
	v_rsq_f32_e32 v134, v133
	s_nop 0
	v_pk_mul_f32 v[128:129], v[128:129], v[134:135] op_sel_hi:[1,0]
	v_pk_mul_f32 v[126:127], v[126:127], v[134:135] op_sel_hi:[1,0]
	v_pk_mul_f32 v[124:125], v[124:125], v[134:135] op_sel_hi:[1,0]
	v_pk_mul_f32 v[122:123], v[122:123], v[134:135] op_sel_hi:[1,0]
	v_pk_mul_f32 v[120:121], v[120:121], v[134:135] op_sel_hi:[1,0]
	v_pk_mul_f32 v[118:119], v[118:119], v[134:135] op_sel_hi:[1,0]
	v_pk_mul_f32 v[116:117], v[116:117], v[134:135] op_sel_hi:[1,0]
	v_pk_mul_f32 v[114:115], v[114:115], v[134:135] op_sel_hi:[1,0]
	s_cbranch_vccnz .LBB0_152
	v_pk_mul_f32 v[134:135], v[128:129], v[128:129]
	v_pk_mul_f32 v[136:137], v[126:127], v[126:127]
	s_nop 0
	v_pk_mov_b32 v[138:139], v[136:137], v[134:135] op_sel:[1,0]
	v_mov_b32_e32 v137, v135
	v_pk_add_f32 v[134:135], v[138:139], v[136:137]
	v_pk_mul_f32 v[136:137], v[124:125], v[124:125]
	v_pk_add_f32 v[134:135], v[134:135], v[134:135] op_sel_hi:[0,1]
	v_pk_mul_f32 v[138:139], v[122:123], v[122:123]
	v_mul_f32_e32 v134, v118, v118
	v_pk_mov_b32 v[140:141], v[138:139], v[136:137] op_sel:[1,0]
	v_mov_b32_e32 v139, v137
	v_pk_add_f32 v[136:137], v[140:141], v[138:139]
	v_pk_fma_f32 v[138:139], v[118:119], v[118:119], v[134:135] op_sel_hi:[1,1,0]
	v_mul_f32_e32 v134, v120, v120
	v_pk_add_f32 v[136:137], v[136:137], v[136:137] op_sel_hi:[0,1]
	v_pk_fma_f32 v[140:141], v[120:121], v[120:121], v[134:135] op_sel_hi:[1,1,0]
	v_mul_f32_e32 v138, v114, v114
	v_mul_f32_e32 v140, v115, v115
	v_mul_f32_e32 v134, v116, v116
	v_mul_f32_e32 v136, v117, v117
	v_pk_add_f32 v[138:139], v[138:139], v[140:141]
	v_pk_add_f32 v[134:135], v[134:135], v[136:137]
	s_nop 0
	v_pk_add_f32 v[134:135], v[138:139], v[134:135]
	s_nop 0
	v_add_f32_e32 v133, v134, v135
	v_and_b32_e32 v135, 64, v175
	v_xor_b32_e32 v134, 16, v175
	v_add_u32_e32 v135, 64, v135
	v_cmp_lt_i32_e32 vcc, v134, v135
	s_nop 1
	v_cndmask_b32_e32 v134, v175, v134, vcc
	v_lshlrev_b32_e32 v134, 2, v134
	ds_bpermute_b32 v134, v134, v133
	s_waitcnt lgkmcnt(0)
	v_add_f32_e32 v133, v133, v134
	v_xor_b32_e32 v134, 32, v175
	v_cmp_lt_i32_e32 vcc, v134, v135
	s_nop 1
	v_cndmask_b32_e32 v134, v175, v134, vcc
	v_lshlrev_b32_e32 v134, 2, v134
	ds_bpermute_b32 v134, v134, v133
	s_waitcnt lgkmcnt(0)
	v_add_f32_e32 v133, v133, v134
	v_fmamk_f32 v133, v133, 0x3c800000, v174
	v_rsq_f32_e32 v160, v133
; __device__ __forceinline__ unsigned pkh(float lo, float hi) { f32x2 v = {lo, hi}; h16x2 h = __builtin_convertvector(v, h16x2); return __builtin_bit_cast(unsigned, h); }
;     __device__ __forceinline__ void operator()(f32x4 (&acc)[2][2][4][2], const Unit& u, const Order& S, int wr, int wc, int fr_, int fq_, LAS unsigned char*, int) const {
;     ...
; #pragma unroll
;         for (int ai = 0; ai < 2; ++ai)
; #pragma unroll
;             for (int m = 0; m < 4; ++m) {
;                 const int key = ai * HALF + wr * 64 + m * 16 + fr;
;                 const float sc = __builtin_amdgcn_rsqf(ss_in[u.pm * BM + key] * (1.0f / DM) + EPS);
;                 f32x4 v[2][2]; float sq = 0.f;
; #pragma unroll
;                 for (int bj = 0; bj < 2; ++bj)
; #pragma unroll
;                     for (int n = 0; n < 2; ++n) { v[bj][n] = acc[ai][bj][m][n] * sc; const f32x4 t = v[bj][n]; sq += (t[0] * t[0] + t[1] * t[1]) + (t[2] * t[2] + t[3] * t[3]); }
;                 float rn = 1.f;
;                 if (isk) { sq += __shfl_xor(sq, 16); sq += __shfl_xor(sq, 32); rn = __builtin_amdgcn_rsqf(sq * (1.0f / HD) + EPS); }
; #pragma unroll
;                 for (int bj = 0; bj < 2; ++bj) {
;                     const f32x4 a = v[bj][0] * rn * gv[bj][0], b = v[bj][1] * rn * gv[bj][1];
;                     u32x4 w; w.x = pkh(a[0], a[1]); w.y = pkh(a[2], a[3]); w.z = pkh(b[0], b[1]); w.w = pkh(b[2], b[3]);
;                     *(u32x4*)(dst + (size_t)key * HD + 32 * bj + 8 * fq) = w;
;                 }
;             }
.LBB0_152:
	v_ashrrev_i32_e32 v133, 31, v132
	v_pk_mul_f32 v[128:129], v[128:129], v[160:161] op_sel_hi:[1,0]
	v_pk_mul_f32 v[126:127], v[126:127], v[160:161] op_sel_hi:[1,0]
	v_pk_mul_f32 v[124:125], v[124:125], v[160:161] op_sel_hi:[1,0]
	v_pk_mul_f32 v[122:123], v[122:123], v[160:161] op_sel_hi:[1,0]
	v_lshlrev_b64 v[132:133], 7, v[132:133]
	v_pk_mul_f32 v[128:129], v[88:89], v[128:129]
	v_pk_mul_f32 v[126:127], v[86:87], v[126:127]
	v_pk_mul_f32 v[134:135], v[84:85], v[124:125]
	v_pk_mul_f32 v[124:125], v[82:83], v[122:123]
	v_lshl_add_u64 v[132:133], v[130:131], 0, v[132:133]
	v_cvt_pk_f16_f32 v122, v126, v127
	v_cvt_pk_f16_f32 v123, v128, v129
	v_cvt_pk_f16_f32 v124, v124, v125
	v_cvt_pk_f16_f32 v125, v134, v135
	v_pk_mul_f32 v[120:121], v[120:121], v[160:161] op_sel_hi:[1,0]
	v_pk_mul_f32 v[118:119], v[118:119], v[160:161] op_sel_hi:[1,0]
	v_pk_mul_f32 v[116:117], v[116:117], v[160:161] op_sel_hi:[1,0]
	v_pk_mul_f32 v[114:115], v[114:115], v[160:161] op_sel_hi:[1,0]
	global_store_dwordx4 v[132:133], v[122:125], off sc1
	v_pk_mul_f32 v[120:121], v[96:97], v[120:121]
	v_pk_mul_f32 v[118:119], v[94:95], v[118:119]
	v_pk_mul_f32 v[122:123], v[92:93], v[116:117]
	v_pk_mul_f32 v[116:117], v[90:91], v[114:115]
	v_cvt_pk_f16_f32 v114, v118, v119
	v_cvt_pk_f16_f32 v115, v120, v121
	v_cvt_pk_f16_f32 v116, v116, v117
	v_cvt_pk_f16_f32 v117, v122, v123
	global_store_dwordx4 v[132:133], v[114:117], off offset:64 sc1
	s_and_b64 vcc, exec, s[0:1]
	s_nop 0
	v_add_u32_e32 v116, 32, v158
	v_add_u32_e32 v114, s23, v116
	v_ashrrev_i32_e32 v115, 31, v114
	v_lshl_add_u64 v[114:115], v[114:115], 2, s[4:5]
	global_load_dword v114, v[114:115], off
	s_waitcnt vmcnt(0)
	v_fmamk_f32 v114, v114, 0x3a800000, v174
	v_rsq_f32_e32 v118, v114
	v_mov_b32_e32 v114, 1.0
	v_pk_mul_f32 v[112:113], v[112:113], v[118:119] op_sel_hi:[1,0]
	v_pk_mul_f32 v[110:111], v[110:111], v[118:119] op_sel_hi:[1,0]
	v_pk_mul_f32 v[108:109], v[108:109], v[118:119] op_sel_hi:[1,0]
	v_pk_mul_f32 v[106:107], v[106:107], v[118:119] op_sel_hi:[1,0]
	v_pk_mul_f32 v[104:105], v[104:105], v[118:119] op_sel_hi:[1,0]
	v_pk_mul_f32 v[102:103], v[102:103], v[118:119] op_sel_hi:[1,0]
	v_pk_mul_f32 v[100:101], v[100:101], v[118:119] op_sel_hi:[1,0]
	v_pk_mul_f32 v[98:99], v[98:99], v[118:119] op_sel_hi:[1,0]
	v_mov_b32_e32 v118, 1.0
	s_cbranch_vccnz .LBB0_154
	v_pk_mul_f32 v[118:119], v[112:113], v[112:113]
	v_pk_mul_f32 v[120:121], v[110:111], v[110:111]
	v_xor_b32_e32 v117, 16, v175
	v_pk_mov_b32 v[122:123], v[120:121], v[118:119] op_sel:[1,0]
	v_mov_b32_e32 v121, v119
	v_pk_add_f32 v[118:119], v[122:123], v[120:121]
	v_pk_mul_f32 v[120:121], v[108:109], v[108:109]
	v_pk_add_f32 v[118:119], v[118:119], v[118:119] op_sel_hi:[0,1]
	v_pk_mul_f32 v[122:123], v[106:107], v[106:107]
	v_mul_f32_e32 v118, v102, v102
	v_pk_mov_b32 v[124:125], v[122:123], v[120:121] op_sel:[1,0]
	v_mov_b32_e32 v123, v121
	v_pk_add_f32 v[120:121], v[124:125], v[122:123]
	v_pk_fma_f32 v[122:123], v[102:103], v[102:103], v[118:119] op_sel_hi:[1,1,0]
	v_mul_f32_e32 v118, v104, v104
	v_pk_add_f32 v[120:121], v[120:121], v[120:121] op_sel_hi:[0,1]
	v_pk_fma_f32 v[124:125], v[104:105], v[104:105], v[118:119] op_sel_hi:[1,1,0]
	v_mul_f32_e32 v122, v98, v98
	v_mul_f32_e32 v124, v99, v99
	v_mul_f32_e32 v118, v100, v100
	v_mul_f32_e32 v120, v101, v101
	v_pk_add_f32 v[122:123], v[122:123], v[124:125]
	v_pk_add_f32 v[118:119], v[118:119], v[120:121]
	s_nop 0
	v_pk_add_f32 v[118:119], v[122:123], v[118:119]
	s_nop 0
	v_add_f32_e32 v115, v118, v119
	v_and_b32_e32 v118, 64, v175
	v_add_u32_e32 v118, 64, v118
	v_cmp_lt_i32_e32 vcc, v117, v118
	s_nop 1
	v_cndmask_b32_e32 v117, v175, v117, vcc
	v_lshlrev_b32_e32 v117, 2, v117
	ds_bpermute_b32 v117, v117, v115
	s_waitcnt lgkmcnt(0)
	v_add_f32_e32 v115, v115, v117
	v_xor_b32_e32 v117, 32, v175
	v_cmp_lt_i32_e32 vcc, v117, v118
	s_nop 1
	v_cndmask_b32_e32 v117, v175, v117, vcc
	v_lshlrev_b32_e32 v117, 2, v117
	ds_bpermute_b32 v117, v117, v115
	s_waitcnt lgkmcnt(0)
	v_add_f32_e32 v115, v115, v117
	v_fmamk_f32 v115, v115, 0x3c800000, v174
	v_rsq_f32_e32 v118, v115
.LBB0_154:
	v_ashrrev_i32_e32 v117, 31, v116
	v_pk_mul_f32 v[112:113], v[112:113], v[118:119] op_sel_hi:[1,0]
	v_pk_mul_f32 v[110:111], v[110:111], v[118:119] op_sel_hi:[1,0]
	v_pk_mul_f32 v[108:109], v[108:109], v[118:119] op_sel_hi:[1,0]
	v_pk_mul_f32 v[106:107], v[106:107], v[118:119] op_sel_hi:[1,0]
	v_lshlrev_b64 v[116:117], 7, v[116:117]
	v_pk_mul_f32 v[112:113], v[88:89], v[112:113]
	v_pk_mul_f32 v[110:111], v[86:87], v[110:111]
	v_pk_mul_f32 v[120:121], v[84:85], v[108:109]
	v_pk_mul_f32 v[108:109], v[82:83], v[106:107]
	v_lshl_add_u64 v[116:117], v[130:131], 0, v[116:117]
	v_cvt_pk_f16_f32 v106, v110, v111
	v_cvt_pk_f16_f32 v107, v112, v113
	v_cvt_pk_f16_f32 v108, v108, v109
	v_cvt_pk_f16_f32 v109, v120, v121
	v_pk_mul_f32 v[104:105], v[104:105], v[118:119] op_sel_hi:[1,0]
	v_pk_mul_f32 v[102:103], v[102:103], v[118:119] op_sel_hi:[1,0]
	v_pk_mul_f32 v[100:101], v[100:101], v[118:119] op_sel_hi:[1,0]
	v_pk_mul_f32 v[98:99], v[98:99], v[118:119] op_sel_hi:[1,0]
	global_store_dwordx4 v[116:117], v[106:109], off sc1
	v_pk_mul_f32 v[104:105], v[96:97], v[104:105]
	v_pk_mul_f32 v[102:103], v[94:95], v[102:103]
	v_pk_mul_f32 v[106:107], v[92:93], v[100:101]
	v_pk_mul_f32 v[100:101], v[90:91], v[98:99]
	v_cvt_pk_f16_f32 v98, v102, v103
	v_cvt_pk_f16_f32 v99, v104, v105
	v_cvt_pk_f16_f32 v100, v100, v101
	v_cvt_pk_f16_f32 v101, v106, v107
	global_store_dwordx4 v[116:117], v[98:101], off offset:64 sc1
	s_and_b64 vcc, exec, s[0:1]
	s_nop 0
	v_add_u32_e32 v98, 48, v158
	v_add_u32_e32 v100, s23, v98
	v_ashrrev_i32_e32 v101, 31, v100
	v_lshl_add_u64 v[100:101], v[100:101], 2, s[4:5]
	global_load_dword v99, v[100:101], off
	s_waitcnt vmcnt(0)
	v_fmamk_f32 v99, v99, 0x3a800000, v174
	v_rsq_f32_e32 v100, v99
	s_nop 0
	v_pk_mul_f32 v[80:81], v[80:81], v[100:101] op_sel_hi:[1,0]
	v_pk_mul_f32 v[78:79], v[78:79], v[100:101] op_sel_hi:[1,0]
	v_pk_mul_f32 v[76:77], v[76:77], v[100:101] op_sel_hi:[1,0]
	v_pk_mul_f32 v[74:75], v[74:75], v[100:101] op_sel_hi:[1,0]
	v_pk_mul_f32 v[72:73], v[72:73], v[100:101] op_sel_hi:[1,0]
	v_pk_mul_f32 v[70:71], v[70:71], v[100:101] op_sel_hi:[1,0]
	v_pk_mul_f32 v[68:69], v[68:69], v[100:101] op_sel_hi:[1,0]
	v_pk_mul_f32 v[66:67], v[66:67], v[100:101] op_sel_hi:[1,0]
	s_cbranch_vccnz .LBB0_156
; __device__ __forceinline__ unsigned pkh(float lo, float hi) { f32x2 v = {lo, hi}; h16x2 h = __builtin_convertvector(v, h16x2); return __builtin_bit_cast(unsigned, h); }
;     __device__ __forceinline__ void operator()(f32x4 (&acc)[2][2][4][2], const Unit& u, const Order& S, int wr, int wc, int fr_, int fq_, LAS unsigned char*, int) const {
;     ...
; #pragma unroll
;         for (int ai = 0; ai < 2; ++ai)
; #pragma unroll
;             for (int m = 0; m < 4; ++m) {
;                 const int key = ai * HALF + wr * 64 + m * 16 + fr;
;                 const float sc = __builtin_amdgcn_rsqf(ss_in[u.pm * BM + key] * (1.0f / DM) + EPS);
;                 f32x4 v[2][2]; float sq = 0.f;
; #pragma unroll
;                 for (int bj = 0; bj < 2; ++bj)
; #pragma unroll
;                     for (int n = 0; n < 2; ++n) { v[bj][n] = acc[ai][bj][m][n] * sc; const f32x4 t = v[bj][n]; sq += (t[0] * t[0] + t[1] * t[1]) + (t[2] * t[2] + t[3] * t[3]); }
;                 float rn = 1.f;
;                 if (isk) { sq += __shfl_xor(sq, 16); sq += __shfl_xor(sq, 32); rn = __builtin_amdgcn_rsqf(sq * (1.0f / HD) + EPS); }
; #pragma unroll
;                 for (int bj = 0; bj < 2; ++bj) {
;                     const f32x4 a = v[bj][0] * rn * gv[bj][0], b = v[bj][1] * rn * gv[bj][1];
;                     u32x4 w; w.x = pkh(a[0], a[1]); w.y = pkh(a[2], a[3]); w.z = pkh(b[0], b[1]); w.w = pkh(b[2], b[3]);
;                     *(u32x4*)(dst + (size_t)key * HD + 32 * bj + 8 * fq) = w;
;                 }
;             }
	v_pk_mul_f32 v[100:101], v[80:81], v[80:81]
	v_pk_mul_f32 v[102:103], v[78:79], v[78:79]
	s_nop 0
	v_pk_mov_b32 v[104:105], v[102:103], v[100:101] op_sel:[1,0]
	v_mov_b32_e32 v103, v101
	v_pk_add_f32 v[100:101], v[104:105], v[102:103]
	v_pk_mul_f32 v[102:103], v[76:77], v[76:77]
	v_pk_add_f32 v[100:101], v[100:101], v[100:101] op_sel_hi:[0,1]
	v_pk_mul_f32 v[104:105], v[74:75], v[74:75]
	v_mul_f32_e32 v100, v70, v70
	v_pk_mov_b32 v[106:107], v[104:105], v[102:103] op_sel:[1,0]
	v_mov_b32_e32 v105, v103
	v_pk_add_f32 v[102:103], v[106:107], v[104:105]
	v_pk_fma_f32 v[104:105], v[70:71], v[70:71], v[100:101] op_sel_hi:[1,1,0]
	v_mul_f32_e32 v100, v72, v72
	v_pk_add_f32 v[102:103], v[102:103], v[102:103] op_sel_hi:[0,1]
	v_pk_fma_f32 v[106:107], v[72:73], v[72:73], v[100:101] op_sel_hi:[1,1,0]
	v_mul_f32_e32 v104, v66, v66
	v_mul_f32_e32 v106, v67, v67
	v_mul_f32_e32 v100, v68, v68
	v_mul_f32_e32 v102, v69, v69
	v_pk_add_f32 v[104:105], v[104:105], v[106:107]
	v_pk_add_f32 v[100:101], v[100:101], v[102:103]
	s_nop 0
	v_pk_add_f32 v[100:101], v[104:105], v[100:101]
	s_nop 0
	v_add_f32_e32 v99, v100, v101
	v_and_b32_e32 v101, 64, v175
	v_xor_b32_e32 v100, 16, v175
	v_add_u32_e32 v101, 64, v101
	v_cmp_lt_i32_e32 vcc, v100, v101
	s_nop 1
	v_cndmask_b32_e32 v100, v175, v100, vcc
	v_lshlrev_b32_e32 v100, 2, v100
	ds_bpermute_b32 v100, v100, v99
	s_waitcnt lgkmcnt(0)
	v_add_f32_e32 v99, v99, v100
	v_xor_b32_e32 v100, 32, v175
	v_cmp_lt_i32_e32 vcc, v100, v101
	s_nop 1
	v_cndmask_b32_e32 v100, v175, v100, vcc
	v_lshlrev_b32_e32 v100, 2, v100
	ds_bpermute_b32 v100, v100, v99
	s_waitcnt lgkmcnt(0)
	v_add_f32_e32 v99, v99, v100
	v_fmamk_f32 v99, v99, 0x3c800000, v174
	v_rsq_f32_e32 v114, v99
.LBB0_156:
	v_ashrrev_i32_e32 v99, 31, v98
	v_pk_mul_f32 v[80:81], v[80:81], v[114:115] op_sel_hi:[1,0]
	v_pk_mul_f32 v[78:79], v[78:79], v[114:115] op_sel_hi:[1,0]
	v_pk_mul_f32 v[76:77], v[76:77], v[114:115] op_sel_hi:[1,0]
	v_pk_mul_f32 v[74:75], v[74:75], v[114:115] op_sel_hi:[1,0]
	v_lshlrev_b64 v[98:99], 7, v[98:99]
	v_pk_mul_f32 v[80:81], v[88:89], v[80:81]
	v_pk_mul_f32 v[78:79], v[86:87], v[78:79]
	v_pk_mul_f32 v[100:101], v[84:85], v[76:77]
	v_pk_mul_f32 v[76:77], v[82:83], v[74:75]
	v_lshl_add_u64 v[98:99], v[130:131], 0, v[98:99]
	v_cvt_pk_f16_f32 v74, v78, v79
	v_cvt_pk_f16_f32 v75, v80, v81
	v_cvt_pk_f16_f32 v76, v76, v77
	v_cvt_pk_f16_f32 v77, v100, v101
	v_pk_mul_f32 v[72:73], v[72:73], v[114:115] op_sel_hi:[1,0]
	v_pk_mul_f32 v[70:71], v[70:71], v[114:115] op_sel_hi:[1,0]
	v_pk_mul_f32 v[68:69], v[68:69], v[114:115] op_sel_hi:[1,0]
	v_pk_mul_f32 v[66:67], v[66:67], v[114:115] op_sel_hi:[1,0]
	global_store_dwordx4 v[98:99], v[74:77], off sc1
	v_pk_mul_f32 v[72:73], v[96:97], v[72:73]
	v_pk_mul_f32 v[70:71], v[94:95], v[70:71]
	v_pk_mul_f32 v[74:75], v[92:93], v[68:69]
	v_pk_mul_f32 v[68:69], v[90:91], v[66:67]
	v_cvt_pk_f16_f32 v66, v70, v71
	v_cvt_pk_f16_f32 v67, v72, v73
	v_cvt_pk_f16_f32 v68, v68, v69
	v_cvt_pk_f16_f32 v69, v74, v75
	global_store_dwordx4 v[98:99], v[66:69], off offset:64 sc1
	s_and_b64 vcc, exec, s[0:1]
	s_nop 0
	v_add_u32_e32 v68, 0x80, v158
	v_add_u32_e32 v66, s23, v68
	v_ashrrev_i32_e32 v67, 31, v66
	v_lshl_add_u64 v[66:67], v[66:67], 2, s[4:5]
	global_load_dword v66, v[66:67], off
	s_waitcnt vmcnt(0)
	v_fmamk_f32 v66, v66, 0x3a800000, v174
	v_rsq_f32_e32 v70, v66
	v_mov_b32_e32 v66, 1.0
	v_pk_mul_f32 v[64:65], v[64:65], v[70:71] op_sel_hi:[1,0]
	v_pk_mul_f32 v[62:63], v[62:63], v[70:71] op_sel_hi:[1,0]
	v_pk_mul_f32 v[60:61], v[60:61], v[70:71] op_sel_hi:[1,0]
	v_pk_mul_f32 v[58:59], v[58:59], v[70:71] op_sel_hi:[1,0]
	v_pk_mul_f32 v[56:57], v[56:57], v[70:71] op_sel_hi:[1,0]
	v_pk_mul_f32 v[54:55], v[54:55], v[70:71] op_sel_hi:[1,0]
	v_pk_mul_f32 v[52:53], v[52:53], v[70:71] op_sel_hi:[1,0]
	v_pk_mul_f32 v[50:51], v[50:51], v[70:71] op_sel_hi:[1,0]
	v_mov_b32_e32 v70, 1.0
	s_cbranch_vccnz .LBB0_158
	v_pk_mul_f32 v[70:71], v[64:65], v[64:65]
	v_pk_mul_f32 v[72:73], v[62:63], v[62:63]
	v_xor_b32_e32 v69, 16, v175
	v_pk_mov_b32 v[74:75], v[72:73], v[70:71] op_sel:[1,0]
	v_mov_b32_e32 v73, v71
	v_pk_add_f32 v[70:71], v[74:75], v[72:73]
	v_pk_mul_f32 v[72:73], v[60:61], v[60:61]
	v_pk_add_f32 v[70:71], v[70:71], v[70:71] op_sel_hi:[0,1]
	v_pk_mul_f32 v[74:75], v[58:59], v[58:59]
	v_mul_f32_e32 v70, v54, v54
	v_pk_mov_b32 v[76:77], v[74:75], v[72:73] op_sel:[1,0]
	v_mov_b32_e32 v75, v73
	v_pk_add_f32 v[72:73], v[76:77], v[74:75]
	v_pk_fma_f32 v[74:75], v[54:55], v[54:55], v[70:71] op_sel_hi:[1,1,0]
	v_mul_f32_e32 v70, v56, v56
	v_pk_add_f32 v[72:73], v[72:73], v[72:73] op_sel_hi:[0,1]
	v_pk_fma_f32 v[76:77], v[56:57], v[56:57], v[70:71] op_sel_hi:[1,1,0]
	v_mul_f32_e32 v74, v50, v50
	v_mul_f32_e32 v76, v51, v51
	v_mul_f32_e32 v70, v52, v52
	v_mul_f32_e32 v72, v53, v53
	v_pk_add_f32 v[74:75], v[74:75], v[76:77]
	v_pk_add_f32 v[70:71], v[70:71], v[72:73]
	s_nop 0
	v_pk_add_f32 v[70:71], v[74:75], v[70:71]
	s_nop 0
	v_add_f32_e32 v67, v70, v71
	v_and_b32_e32 v70, 64, v175
	v_add_u32_e32 v70, 64, v70
	v_cmp_lt_i32_e32 vcc, v69, v70
	s_nop 1
	v_cndmask_b32_e32 v69, v175, v69, vcc
	v_lshlrev_b32_e32 v69, 2, v69
	ds_bpermute_b32 v69, v69, v67
	s_waitcnt lgkmcnt(0)
	v_add_f32_e32 v67, v67, v69
	v_xor_b32_e32 v69, 32, v175
	v_cmp_lt_i32_e32 vcc, v69, v70
	s_nop 1
	v_cndmask_b32_e32 v69, v175, v69, vcc
	v_lshlrev_b32_e32 v69, 2, v69
	ds_bpermute_b32 v69, v69, v67
	s_waitcnt lgkmcnt(0)
	v_add_f32_e32 v67, v67, v69
	v_fmamk_f32 v67, v67, 0x3c800000, v174
	v_rsq_f32_e32 v70, v67
; __device__ __forceinline__ unsigned pkh(float lo, float hi) { f32x2 v = {lo, hi}; h16x2 h = __builtin_convertvector(v, h16x2); return __builtin_bit_cast(unsigned, h); }
;     __device__ __forceinline__ void operator()(f32x4 (&acc)[2][2][4][2], const Unit& u, const Order& S, int wr, int wc, int fr_, int fq_, LAS unsigned char*, int) const {
;     ...
; #pragma unroll
;         for (int ai = 0; ai < 2; ++ai)
; #pragma unroll
;             for (int m = 0; m < 4; ++m) {
;                 const int key = ai * HALF + wr * 64 + m * 16 + fr;
;                 const float sc = __builtin_amdgcn_rsqf(ss_in[u.pm * BM + key] * (1.0f / DM) + EPS);
;                 f32x4 v[2][2]; float sq = 0.f;
; #pragma unroll
;                 for (int bj = 0; bj < 2; ++bj)
; #pragma unroll
;                     for (int n = 0; n < 2; ++n) { v[bj][n] = acc[ai][bj][m][n] * sc; const f32x4 t = v[bj][n]; sq += (t[0] * t[0] + t[1] * t[1]) + (t[2] * t[2] + t[3] * t[3]); }
;                 float rn = 1.f;
;                 if (isk) { sq += __shfl_xor(sq, 16); sq += __shfl_xor(sq, 32); rn = __builtin_amdgcn_rsqf(sq * (1.0f / HD) + EPS); }
; #pragma unroll
;                 for (int bj = 0; bj < 2; ++bj) {
;                     const f32x4 a = v[bj][0] * rn * gv[bj][0], b = v[bj][1] * rn * gv[bj][1];
;                     u32x4 w; w.x = pkh(a[0], a[1]); w.y = pkh(a[2], a[3]); w.z = pkh(b[0], b[1]); w.w = pkh(b[2], b[3]);
;                     *(u32x4*)(dst + (size_t)key * HD + 32 * bj + 8 * fq) = w;
;                 }
;             }
.LBB0_158:
	v_ashrrev_i32_e32 v69, 31, v68
	v_pk_mul_f32 v[64:65], v[64:65], v[70:71] op_sel_hi:[1,0]
	v_pk_mul_f32 v[62:63], v[62:63], v[70:71] op_sel_hi:[1,0]
	v_pk_mul_f32 v[60:61], v[60:61], v[70:71] op_sel_hi:[1,0]
	v_pk_mul_f32 v[58:59], v[58:59], v[70:71] op_sel_hi:[1,0]
	v_lshlrev_b64 v[68:69], 7, v[68:69]
	v_pk_mul_f32 v[64:65], v[88:89], v[64:65]
	v_pk_mul_f32 v[62:63], v[86:87], v[62:63]
	v_pk_mul_f32 v[72:73], v[84:85], v[60:61]
	v_pk_mul_f32 v[60:61], v[82:83], v[58:59]
	v_lshl_add_u64 v[68:69], v[130:131], 0, v[68:69]
	v_cvt_pk_f16_f32 v58, v62, v63
	v_cvt_pk_f16_f32 v59, v64, v65
	v_cvt_pk_f16_f32 v60, v60, v61
	v_cvt_pk_f16_f32 v61, v72, v73
	v_pk_mul_f32 v[56:57], v[56:57], v[70:71] op_sel_hi:[1,0]
	v_pk_mul_f32 v[54:55], v[54:55], v[70:71] op_sel_hi:[1,0]
	v_pk_mul_f32 v[52:53], v[52:53], v[70:71] op_sel_hi:[1,0]
	v_pk_mul_f32 v[50:51], v[50:51], v[70:71] op_sel_hi:[1,0]
	global_store_dwordx4 v[68:69], v[58:61], off sc1
	v_pk_mul_f32 v[56:57], v[96:97], v[56:57]
	v_pk_mul_f32 v[54:55], v[94:95], v[54:55]
	v_pk_mul_f32 v[58:59], v[92:93], v[52:53]
	v_pk_mul_f32 v[52:53], v[90:91], v[50:51]
	v_cvt_pk_f16_f32 v50, v54, v55
	v_cvt_pk_f16_f32 v51, v56, v57
	v_cvt_pk_f16_f32 v52, v52, v53
	v_cvt_pk_f16_f32 v53, v58, v59
	global_store_dwordx4 v[68:69], v[50:53], off offset:64 sc1
	s_and_b64 vcc, exec, s[0:1]
	s_nop 0
	v_add_u32_e32 v50, 0x90, v158
	v_add_u32_e32 v52, s23, v50
	v_ashrrev_i32_e32 v53, 31, v52
	v_lshl_add_u64 v[52:53], v[52:53], 2, s[4:5]
	global_load_dword v51, v[52:53], off
	s_waitcnt vmcnt(0)
	v_fmamk_f32 v51, v51, 0x3a800000, v174
	v_rsq_f32_e32 v52, v51
	s_nop 0
	v_pk_mul_f32 v[48:49], v[48:49], v[52:53] op_sel_hi:[1,0]
	v_pk_mul_f32 v[46:47], v[46:47], v[52:53] op_sel_hi:[1,0]
	v_pk_mul_f32 v[44:45], v[44:45], v[52:53] op_sel_hi:[1,0]
	v_pk_mul_f32 v[42:43], v[42:43], v[52:53] op_sel_hi:[1,0]
	v_pk_mul_f32 v[40:41], v[40:41], v[52:53] op_sel_hi:[1,0]
	v_pk_mul_f32 v[38:39], v[38:39], v[52:53] op_sel_hi:[1,0]
	v_pk_mul_f32 v[36:37], v[36:37], v[52:53] op_sel_hi:[1,0]
	v_pk_mul_f32 v[34:35], v[34:35], v[52:53] op_sel_hi:[1,0]
	s_cbranch_vccnz .LBB0_160
	v_pk_mul_f32 v[52:53], v[48:49], v[48:49]
	v_pk_mul_f32 v[54:55], v[46:47], v[46:47]
	s_nop 0
	v_pk_mov_b32 v[56:57], v[54:55], v[52:53] op_sel:[1,0]
	v_mov_b32_e32 v55, v53
	v_pk_add_f32 v[52:53], v[56:57], v[54:55]
	v_pk_mul_f32 v[54:55], v[44:45], v[44:45]
	v_pk_add_f32 v[52:53], v[52:53], v[52:53] op_sel_hi:[0,1]
	v_pk_mul_f32 v[56:57], v[42:43], v[42:43]
	v_mul_f32_e32 v52, v38, v38
	v_pk_mov_b32 v[58:59], v[56:57], v[54:55] op_sel:[1,0]
	v_mov_b32_e32 v57, v55
	v_pk_add_f32 v[54:55], v[58:59], v[56:57]
	v_pk_fma_f32 v[56:57], v[38:39], v[38:39], v[52:53] op_sel_hi:[1,1,0]
	v_mul_f32_e32 v52, v40, v40
	v_pk_add_f32 v[54:55], v[54:55], v[54:55] op_sel_hi:[0,1]
	v_pk_fma_f32 v[58:59], v[40:41], v[40:41], v[52:53] op_sel_hi:[1,1,0]
	v_mul_f32_e32 v56, v34, v34
	v_mul_f32_e32 v58, v35, v35
	v_mul_f32_e32 v52, v36, v36
	v_mul_f32_e32 v54, v37, v37
	v_pk_add_f32 v[56:57], v[56:57], v[58:59]
	v_pk_add_f32 v[52:53], v[52:53], v[54:55]
	s_nop 0
	v_pk_add_f32 v[52:53], v[56:57], v[52:53]
	s_nop 0
	v_add_f32_e32 v51, v52, v53
	v_and_b32_e32 v53, 64, v175
	v_xor_b32_e32 v52, 16, v175
	v_add_u32_e32 v53, 64, v53
	v_cmp_lt_i32_e32 vcc, v52, v53
	s_nop 1
	v_cndmask_b32_e32 v52, v175, v52, vcc
	v_lshlrev_b32_e32 v52, 2, v52
	ds_bpermute_b32 v52, v52, v51
	s_waitcnt lgkmcnt(0)
	v_add_f32_e32 v51, v51, v52
	v_xor_b32_e32 v52, 32, v175
	v_cmp_lt_i32_e32 vcc, v52, v53
	s_nop 1
	v_cndmask_b32_e32 v52, v175, v52, vcc
	v_lshlrev_b32_e32 v52, 2, v52
	ds_bpermute_b32 v52, v52, v51
	s_waitcnt lgkmcnt(0)
	v_add_f32_e32 v51, v51, v52
	v_fmamk_f32 v51, v51, 0x3c800000, v174
	v_rsq_f32_e32 v66, v51
.LBB0_160:
	v_ashrrev_i32_e32 v51, 31, v50
	v_pk_mul_f32 v[48:49], v[48:49], v[66:67] op_sel_hi:[1,0]
	v_pk_mul_f32 v[46:47], v[46:47], v[66:67] op_sel_hi:[1,0]
	v_pk_mul_f32 v[44:45], v[44:45], v[66:67] op_sel_hi:[1,0]
	v_pk_mul_f32 v[42:43], v[42:43], v[66:67] op_sel_hi:[1,0]
	v_lshlrev_b64 v[50:51], 7, v[50:51]
	v_pk_mul_f32 v[48:49], v[88:89], v[48:49]
	v_pk_mul_f32 v[46:47], v[86:87], v[46:47]
	v_pk_mul_f32 v[52:53], v[84:85], v[44:45]
	v_pk_mul_f32 v[44:45], v[82:83], v[42:43]
	v_lshl_add_u64 v[50:51], v[130:131], 0, v[50:51]
	v_cvt_pk_f16_f32 v42, v46, v47
	v_cvt_pk_f16_f32 v43, v48, v49
	v_cvt_pk_f16_f32 v44, v44, v45
	v_cvt_pk_f16_f32 v45, v52, v53
	v_pk_mul_f32 v[40:41], v[40:41], v[66:67] op_sel_hi:[1,0]
	v_pk_mul_f32 v[38:39], v[38:39], v[66:67] op_sel_hi:[1,0]
	v_pk_mul_f32 v[36:37], v[36:37], v[66:67] op_sel_hi:[1,0]
	v_pk_mul_f32 v[34:35], v[34:35], v[66:67] op_sel_hi:[1,0]
	global_store_dwordx4 v[50:51], v[42:45], off sc1
	v_pk_mul_f32 v[40:41], v[96:97], v[40:41]
	v_pk_mul_f32 v[38:39], v[94:95], v[38:39]
	v_pk_mul_f32 v[42:43], v[92:93], v[36:37]
	v_pk_mul_f32 v[36:37], v[90:91], v[34:35]
	v_cvt_pk_f16_f32 v34, v38, v39
	v_cvt_pk_f16_f32 v35, v40, v41
	v_cvt_pk_f16_f32 v36, v36, v37
	v_cvt_pk_f16_f32 v37, v42, v43
	global_store_dwordx4 v[50:51], v[34:37], off offset:64 sc1
	s_and_b64 vcc, exec, s[0:1]
	s_nop 0
	v_add_u32_e32 v36, 0xa0, v158
	v_add_u32_e32 v34, s23, v36
	v_ashrrev_i32_e32 v35, 31, v34
	v_lshl_add_u64 v[34:35], v[34:35], 2, s[4:5]
	global_load_dword v34, v[34:35], off
	s_waitcnt vmcnt(0)
	v_fmamk_f32 v34, v34, 0x3a800000, v174
	v_rsq_f32_e32 v38, v34
	v_mov_b32_e32 v34, 1.0
	v_pk_mul_f32 v[32:33], v[32:33], v[38:39] op_sel_hi:[1,0]
	v_pk_mul_f32 v[30:31], v[30:31], v[38:39] op_sel_hi:[1,0]
	v_pk_mul_f32 v[28:29], v[28:29], v[38:39] op_sel_hi:[1,0]
	v_pk_mul_f32 v[26:27], v[26:27], v[38:39] op_sel_hi:[1,0]
	v_pk_mul_f32 v[24:25], v[24:25], v[38:39] op_sel_hi:[1,0]
	v_pk_mul_f32 v[22:23], v[22:23], v[38:39] op_sel_hi:[1,0]
	v_pk_mul_f32 v[20:21], v[20:21], v[38:39] op_sel_hi:[1,0]
	v_pk_mul_f32 v[18:19], v[18:19], v[38:39] op_sel_hi:[1,0]
	v_mov_b32_e32 v38, 1.0
	s_cbranch_vccnz .LBB0_162
; __device__ __forceinline__ unsigned pkh(float lo, float hi) { f32x2 v = {lo, hi}; h16x2 h = __builtin_convertvector(v, h16x2); return __builtin_bit_cast(unsigned, h); }
; #define PG8_BAR __builtin_amdgcn_s_barrier()
; template <class Epi, bool ALIGN_EPI, bool FP8 = false>
; __device__ __forceinline__ void gemm_phase(LAS unsigned char* lds, LAS unsigned char* xl, const Gemm g, const Order& S, const Epi& E) {
;     ...
;         if (!has_next) break;
; #pragma unroll
;         for (int a = 0; a < 2; ++a)
; #pragma unroll
;             for (int b = 0; b < 2; ++b)
; #pragma unroll
;                 for (int m = 0; m < 4; ++m)
; #pragma unroll
;                     for (int n = 0; n < 2; ++n) acc[a][b][m][n] = (f32x4){0.f, 0.f, 0.f, 0.f};
;         cur = nxt; cA = nA; cB = nB; ++ui;
;         if constexpr (ALIGN_EPI) { if (wr == 1) PG8_BAR; }
;     __device__ __forceinline__ void operator()(f32x4 (&acc)[2][2][4][2], const Unit& u, const Order& S, int wr, int wc, int fr_, int fq_, LAS unsigned char*, int) const {
;     ...
; #pragma unroll
;         for (int ai = 0; ai < 2; ++ai)
; #pragma unroll
;             for (int m = 0; m < 4; ++m) {
;                 const int key = ai * HALF + wr * 64 + m * 16 + fr;
;                 const float sc = __builtin_amdgcn_rsqf(ss_in[u.pm * BM + key] * (1.0f / DM) + EPS);
;                 f32x4 v[2][2]; float sq = 0.f;
; #pragma unroll
;                 for (int bj = 0; bj < 2; ++bj)
; #pragma unroll
;                     for (int n = 0; n < 2; ++n) { v[bj][n] = acc[ai][bj][m][n] * sc; const f32x4 t = v[bj][n]; sq += (t[0] * t[0] + t[1] * t[1]) + (t[2] * t[2] + t[3] * t[3]); }
;                 float rn = 1.f;
;                 if (isk) { sq += __shfl_xor(sq, 16); sq += __shfl_xor(sq, 32); rn = __builtin_amdgcn_rsqf(sq * (1.0f / HD) + EPS); }
; #pragma unroll
;                 for (int bj = 0; bj < 2; ++bj) {
;                     const f32x4 a = v[bj][0] * rn * gv[bj][0], b = v[bj][1] * rn * gv[bj][1];
;                     u32x4 w; w.x = pkh(a[0], a[1]); w.y = pkh(a[2], a[3]); w.z = pkh(b[0], b[1]); w.w = pkh(b[2], b[3]);
;                     *(u32x4*)(dst + (size_t)key * HD + 32 * bj + 8 * fq) = w;
;                 }
;             }
	v_pk_mul_f32 v[38:39], v[32:33], v[32:33]
	v_pk_mul_f32 v[40:41], v[30:31], v[30:31]
	v_xor_b32_e32 v37, 16, v175
	v_pk_mov_b32 v[42:43], v[40:41], v[38:39] op_sel:[1,0]
	v_mov_b32_e32 v41, v39
	v_pk_add_f32 v[38:39], v[42:43], v[40:41]
	v_pk_mul_f32 v[40:41], v[28:29], v[28:29]
	v_pk_add_f32 v[38:39], v[38:39], v[38:39] op_sel_hi:[0,1]
	v_pk_mul_f32 v[42:43], v[26:27], v[26:27]
	v_mul_f32_e32 v38, v22, v22
	v_pk_mov_b32 v[44:45], v[42:43], v[40:41] op_sel:[1,0]
	v_mov_b32_e32 v43, v41
	v_pk_add_f32 v[40:41], v[44:45], v[42:43]
	v_pk_fma_f32 v[42:43], v[22:23], v[22:23], v[38:39] op_sel_hi:[1,1,0]
	v_mul_f32_e32 v38, v24, v24
	v_pk_add_f32 v[40:41], v[40:41], v[40:41] op_sel_hi:[0,1]
	v_pk_fma_f32 v[44:45], v[24:25], v[24:25], v[38:39] op_sel_hi:[1,1,0]
	v_mul_f32_e32 v42, v18, v18
	v_mul_f32_e32 v44, v19, v19
	v_mul_f32_e32 v38, v20, v20
	v_mul_f32_e32 v40, v21, v21
	v_pk_add_f32 v[42:43], v[42:43], v[44:45]
	v_pk_add_f32 v[38:39], v[38:39], v[40:41]
	s_nop 0
	v_pk_add_f32 v[38:39], v[42:43], v[38:39]
	s_nop 0
	v_add_f32_e32 v35, v38, v39
	v_and_b32_e32 v38, 64, v175
	v_add_u32_e32 v38, 64, v38
	v_cmp_lt_i32_e32 vcc, v37, v38
	s_nop 1
	v_cndmask_b32_e32 v37, v175, v37, vcc
	v_lshlrev_b32_e32 v37, 2, v37
	ds_bpermute_b32 v37, v37, v35
	s_waitcnt lgkmcnt(0)
	v_add_f32_e32 v35, v35, v37
	v_xor_b32_e32 v37, 32, v175
	v_cmp_lt_i32_e32 vcc, v37, v38
	s_nop 1
	v_cndmask_b32_e32 v37, v175, v37, vcc
	v_lshlrev_b32_e32 v37, 2, v37
	ds_bpermute_b32 v37, v37, v35
	s_waitcnt lgkmcnt(0)
	v_add_f32_e32 v35, v35, v37
	v_fmamk_f32 v35, v35, 0x3c800000, v174
	v_rsq_f32_e32 v38, v35
.LBB0_162:
	v_ashrrev_i32_e32 v37, 31, v36
	v_pk_mul_f32 v[32:33], v[32:33], v[38:39] op_sel_hi:[1,0]
	v_pk_mul_f32 v[30:31], v[30:31], v[38:39] op_sel_hi:[1,0]
	v_pk_mul_f32 v[28:29], v[28:29], v[38:39] op_sel_hi:[1,0]
	v_pk_mul_f32 v[26:27], v[26:27], v[38:39] op_sel_hi:[1,0]
	v_lshlrev_b64 v[36:37], 7, v[36:37]
	v_pk_mul_f32 v[32:33], v[88:89], v[32:33]
	v_pk_mul_f32 v[30:31], v[86:87], v[30:31]
	v_pk_mul_f32 v[40:41], v[84:85], v[28:29]
	v_pk_mul_f32 v[28:29], v[82:83], v[26:27]
	v_lshl_add_u64 v[36:37], v[130:131], 0, v[36:37]
	v_cvt_pk_f16_f32 v26, v30, v31
	v_cvt_pk_f16_f32 v27, v32, v33
	v_cvt_pk_f16_f32 v28, v28, v29
	v_cvt_pk_f16_f32 v29, v40, v41
	v_pk_mul_f32 v[24:25], v[24:25], v[38:39] op_sel_hi:[1,0]
	v_pk_mul_f32 v[22:23], v[22:23], v[38:39] op_sel_hi:[1,0]
	v_pk_mul_f32 v[20:21], v[20:21], v[38:39] op_sel_hi:[1,0]
	v_pk_mul_f32 v[18:19], v[18:19], v[38:39] op_sel_hi:[1,0]
	global_store_dwordx4 v[36:37], v[26:29], off sc1
	v_pk_mul_f32 v[24:25], v[96:97], v[24:25]
	v_pk_mul_f32 v[22:23], v[94:95], v[22:23]
	v_pk_mul_f32 v[26:27], v[92:93], v[20:21]
	v_pk_mul_f32 v[20:21], v[90:91], v[18:19]
	v_cvt_pk_f16_f32 v18, v22, v23
	v_cvt_pk_f16_f32 v19, v24, v25
	v_cvt_pk_f16_f32 v20, v20, v21
	v_cvt_pk_f16_f32 v21, v26, v27
	global_store_dwordx4 v[36:37], v[18:21], off offset:64 sc1
	s_and_b64 vcc, exec, s[0:1]
	s_nop 0
	v_add_u32_e32 v18, 0xb0, v158
	v_add_u32_e32 v20, s23, v18
	v_ashrrev_i32_e32 v21, 31, v20
	v_lshl_add_u64 v[20:21], v[20:21], 2, s[4:5]
	global_load_dword v19, v[20:21], off
	s_waitcnt vmcnt(0)
	v_fmamk_f32 v19, v19, 0x3a800000, v174
	v_rsq_f32_e32 v20, v19
	s_nop 0
	v_pk_mul_f32 v[16:17], v[16:17], v[20:21] op_sel_hi:[1,0]
	v_pk_mul_f32 v[14:15], v[14:15], v[20:21] op_sel_hi:[1,0]
	v_pk_mul_f32 v[12:13], v[12:13], v[20:21] op_sel_hi:[1,0]
	v_pk_mul_f32 v[10:11], v[10:11], v[20:21] op_sel_hi:[1,0]
	v_pk_mul_f32 v[8:9], v[8:9], v[20:21] op_sel_hi:[1,0]
	v_pk_mul_f32 v[6:7], v[6:7], v[20:21] op_sel_hi:[1,0]
	v_pk_mul_f32 v[4:5], v[4:5], v[20:21] op_sel_hi:[1,0]
	v_pk_mul_f32 v[2:3], v[2:3], v[20:21] op_sel_hi:[1,0]
	s_cbranch_vccnz .LBB0_164
	v_pk_mul_f32 v[20:21], v[16:17], v[16:17]
	v_pk_mul_f32 v[22:23], v[14:15], v[14:15]
	s_nop 0
	v_pk_mov_b32 v[24:25], v[22:23], v[20:21] op_sel:[1,0]
	v_mov_b32_e32 v23, v21
	v_pk_add_f32 v[20:21], v[24:25], v[22:23]
	v_pk_mul_f32 v[22:23], v[12:13], v[12:13]
	v_pk_add_f32 v[20:21], v[20:21], v[20:21] op_sel_hi:[0,1]
	v_pk_mul_f32 v[24:25], v[10:11], v[10:11]
	v_mul_f32_e32 v20, v6, v6
	v_pk_mov_b32 v[26:27], v[24:25], v[22:23] op_sel:[1,0]
	v_mov_b32_e32 v25, v23
	v_pk_add_f32 v[22:23], v[26:27], v[24:25]
	v_pk_fma_f32 v[24:25], v[6:7], v[6:7], v[20:21] op_sel_hi:[1,1,0]
	v_mul_f32_e32 v20, v8, v8
	v_pk_add_f32 v[22:23], v[22:23], v[22:23] op_sel_hi:[0,1]
	v_pk_fma_f32 v[26:27], v[8:9], v[8:9], v[20:21] op_sel_hi:[1,1,0]
	v_mul_f32_e32 v24, v2, v2
	v_mul_f32_e32 v26, v3, v3
	v_mul_f32_e32 v20, v4, v4
	v_mul_f32_e32 v22, v5, v5
	v_pk_add_f32 v[24:25], v[24:25], v[26:27]
	v_pk_add_f32 v[20:21], v[20:21], v[22:23]
	s_nop 0
	v_pk_add_f32 v[20:21], v[24:25], v[20:21]
	s_nop 0
	v_add_f32_e32 v19, v20, v21
	v_and_b32_e32 v21, 64, v175
	v_xor_b32_e32 v20, 16, v175
	v_add_u32_e32 v21, 64, v21
	v_cmp_lt_i32_e32 vcc, v20, v21
	s_nop 1
	v_cndmask_b32_e32 v20, v175, v20, vcc
	v_lshlrev_b32_e32 v20, 2, v20
	ds_bpermute_b32 v20, v20, v19
	s_waitcnt lgkmcnt(0)
	v_add_f32_e32 v19, v19, v20
	v_xor_b32_e32 v20, 32, v175
	v_cmp_lt_i32_e32 vcc, v20, v21
	s_nop 1
	v_cndmask_b32_e32 v20, v175, v20, vcc
	v_lshlrev_b32_e32 v20, 2, v20
	ds_bpermute_b32 v20, v20, v19
	s_waitcnt lgkmcnt(0)
	v_add_f32_e32 v19, v19, v20
	v_fmamk_f32 v19, v19, 0x3c800000, v174
	v_rsq_f32_e32 v34, v19
.LBB0_164:
	v_ashrrev_i32_e32 v19, 31, v18
	v_pk_mul_f32 v[16:17], v[16:17], v[34:35] op_sel_hi:[1,0]
	v_pk_mul_f32 v[14:15], v[14:15], v[34:35] op_sel_hi:[1,0]
	v_pk_mul_f32 v[12:13], v[12:13], v[34:35] op_sel_hi:[1,0]
	v_pk_mul_f32 v[10:11], v[10:11], v[34:35] op_sel_hi:[1,0]
	v_lshlrev_b64 v[18:19], 7, v[18:19]
	v_pk_mul_f32 v[16:17], v[88:89], v[16:17]
	v_pk_mul_f32 v[14:15], v[86:87], v[14:15]
	v_pk_mul_f32 v[20:21], v[84:85], v[12:13]
	v_pk_mul_f32 v[12:13], v[82:83], v[10:11]
	v_lshl_add_u64 v[18:19], v[130:131], 0, v[18:19]
	v_cvt_pk_f16_f32 v10, v14, v15
	v_cvt_pk_f16_f32 v11, v16, v17
	v_cvt_pk_f16_f32 v12, v12, v13
	v_cvt_pk_f16_f32 v13, v20, v21
	v_pk_mul_f32 v[8:9], v[8:9], v[34:35] op_sel_hi:[1,0]
	v_pk_mul_f32 v[6:7], v[6:7], v[34:35] op_sel_hi:[1,0]
	v_pk_mul_f32 v[4:5], v[4:5], v[34:35] op_sel_hi:[1,0]
	v_pk_mul_f32 v[2:3], v[2:3], v[34:35] op_sel_hi:[1,0]
	global_store_dwordx4 v[18:19], v[10:13], off sc1
	v_pk_mul_f32 v[8:9], v[96:97], v[8:9]
	v_pk_mul_f32 v[6:7], v[94:95], v[6:7]
	v_pk_mul_f32 v[10:11], v[92:93], v[4:5]
	v_pk_mul_f32 v[4:5], v[90:91], v[2:3]
	v_cvt_pk_f16_f32 v2, v6, v7
	v_cvt_pk_f16_f32 v3, v8, v9
	v_cvt_pk_f16_f32 v4, v4, v5
	v_cvt_pk_f16_f32 v5, v10, v11
	s_andn2_b64 vcc, exec, s[24:25]
	s_mov_b64 s[0:1], -1
	global_store_dwordx4 v[18:19], v[2:5], off offset:64 sc1
	s_cbranch_vccnz .LBB0_133
	s_andn2_b64 vcc, exec, s[2:3]
	s_cbranch_vccnz .LBB0_132
	s_barrier
	s_branch .LBB0_132

; #define LAS __attribute__((address_space(3)))
; #define GAS __attribute__((address_space(1)))
; #define LDS_WAIT() asm volatile("s_waitcnt lgkmcnt(0)" ::: "memory")
; __device__ __forceinline__ unsigned pkh(float lo, float hi) { f32x2 v = {lo, hi}; h16x2 h = __builtin_convertvector(v, h16x2); return __builtin_bit_cast(unsigned, h); }
; template <bool FP8>
; __device__ __forceinline__ void p0_transpose_item(const float* W, int K, int N, f16_t* WT, const float* gain, LAS float* scr, int k0, int n0, int dst0, int lane) {
;     { f32x4 v[8];
; #pragma unroll
;         for (int i = 0; i < 8; ++i) v[i] = __builtin_nontemporal_load((const f32x4*)(W + (size_t)(k0 + (lane >> 3) + 8 * i) * N + n0 + 4 * (lane & 7)));
; #pragma unroll
;         for (int i = 0; i < 8; ++i) { const int kk = (lane >> 3) + 8 * i; const float gsc = (gain ? gain[k0 + kk] : 1.0f) * (FP8 ? F8_SW : 1.0f);
; #pragma unroll
;             for (int e = 0; e < 4; ++e) scr[kk * 33 + 4 * (lane & 7) + e] = v[i][e] * gsc; } }
;     LDS_WAIT(); asm volatile("" ::: "memory");
;     const int c = lane & 7;
; #pragma unroll
;     for (int j = 0; j < 4; ++j) { const int n = (lane >> 3) + 8 * j; const LAS float* s = scr + (8 * c) * 33 + n;
;         if constexpr (FP8) { u32x2 o; o.x = pk8(s[0 * 33], s[1 * 33], s[2 * 33], s[3 * 33]); o.y = pk8(s[4 * 33], s[5 * 33], s[6 * 33], s[7 * 33]);
;             *(GAS u32x2*)((unsigned char*)WT + (size_t)(dst0 + n) * K + k0 + 8 * c) = o; }
;         else { u32x4 o; o.x = pkh(s[0 * 33], s[1 * 33]); o.y = pkh(s[2 * 33], s[3 * 33]); o.z = pkh(s[4 * 33], s[5 * 33]); o.w = pkh(s[6 * 33], s[7 * 33]);
;             *(GAS u32x4*)(WT + (size_t)(dst0 + n) * K + k0 + 8 * c) = o; } }
;     LDS_WAIT(); asm volatile("" ::: "memory");
; }
; template <int MAP, bool FP8 = false>
; __device__ __forceinline__ void p0_matrix(const Frame& F, const float* W, int K, int N, f16_t* WT, const float* gain, int& base, int gw, int NGW, LAS float* scr) {
;     ...
;     for (int it = first; it < items; it += NGW) {
;         const int kb = it / nblk, nb = it % nblk, n0 = 32 * nb;
;         const int d0 = (MAP == 0) ? map_ident(n0) : (MAP == 1) ? map_heads(n0) : map_up(n0);
;         p0_transpose_item<FP8>(W, K, N, WT, gain, scr, 64 * kb, n0, d0, F.lane);
.LBB0_253:
	s_ashr_i32 s0, s6, 31
	s_lshr_b32 s0, s0, 27
	s_add_i32 s0, s6, s0
	s_ashr_i32 s0, s0, 5
	s_lshl_b32 s2, s0, 6
	s_lshl_b32 s1, s0, 10
	v_or_b32_e32 v24, s2, v6
	s_sub_i32 s0, s4, s1
	v_or_b32_e32 v26, 8, v24
	v_or_b32_e32 v28, 16, v24
	v_or_b32_e32 v30, 24, v24
	v_or_b32_e32 v32, 32, v24
	v_or_b32_e32 v34, 40, v24
	v_or_b32_e32 v36, 48, v24
	v_or_b32_e32 v38, 56, v24
	s_ashr_i32 s1, s0, 31
	v_ashrrev_i32_e32 v25, 31, v24
	v_ashrrev_i32_e32 v27, 31, v26
	v_ashrrev_i32_e32 v29, 31, v28
	v_ashrrev_i32_e32 v31, 31, v30
	v_ashrrev_i32_e32 v33, 31, v32
	v_ashrrev_i32_e32 v35, 31, v34
	v_ashrrev_i32_e32 v37, 31, v36
	v_ashrrev_i32_e32 v39, 31, v38
	v_lshl_add_u64 v[40:41], s[0:1], 2, v[2:3]
	v_lshlrev_b64 v[24:25], 12, v[24:25]
	v_lshlrev_b64 v[42:43], 12, v[26:27]
	v_lshlrev_b64 v[28:29], 12, v[28:29]
	v_lshlrev_b64 v[30:31], 12, v[30:31]
	v_lshlrev_b64 v[32:33], 12, v[32:33]
	v_lshlrev_b64 v[34:35], 12, v[34:35]
	v_lshlrev_b64 v[36:37], 12, v[36:37]
	v_lshlrev_b64 v[38:39], 12, v[38:39]
	v_lshl_add_u64 v[24:25], v[40:41], 0, v[24:25]
	v_lshl_add_u64 v[42:43], v[40:41], 0, v[42:43]
	v_lshl_add_u64 v[44:45], v[40:41], 0, v[28:29]
	v_lshl_add_u64 v[46:47], v[40:41], 0, v[30:31]
	v_lshl_add_u64 v[48:49], v[40:41], 0, v[32:33]
	v_lshl_add_u64 v[50:51], v[40:41], 0, v[34:35]
	v_lshl_add_u64 v[52:53], v[40:41], 0, v[36:37]
	v_lshl_add_u64 v[54:55], v[40:41], 0, v[38:39]
	global_load_dwordx4 v[24:27], v[24:25], off nt
	s_nop 0
	global_load_dwordx4 v[28:31], v[42:43], off nt
	global_load_dwordx4 v[32:35], v[44:45], off nt
	global_load_dwordx4 v[36:39], v[46:47], off nt
	s_nop 0
	global_load_dwordx4 v[40:43], v[48:49], off nt
	global_load_dwordx4 v[44:47], v[50:51], off nt
	s_nop 0
	global_load_dwordx4 v[48:51], v[52:53], off nt
	s_nop 0
	global_load_dwordx4 v[52:55], v[54:55], off nt
	v_add_u32_e32 v58, s0, v6
	v_add_u32_e32 v60, 8, v58
	v_add_u32_e32 v62, 16, v58
	v_add_u32_e32 v64, 24, v58
	s_ashr_i32 s3, s2, 31
	v_ashrrev_i32_e32 v59, 31, v58
	v_ashrrev_i32_e32 v61, 31, v60
	v_ashrrev_i32_e32 v63, 31, v62
	v_ashrrev_i32_e32 v65, 31, v64
	v_lshl_add_u64 v[56:57], s[2:3], 1, v[4:5]
	v_lshlrev_b64 v[58:59], 11, v[58:59]
	v_lshlrev_b64 v[60:61], 11, v[60:61]
	v_lshlrev_b64 v[62:63], 11, v[62:63]
	v_lshlrev_b64 v[64:65], 11, v[64:65]
	v_lshl_add_u64 v[58:59], v[56:57], 0, v[58:59]
	v_lshl_add_u64 v[60:61], v[56:57], 0, v[60:61]
	v_lshl_add_u64 v[62:63], v[56:57], 0, v[62:63]
	v_lshl_add_u64 v[56:57], v[56:57], 0, v[64:65]
	s_add_i32 s6, s6, s18
	s_add_i32 s4, s4, s5
	s_cmpk_lt_i32 s6, 0x200
	s_waitcnt vmcnt(7)
	ds_write2_b32 v8, v24, v25 offset1:1
	ds_write2_b32 v8, v26, v27 offset0:2 offset1:3
	s_waitcnt vmcnt(6)
	ds_write2_b32 v9, v28, v29 offset1:1
	ds_write2_b32 v10, v30, v31 offset1:1
	s_waitcnt vmcnt(5)
	ds_write2_b32 v11, v32, v33 offset1:1
	ds_write2_b32 v12, v34, v35 offset1:1
	s_waitcnt vmcnt(4)
	ds_write2_b32 v13, v36, v37 offset1:1
	ds_write2_b32 v14, v38, v39 offset1:1
	s_waitcnt vmcnt(3)
	ds_write2_b32 v15, v40, v41 offset1:1
	ds_write2_b32 v16, v42, v43 offset1:1
	s_waitcnt vmcnt(2)
	ds_write2_b32 v17, v44, v45 offset1:1
	ds_write2_b32 v18, v46, v47 offset1:1
	s_waitcnt vmcnt(1)
	ds_write2_b32 v19, v48, v49 offset1:1
	ds_write2_b32 v20, v50, v51 offset1:1
	s_waitcnt vmcnt(0)
	ds_write2_b32 v21, v52, v53 offset1:1
	ds_write2_b32 v22, v54, v55 offset1:1
	s_waitcnt lgkmcnt(0)
	ds_read2_b32 v[28:29], v7 offset0:33 offset1:41
	ds_read2_b32 v[30:31], v7 offset1:8
	ds_read2_b32 v[32:33], v7 offset0:66 offset1:74
	ds_read2_b32 v[34:35], v7 offset0:99 offset1:107
	ds_read2_b32 v[36:37], v7 offset0:132 offset1:140
	ds_read2_b32 v[38:39], v7 offset0:165 offset1:173
	ds_read2_b32 v[40:41], v7 offset0:198 offset1:206
	ds_read2_b32 v[42:43], v7 offset0:231 offset1:239
	ds_read2_b32 v[44:45], v7 offset0:49 offset1:57
	ds_read2_b32 v[46:47], v7 offset0:16 offset1:24
	ds_read2_b32 v[48:49], v7 offset0:82 offset1:90
	ds_read2_b32 v[50:51], v7 offset0:115 offset1:123
	ds_read2_b32 v[52:53], v7 offset0:148 offset1:156
	ds_read2_b32 v[54:55], v7 offset0:181 offset1:189
	ds_read2_b32 v[64:65], v7 offset0:214 offset1:222
	ds_read2_b32 v[66:67], v7 offset0:247 offset1:255
	s_waitcnt lgkmcnt(14)
	v_cvt_pk_f16_f32 v24, v30, v28
	s_waitcnt lgkmcnt(12)
	v_cvt_pk_f16_f32 v25, v32, v34
	s_waitcnt lgkmcnt(10)
	v_cvt_pk_f16_f32 v26, v36, v38
	s_waitcnt lgkmcnt(8)
	v_cvt_pk_f16_f32 v27, v40, v42
	v_cvt_pk_f16_f32 v28, v31, v29
	v_cvt_pk_f16_f32 v29, v33, v35
	v_cvt_pk_f16_f32 v30, v37, v39
	v_cvt_pk_f16_f32 v31, v41, v43
	s_waitcnt lgkmcnt(6)
	v_cvt_pk_f16_f32 v32, v46, v44
	s_waitcnt lgkmcnt(4)
	v_cvt_pk_f16_f32 v33, v48, v50
	s_waitcnt lgkmcnt(2)
	v_cvt_pk_f16_f32 v34, v52, v54
	s_waitcnt lgkmcnt(0)
	v_cvt_pk_f16_f32 v35, v64, v66
	v_cvt_pk_f16_f32 v36, v47, v45
	v_cvt_pk_f16_f32 v37, v49, v51
	v_cvt_pk_f16_f32 v38, v53, v55
	v_cvt_pk_f16_f32 v39, v65, v67
	global_store_dwordx4 v[58:59], v[24:27], off sc1
	global_store_dwordx4 v[60:61], v[28:31], off sc1
	global_store_dwordx4 v[62:63], v[32:35], off sc1
	global_store_dwordx4 v[56:57], v[36:39], off sc1
	s_waitcnt lgkmcnt(0)
	s_cbranch_scc1 .LBB0_253

; #define LAS __attribute__((address_space(3)))
; #define GAS __attribute__((address_space(1)))
; #define LDS_WAIT() asm volatile("s_waitcnt lgkmcnt(0)" ::: "memory")
; __device__ __forceinline__ unsigned pkh(float lo, float hi) { f32x2 v = {lo, hi}; h16x2 h = __builtin_convertvector(v, h16x2); return __builtin_bit_cast(unsigned, h); }
; __device__ __forceinline__ unsigned pk8(float a, float b, float c, float d) { int w = __builtin_amdgcn_cvt_pk_fp8_f32(a, b, 0, false); w = __builtin_amdgcn_cvt_pk_fp8_f32(c, d, w, true); return (unsigned)w; }
; template <bool FP8>
; __device__ __forceinline__ void p0_transpose_item(const float* W, int K, int N, f16_t* WT, const float* gain, LAS float* scr, int k0, int n0, int dst0, int lane) {
;     ...
;         for (int i = 0; i < 8; ++i) v[i] = __builtin_nontemporal_load((const f32x4*)(W + (size_t)(k0 + (lane >> 3) + 8 * i) * N + n0 + 4 * (lane & 7)));
; #pragma unroll
;         for (int i = 0; i < 8; ++i) { const int kk = (lane >> 3) + 8 * i; const float gsc = (gain ? gain[k0 + kk] : 1.0f) * (FP8 ? F8_SW : 1.0f);
; #pragma unroll
;             for (int e = 0; e < 4; ++e) scr[kk * 33 + 4 * (lane & 7) + e] = v[i][e] * gsc; } }
;     LDS_WAIT(); asm volatile("" ::: "memory");
;     const int c = lane & 7;
; #pragma unroll
;     for (int j = 0; j < 4; ++j) { const int n = (lane >> 3) + 8 * j; const LAS float* s = scr + (8 * c) * 33 + n;
;         if constexpr (FP8) { u32x2 o; o.x = pk8(s[0 * 33], s[1 * 33], s[2 * 33], s[3 * 33]); o.y = pk8(s[4 * 33], s[5 * 33], s[6 * 33], s[7 * 33]);
;             *(GAS u32x2*)((unsigned char*)WT + (size_t)(dst0 + n) * K + k0 + 8 * c) = o; }
;         else { u32x4 o; o.x = pkh(s[0 * 33], s[1 * 33]); o.y = pkh(s[2 * 33], s[3 * 33]); o.z = pkh(s[4 * 33], s[5 * 33]); o.w = pkh(s[6 * 33], s[7 * 33]);
;             *(GAS u32x4*)(WT + (size_t)(dst0 + n) * K + k0 + 8 * c) = o; } }
; template <int MAP, bool FP8 = false>
; __device__ __forceinline__ void p0_matrix(const Frame& F, const float* W, int K, int N, f16_t* WT, const float* gain, int& base, int gw, int NGW, LAS float* scr) {
;     ...
;     for (int it = first; it < items; it += NGW) {
;         const int kb = it / nblk, nb = it % nblk, n0 = 32 * nb;
;         const int d0 = (MAP == 0) ? map_ident(n0) : (MAP == 1) ? map_heads(n0) : map_up(n0);
;         p0_transpose_item<FP8>(W, K, N, WT, gain, scr, 64 * kb, n0, d0, F.lane);
.LBB0_256:
	s_mulk_i32 s28, 0xff50
	v_add_u32_e32 v11, 0x18c0, v48
	s_add_i32 s7, s23, s28
	ds_write2_b32 v11, v6, v7 offset1:1
	v_add_u32_e32 v6, 0x18c8, v48
	s_cmpk_gt_i32 s7, 0x57
	ds_write2_b32 v6, v8, v9 offset1:1
	s_waitcnt vmcnt(0)
	v_pk_mul_f32 v[2:3], v[2:3], v[10:11] op_sel_hi:[1,0]
	v_add_u32_e32 v6, 0x1ce0, v48
	s_cselect_b32 s7, 0xfffff500, 0
	ds_write2_b32 v6, v2, v3 offset1:1
	v_pk_mul_f32 v[2:3], v[4:5], v[10:11] op_sel_hi:[1,0]
	v_add_u32_e32 v4, 0x1ce8, v48
	s_cselect_b32 s14, 0x80, 0
	s_add_i32 s7, s7, s24
	ds_write2_b32 v4, v2, v3 offset1:1
	s_add_i32 s7, s7, s27
	s_waitcnt lgkmcnt(0)
	s_lshl_b32 s7, s7, 1
	s_and_b32 s6, s6, 0x60
	s_and_b32 s7, s7, 0xffffff00
	s_or_b32 s6, s14, s6
	ds_read2_b32 v[6:7], v47 offset0:33 offset1:41
	ds_read2_b32 v[8:9], v47 offset1:8
	ds_read2_b32 v[10:11], v47 offset0:66 offset1:74
	ds_read2_b32 v[12:13], v47 offset0:99 offset1:107
	ds_read2_b32 v[14:15], v47 offset0:132 offset1:140
	ds_read2_b32 v[16:17], v47 offset0:165 offset1:173
	ds_read2_b32 v[18:19], v47 offset0:198 offset1:206
	ds_read2_b32 v[20:21], v47 offset0:231 offset1:239
	s_or_b32 s6, s6, s7
	v_or_b32_e32 v24, s6, v34
	v_ashrrev_i32_e32 v25, 31, v24
	v_lshl_add_u64 v[22:23], s[4:5], 1, v[38:39]
	v_lshlrev_b64 v[24:25], 11, v[24:25]
	s_waitcnt lgkmcnt(6)
	v_cvt_pk_f16_f32 v2, v8, v6
	s_waitcnt lgkmcnt(4)
	v_cvt_pk_f16_f32 v3, v10, v12
	s_waitcnt lgkmcnt(2)
	v_cvt_pk_f16_f32 v4, v14, v16
	s_waitcnt lgkmcnt(0)
	v_cvt_pk_f16_f32 v5, v18, v20
	v_lshl_add_u64 v[24:25], v[22:23], 0, v[24:25]
	v_or_b32_e32 v6, s6, v41
	global_store_dwordx4 v[24:25], v[2:5], off sc1
	s_add_i32 s23, s23, s18
	s_add_i32 s24, s24, s25
	v_cvt_pk_f16_f32 v2, v9, v7
	v_ashrrev_i32_e32 v7, 31, v6
	v_cvt_pk_f16_f32 v3, v11, v13
	v_cvt_pk_f16_f32 v4, v15, v17
	v_cvt_pk_f16_f32 v5, v19, v21
	v_lshlrev_b64 v[6:7], 11, v[6:7]
	ds_read2_b32 v[8:9], v47 offset0:49 offset1:57
	ds_read2_b32 v[10:11], v47 offset0:16 offset1:24
	ds_read2_b32 v[12:13], v47 offset0:82 offset1:90
	ds_read2_b32 v[14:15], v47 offset0:115 offset1:123
	ds_read2_b32 v[16:17], v47 offset0:148 offset1:156
	ds_read2_b32 v[18:19], v47 offset0:181 offset1:189
	ds_read2_b32 v[20:21], v47 offset0:214 offset1:222
	ds_read2_b32 v[24:25], v47 offset0:247 offset1:255
	v_lshl_add_u64 v[6:7], v[22:23], 0, v[6:7]
	global_store_dwordx4 v[6:7], v[2:5], off sc1
	v_or_b32_e32 v6, s6, v45
	v_ashrrev_i32_e32 v7, 31, v6
	v_lshlrev_b64 v[6:7], 11, v[6:7]
	s_waitcnt lgkmcnt(6)
	v_cvt_pk_f16_f32 v2, v10, v8
	s_waitcnt lgkmcnt(4)
	v_cvt_pk_f16_f32 v3, v12, v14
	s_waitcnt lgkmcnt(2)
	v_cvt_pk_f16_f32 v4, v16, v18
	s_waitcnt lgkmcnt(0)
	v_cvt_pk_f16_f32 v5, v20, v24
	v_lshl_add_u64 v[6:7], v[22:23], 0, v[6:7]
	global_store_dwordx4 v[6:7], v[2:5], off sc1
	v_or_b32_e32 v6, s6, v46
	v_ashrrev_i32_e32 v7, 31, v6
	v_lshlrev_b64 v[6:7], 11, v[6:7]
	v_cvt_pk_f16_f32 v2, v11, v9
	v_cvt_pk_f16_f32 v3, v13, v15
	v_cvt_pk_f16_f32 v4, v17, v19
	v_cvt_pk_f16_f32 v5, v21, v25
	v_lshl_add_u64 v[6:7], v[22:23], 0, v[6:7]
	global_store_dwordx4 v[6:7], v[2:5], off sc1
	s_waitcnt lgkmcnt(0)
	s_cmpk_lt_i32 s23, 0xb00
	s_cbranch_scc0 .LBB0_268

; #define LAS __attribute__((address_space(3)))
; #define GAS __attribute__((address_space(1)))
; #define LDS_WAIT() asm volatile("s_waitcnt lgkmcnt(0)" ::: "memory")
; __device__ __forceinline__ unsigned pkh(float lo, float hi) { f32x2 v = {lo, hi}; h16x2 h = __builtin_convertvector(v, h16x2); return __builtin_bit_cast(unsigned, h); }
; template <bool FP8>
; __device__ __forceinline__ void p0_transpose_item(const float* W, int K, int N, f16_t* WT, const float* gain, LAS float* scr, int k0, int n0, int dst0, int lane) {
;     { f32x4 v[8];
; #pragma unroll
;         for (int i = 0; i < 8; ++i) v[i] = __builtin_nontemporal_load((const f32x4*)(W + (size_t)(k0 + (lane >> 3) + 8 * i) * N + n0 + 4 * (lane & 7)));
; #pragma unroll
;         for (int i = 0; i < 8; ++i) { const int kk = (lane >> 3) + 8 * i; const float gsc = (gain ? gain[k0 + kk] : 1.0f) * (FP8 ? F8_SW : 1.0f);
; #pragma unroll
;             for (int e = 0; e < 4; ++e) scr[kk * 33 + 4 * (lane & 7) + e] = v[i][e] * gsc; } }
;     LDS_WAIT(); asm volatile("" ::: "memory");
;     const int c = lane & 7;
; #pragma unroll
;     for (int j = 0; j < 4; ++j) { const int n = (lane >> 3) + 8 * j; const LAS float* s = scr + (8 * c) * 33 + n;
;         if constexpr (FP8) { u32x2 o; o.x = pk8(s[0 * 33], s[1 * 33], s[2 * 33], s[3 * 33]); o.y = pk8(s[4 * 33], s[5 * 33], s[6 * 33], s[7 * 33]);
;             *(GAS u32x2*)((unsigned char*)WT + (size_t)(dst0 + n) * K + k0 + 8 * c) = o; }
;         else { u32x4 o; o.x = pkh(s[0 * 33], s[1 * 33]); o.y = pkh(s[2 * 33], s[3 * 33]); o.z = pkh(s[4 * 33], s[5 * 33]); o.w = pkh(s[6 * 33], s[7 * 33]);
;             *(GAS u32x4*)(WT + (size_t)(dst0 + n) * K + k0 + 8 * c) = o; } }
;     LDS_WAIT(); asm volatile("" ::: "memory");
; }
; template <int MAP, bool FP8 = false>
; __device__ __forceinline__ void p0_matrix(const Frame& F, const float* W, int K, int N, f16_t* WT, const float* gain, int& base, int gw, int NGW, LAS float* scr) {
;     ...
;     for (int it = first; it < items; it += NGW) {
;         const int kb = it / nblk, nb = it % nblk, n0 = 32 * nb;
;         const int d0 = (MAP == 0) ? map_ident(n0) : (MAP == 1) ? map_heads(n0) : map_up(n0);
;         p0_transpose_item<FP8>(W, K, N, WT, gain, scr, 64 * kb, n0, d0, F.lane);
.LBB0_270:
	s_ashr_i32 s0, s2, 31
	s_lshr_b32 s0, s0, 27
	s_add_i32 s0, s2, s0
	s_ashr_i32 s1, s0, 5
	s_lshl_b32 s0, s1, 6
	s_lshl_b32 s6, s1, 10
	v_or_b32_e32 v24, s0, v6
	s_sub_i32 s6, s4, s6
	v_or_b32_e32 v26, 8, v24
	v_or_b32_e32 v28, 16, v24
	v_or_b32_e32 v30, 24, v24
	v_or_b32_e32 v32, 32, v24
	v_or_b32_e32 v34, 40, v24
	v_or_b32_e32 v36, 48, v24
	v_or_b32_e32 v38, 56, v24
	s_ashr_i32 s7, s6, 31
	v_ashrrev_i32_e32 v25, 31, v24
	v_ashrrev_i32_e32 v27, 31, v26
	v_ashrrev_i32_e32 v29, 31, v28
	v_ashrrev_i32_e32 v31, 31, v30
	v_ashrrev_i32_e32 v33, 31, v32
	v_ashrrev_i32_e32 v35, 31, v34
	v_ashrrev_i32_e32 v37, 31, v36
	v_ashrrev_i32_e32 v39, 31, v38
	v_lshl_add_u64 v[40:41], s[6:7], 2, v[2:3]
	v_lshlrev_b64 v[24:25], 12, v[24:25]
	v_lshlrev_b64 v[42:43], 12, v[26:27]
	v_lshlrev_b64 v[28:29], 12, v[28:29]
	v_lshlrev_b64 v[30:31], 12, v[30:31]
	v_lshlrev_b64 v[32:33], 12, v[32:33]
	v_lshlrev_b64 v[34:35], 12, v[34:35]
	v_lshlrev_b64 v[36:37], 12, v[36:37]
	v_lshlrev_b64 v[38:39], 12, v[38:39]
	v_lshl_add_u64 v[24:25], v[40:41], 0, v[24:25]
	v_lshl_add_u64 v[42:43], v[40:41], 0, v[42:43]
	v_lshl_add_u64 v[44:45], v[40:41], 0, v[28:29]
	v_lshl_add_u64 v[46:47], v[40:41], 0, v[30:31]
	v_lshl_add_u64 v[48:49], v[40:41], 0, v[32:33]
	v_lshl_add_u64 v[50:51], v[40:41], 0, v[34:35]
	v_lshl_add_u64 v[52:53], v[40:41], 0, v[36:37]
	v_lshl_add_u64 v[54:55], v[40:41], 0, v[38:39]
	global_load_dwordx4 v[24:27], v[24:25], off nt
	s_nop 0
	global_load_dwordx4 v[28:31], v[42:43], off nt
	global_load_dwordx4 v[32:35], v[44:45], off nt
	global_load_dwordx4 v[36:39], v[46:47], off nt
	s_nop 0
	global_load_dwordx4 v[40:43], v[48:49], off nt
	global_load_dwordx4 v[44:47], v[50:51], off nt
	s_nop 0
	global_load_dwordx4 v[48:51], v[52:53], off nt
	s_nop 0
	global_load_dwordx4 v[52:55], v[54:55], off nt
	s_mul_i32 s6, s1, 0xffa80000
	v_add_u32_e32 v56, s6, v7
	s_ashr_i32 s1, s0, 31
	v_add_u32_e32 v60, 0xb000, v56
	v_add_u32_e32 v62, 0x16000, v56
	v_add_u32_e32 v64, 0x21000, v56
	v_lshl_add_u64 v[58:59], s[0:1], 1, v[4:5]
	v_ashrrev_i32_e32 v57, 31, v56
	v_ashrrev_i32_e32 v61, 31, v60
	v_ashrrev_i32_e32 v63, 31, v62
	v_ashrrev_i32_e32 v65, 31, v64
	v_lshl_add_u64 v[56:57], v[58:59], 0, v[56:57]
	v_lshl_add_u64 v[60:61], v[58:59], 0, v[60:61]
	v_lshl_add_u64 v[62:63], v[58:59], 0, v[62:63]
	v_lshl_add_u64 v[58:59], v[58:59], 0, v[64:65]
	s_add_i32 s2, s2, s18
	s_add_i32 s4, s4, s5
	s_cmpk_lt_i32 s2, 0x580
	v_add_u32_e32 v7, s3, v7
	s_waitcnt vmcnt(7)
	ds_write2_b32 v8, v24, v25 offset1:1
	ds_write2_b32 v8, v26, v27 offset0:2 offset1:3
	s_waitcnt vmcnt(6)
	ds_write2_b32 v9, v28, v29 offset1:1
	ds_write2_b32 v10, v30, v31 offset1:1
	s_waitcnt vmcnt(5)
	ds_write2_b32 v11, v32, v33 offset1:1
	ds_write2_b32 v12, v34, v35 offset1:1
	s_waitcnt vmcnt(4)
	ds_write2_b32 v13, v36, v37 offset1:1
	ds_write2_b32 v14, v38, v39 offset1:1
	s_waitcnt vmcnt(3)
	ds_write2_b32 v15, v40, v41 offset1:1
	ds_write2_b32 v16, v42, v43 offset1:1
	s_waitcnt vmcnt(2)
	ds_write2_b32 v17, v44, v45 offset1:1
	ds_write2_b32 v18, v46, v47 offset1:1
	s_waitcnt vmcnt(1)
	ds_write2_b32 v19, v48, v49 offset1:1
	ds_write2_b32 v20, v50, v51 offset1:1
	s_waitcnt vmcnt(0)
	ds_write2_b32 v21, v52, v53 offset1:1
	ds_write2_b32 v22, v54, v55 offset1:1
	s_waitcnt lgkmcnt(0)
	ds_read2_b32 v[28:29], v1 offset0:33 offset1:41
	ds_read2_b32 v[30:31], v1 offset1:8
	ds_read2_b32 v[32:33], v1 offset0:66 offset1:74
	ds_read2_b32 v[34:35], v1 offset0:99 offset1:107
	ds_read2_b32 v[36:37], v1 offset0:132 offset1:140
	ds_read2_b32 v[38:39], v1 offset0:165 offset1:173
	ds_read2_b32 v[40:41], v1 offset0:198 offset1:206
	ds_read2_b32 v[42:43], v1 offset0:231 offset1:239
	ds_read2_b32 v[44:45], v1 offset0:49 offset1:57
	ds_read2_b32 v[46:47], v1 offset0:16 offset1:24
	ds_read2_b32 v[48:49], v1 offset0:82 offset1:90
	ds_read2_b32 v[50:51], v1 offset0:115 offset1:123
	ds_read2_b32 v[52:53], v1 offset0:148 offset1:156
	ds_read2_b32 v[54:55], v1 offset0:181 offset1:189
	ds_read2_b32 v[64:65], v1 offset0:214 offset1:222
	ds_read2_b32 v[66:67], v1 offset0:247 offset1:255
	s_waitcnt lgkmcnt(14)
	v_cvt_pk_f16_f32 v24, v30, v28
	s_waitcnt lgkmcnt(12)
	v_cvt_pk_f16_f32 v25, v32, v34
	s_waitcnt lgkmcnt(10)
	v_cvt_pk_f16_f32 v26, v36, v38
	s_waitcnt lgkmcnt(8)
	v_cvt_pk_f16_f32 v27, v40, v42
	v_cvt_pk_f16_f32 v28, v31, v29
	v_cvt_pk_f16_f32 v29, v33, v35
	v_cvt_pk_f16_f32 v30, v37, v39
	v_cvt_pk_f16_f32 v31, v41, v43
	s_waitcnt lgkmcnt(6)
	v_cvt_pk_f16_f32 v32, v46, v44
	s_waitcnt lgkmcnt(4)
	v_cvt_pk_f16_f32 v33, v48, v50
	s_waitcnt lgkmcnt(2)
	v_cvt_pk_f16_f32 v34, v52, v54
	s_waitcnt lgkmcnt(0)
	v_cvt_pk_f16_f32 v35, v64, v66
	v_cvt_pk_f16_f32 v36, v47, v45
	v_cvt_pk_f16_f32 v37, v49, v51
	v_cvt_pk_f16_f32 v38, v53, v55
	v_cvt_pk_f16_f32 v39, v65, v67
	global_store_dwordx4 v[56:57], v[24:27], off sc1
	global_store_dwordx4 v[60:61], v[28:31], off sc1
	global_store_dwordx4 v[62:63], v[32:35], off sc1
	global_store_dwordx4 v[58:59], v[36:39], off sc1
	s_waitcnt lgkmcnt(0)
	s_cbranch_scc1 .LBB0_270

; #define LAS __attribute__((address_space(3)))
; __device__ __forceinline__ unsigned pkh(float lo, float hi) { f32x2 v = {lo, hi}; h16x2 h = __builtin_convertvector(v, h16x2); return __builtin_bit_cast(unsigned, h); }
; __device__ __forceinline__ h16x4 vtr(LAS const unsigned char* p) { return __builtin_bit_cast(h16x4, __builtin_amdgcn_ds_read_tr16_b64_v4i16((LAS v4i16_t*)p)); }
; __device__ __forceinline__ h16x8 cat8(h16x4 lo, h16x4 hi) { return (h16x8){lo[0], lo[1], lo[2], lo[3], hi[0], hi[1], hi[2], hi[3]}; }
; __device__ __forceinline__ int pair16_dim(int G, int dt0) { return (G & 1) ? 16 * (dt0 + 1) + 4 * (G - 1) : 16 * dt0 + 4 * G; }
; __device__ __forceinline__ float wave_max(float v) {
; #pragma unroll
;     for (int o = 1; o < 64; o <<= 1) v = fmaxf(v, __shfl_xor(v, o));
;     return v;
; template <bool DO_SGU, bool DO_X>
; __device__ __forceinline__ void mixer_a(const Frame& F, const Args& a) {
;     ...
;             for (int ks = 0; ks < nsteps; ++ks) {
;                 const h16x8 bf = *(LAS const h16x8*)(Wimg + (16 * w + fr) * 256 + (((4 * ks + G) ^ fr) << 4));
;                 LAS const unsigned char* v0 = Vimg + (32 * ks + 8 * G + qq) * 256 + p * 8;
; #pragma unroll
;                 for (int dt = 0; dt < 8; ++dt) {
;                     const h16x4 lo = vtr(v0 + ((dt ^ qq) << 5)), hi = vtr(v0 + 4 * 256 + ((dt ^ (4 + qq)) << 5));
;                     acc[dt] = __builtin_amdgcn_mfma_f32_16x16x32_f16(cat8(lo, hi), bf, acc[dt], 0, 0, 0);
;                 }
;             }
;             const float bias = bsp[g * CHUNK + t];
; #pragma unroll
;             for (int pr = 0; pr < 4; ++pr) { const int dt0 = 2 * pr, col = g * 128 + pair16_dim(G, dt0);
;                 u32x2 xa, xb; xa.x = pkh(acc[dt0][0] + bias, acc[dt0][1] + bias); xa.y = pkh(acc[dt0][2] + bias, acc[dt0][3] + bias);
;                 xb.x = pkh(acc[dt0 + 1][0] + bias, acc[dt0 + 1][1] + bias); xb.y = pkh(acc[dt0 + 1][2] + bias, acc[dt0 + 1][3] + bias);
;                 const h16x8 m8 = __builtin_bit_cast(h16x8, pair16(xa, xb));
;                 *(h16x8*)(Y + (size_t)row * DM + col) = ur[pr] * m8; }
;         }
;         __syncthreads();
;         if (DO_X) xattn_chunk<false>(F, a, chunk, P, NA, 2 * MIXW, a.in[16], Y);
.LBB0_331:
	v_xor_b32_e32 v44, v43, v1
	v_add_u32_e32 v48, v41, v122
	v_add_u32_e32 v49, v40, v122
	v_add_u32_e32 v80, v39, v122
	v_lshl_add_u32 v162, v44, 4, v42
	ds_read_b64_tr_b16 v[44:45], v48 offset:32768
	ds_read_b64_tr_b16 v[46:47], v48 offset:33920
	ds_read_b64_tr_b16 v[156:157], v49 offset:32768
	ds_read_b64_tr_b16 v[158:159], v49 offset:33920
	ds_read_b64_tr_b16 v[160:161], v80 offset:32768
	ds_read_b64_tr_b16 v[164:165], v48 offset:32896
	ds_read_b64_tr_b16 v[166:167], v48 offset:33792
	ds_read_b128 v[168:171], v162
	s_waitcnt lgkmcnt(0)
	v_mfma_f32_16x16x32_f16 v[50:53], v[44:47], v[168:171], v[50:53]
	ds_read_b64_tr_b16 v[162:163], v80 offset:33920
	ds_read_b64_tr_b16 v[44:45], v49 offset:32896
	ds_read_b64_tr_b16 v[46:47], v49 offset:33792
	v_add_u32_e32 v155, v38, v122
	s_add_i32 s4, s4, -1
	v_mfma_f32_16x16x32_f16 v[54:57], v[156:159], v[168:171], v[54:57]
	ds_read_b64_tr_b16 v[156:157], v155 offset:32768
	ds_read_b64_tr_b16 v[172:173], v80 offset:32896
	ds_read_b64_tr_b16 v[174:175], v80 offset:33792
	v_add_u32_e32 v38, 0x2000, v38
	v_add_u32_e32 v39, 0x2000, v39
	s_waitcnt lgkmcnt(5)
	v_mfma_f32_16x16x32_f16 v[58:61], v[160:163], v[168:171], v[58:61]
	ds_read_b64_tr_b16 v[158:159], v155 offset:33920
	ds_read_b64_tr_b16 v[160:161], v155 offset:32896
	ds_read_b64_tr_b16 v[162:163], v155 offset:33792
	v_add_u32_e32 v40, 0x2000, v40
	v_add_u32_e32 v41, 0x2000, v41
	s_waitcnt lgkmcnt(2)
	v_mfma_f32_16x16x32_f16 v[62:65], v[156:159], v[168:171], v[62:65]
	s_cmp_eq_u32 s4, 0
	v_add_u32_e32 v43, 4, v43
	v_mfma_f32_16x16x32_f16 v[66:69], v[164:167], v[168:171], v[66:69]
	v_mfma_f32_16x16x32_f16 v[70:73], v[44:47], v[168:171], v[70:73]
	v_mfma_f32_16x16x32_f16 v[74:77], v[172:175], v[168:171], v[74:77]
	s_waitcnt lgkmcnt(0)
	v_mfma_f32_16x16x32_f16 v[34:37], v[160:163], v[168:171], v[34:37]
	s_cbranch_scc0 .LBB0_331
	v_add_u32_e32 v80, s14, v120
	v_lshl_add_u64 v[38:39], v[80:81], 2, s[56:57]
	global_load_dword v156, v[38:39], off
	s_waitcnt vmcnt(4)
	v_mov_b64_e32 v[40:41], v[24:25]
	s_waitcnt vmcnt(3)
	v_mov_b64_e32 v[44:45], v[28:29]
	s_waitcnt vmcnt(2)
	v_mov_b64_e32 v[48:49], v[32:33]
	v_mov_b64_e32 v[38:39], v[22:23]
	v_mov_b64_e32 v[42:43], v[26:27]
	v_mov_b64_e32 v[46:47], v[30:31]
	v_or_b32_e32 v80, s14, v82
	s_xor_b64 s[2:3], s[2:3], -1
	v_lshlrev_b32_e32 v80, 1, v80
	s_cmp_eq_u32 s19, 6
	v_lshl_add_u64 v[22:23], v[116:117], 0, v[80:81]
	s_waitcnt vmcnt(0)
	v_pk_add_f32 v[24:25], v[50:51], v[156:157] op_sel_hi:[1,0]
	v_pk_add_f32 v[26:27], v[52:53], v[156:157] op_sel_hi:[1,0]
	v_pk_add_f32 v[28:29], v[54:55], v[156:157] op_sel_hi:[1,0]
	v_pk_add_f32 v[30:31], v[56:57], v[156:157] op_sel_hi:[1,0]
	v_pk_add_f32 v[52:53], v[62:63], v[156:157] op_sel_hi:[1,0]
	v_pk_add_f32 v[54:55], v[64:65], v[156:157] op_sel_hi:[1,0]
	v_pk_add_f32 v[56:57], v[66:67], v[156:157] op_sel_hi:[1,0]
	v_pk_add_f32 v[64:65], v[74:75], v[156:157] op_sel_hi:[1,0]
	v_pk_add_f32 v[66:67], v[76:77], v[156:157] op_sel_hi:[1,0]
	v_pk_add_f32 v[34:35], v[34:35], v[156:157] op_sel_hi:[1,0]
	v_pk_add_f32 v[36:37], v[36:37], v[156:157] op_sel_hi:[1,0]
	v_cvt_pk_f16_f32 v24, v24, v25
	v_cvt_pk_f16_f32 v25, v26, v27
	v_cvt_pk_f16_f32 v27, v30, v31
	v_cvt_pk_f16_f32 v30, v52, v53
	v_cvt_pk_f16_f32 v52, v64, v65
	v_cvt_pk_f16_f32 v53, v66, v67
	v_cvt_pk_f16_f32 v34, v34, v35
	v_cvt_pk_f16_f32 v35, v36, v37
	v_pk_add_f32 v[32:33], v[58:59], v[156:157] op_sel_hi:[1,0]
	v_pk_add_f32 v[50:51], v[60:61], v[156:157] op_sel_hi:[1,0]
	v_pk_add_f32 v[58:59], v[68:69], v[156:157] op_sel_hi:[1,0]
	v_pk_add_f32 v[60:61], v[70:71], v[156:157] op_sel_hi:[1,0]
	v_pk_add_f32 v[62:63], v[72:73], v[156:157] op_sel_hi:[1,0]
	v_cvt_pk_f16_f32 v26, v28, v29
	v_permlane16_swap_b32_e32 v52, v34
	v_permlane16_swap_b32_e32 v53, v35
	v_cvt_pk_f16_f32 v28, v32, v33
	v_cvt_pk_f16_f32 v29, v50, v51
	v_cvt_pk_f16_f32 v31, v54, v55
	v_cvt_pk_f16_f32 v32, v56, v57
	v_cvt_pk_f16_f32 v33, v58, v59
	v_cvt_pk_f16_f32 v50, v60, v61
	v_cvt_pk_f16_f32 v51, v62, v63
	v_permlane16_swap_b32_e32 v24, v26
	v_permlane16_swap_b32_e32 v25, v27
	v_pk_mul_f16 v5, v5, v35
	v_pk_mul_f16 v4, v4, v34
	v_mov_b64_e32 v[36:37], v[20:21]
	v_permlane16_swap_b32_e32 v28, v30
	v_permlane16_swap_b32_e32 v29, v31
	v_permlane16_swap_b32_e32 v32, v50
	v_permlane16_swap_b32_e32 v33, v51
	v_pk_mul_f16 v17, v17, v27
	v_pk_mul_f16 v15, v15, v25
	v_pk_mul_f16 v16, v16, v26
	v_pk_mul_f16 v14, v14, v24
	v_mov_b64_e32 v[34:35], v[18:19]
	v_pk_mul_f16 v13, v13, v31
	v_pk_mul_f16 v11, v11, v29
	v_pk_mul_f16 v12, v12, v30
	v_pk_mul_f16 v10, v10, v28
	v_pk_mul_f16 v9, v9, v51
	v_pk_mul_f16 v7, v7, v33
	v_pk_mul_f16 v8, v8, v50
	v_pk_mul_f16 v6, v6, v32
	v_pk_mul_f16 v3, v3, v53
	v_pk_mul_f16 v2, v2, v52
	global_store_dwordx4 v[22:23], v[14:17], off sc1
	global_store_dwordx4 v[22:23], v[10:13], off offset:64 sc1
	global_store_dwordx4 v[22:23], v[6:9], off offset:128 sc1
	global_store_dwordx4 v[22:23], v[2:5], off offset:192 sc1
	s_cbranch_scc0 .LBB0_326
	s_barrier
	global_load_dword v5, v[88:89], off
	v_and_b32_e32 v3, 64, v154
	v_xor_b32_e32 v6, 1, v154
	v_add_u32_e32 v12, 64, v3
	v_cmp_lt_i32_e32 vcc, v6, v12
	v_xor_b32_e32 v7, 2, v154
	v_xor_b32_e32 v8, 4, v154
	v_cndmask_b32_e32 v6, v154, v6, vcc
	v_lshlrev_b32_e32 v6, 2, v6
	v_cmp_lt_i32_e32 vcc, v7, v12
	v_xor_b32_e32 v9, 8, v154
	v_xor_b32_e32 v10, 16, v154
	v_cndmask_b32_e32 v7, v154, v7, vcc
	v_lshlrev_b32_e32 v7, 2, v7
	v_cmp_lt_i32_e32 vcc, v8, v12
	v_xor_b32_e32 v11, 32, v154
	s_ashr_i32 s2, s42, 31
	v_or_b32_e32 v2, s18, v140
	s_lshr_b32 s4, s2, 25
	v_or_b32_e32 v4, 16, v2
	v_ashrrev_i32_e32 v3, 31, v2
	v_mad_i64_i32 v[30:31], s[2:3], v2, s39, v[98:99]
	s_add_i32 s4, s42, s4
	v_mad_i64_i32 v[32:33], s[2:3], v4, s39, v[98:99]
	v_lshlrev_b64 v[34:35], 11, v[2:3]
	s_ashr_i32 s2, s4, 7
	s_mov_b32 s14, 0
	s_lshl_b32 s43, s2, 2
	s_mov_b64 s[18:19], -1
	s_waitcnt vmcnt(0)
	v_and_b32_e32 v13, 0x7fffffff, v5
	ds_bpermute_b32 v6, v6, v13
	v_max_f32_e64 v5, |v5|, |v5|
	s_waitcnt lgkmcnt(0)
	v_max_f32_e32 v6, v6, v6
	v_max_f32_e32 v5, v5, v6
	ds_bpermute_b32 v6, v7, v5
	v_cndmask_b32_e32 v7, v154, v8, vcc
	v_lshlrev_b32_e32 v7, 2, v7
	v_cmp_lt_i32_e32 vcc, v9, v12
	s_waitcnt lgkmcnt(0)
	v_max_f32_e32 v6, v6, v6
	v_max_f32_e32 v5, v5, v6
	ds_bpermute_b32 v6, v7, v5
	v_cndmask_b32_e32 v7, v154, v9, vcc
	v_lshlrev_b32_e32 v7, 2, v7
	v_cmp_lt_i32_e32 vcc, v10, v12
	s_waitcnt lgkmcnt(0)
	v_max_f32_e32 v6, v6, v6
	v_max_f32_e32 v5, v5, v6
	ds_bpermute_b32 v6, v7, v5
	v_cndmask_b32_e32 v7, v154, v10, vcc
	v_lshlrev_b32_e32 v40, 2, v7
	v_cmp_lt_i32_e32 vcc, v11, v12
	s_waitcnt lgkmcnt(0)
	v_max_f32_e32 v6, v6, v6
	v_max_f32_e32 v6, v5, v6
	ds_bpermute_b32 v7, v40, v6
	v_cndmask_b32_e32 v8, v154, v11, vcc
	v_lshlrev_b32_e32 v41, 2, v8
	v_ashrrev_i32_e32 v5, 31, v4
	v_lshlrev_b64 v[36:37], 11, v[4:5]
	s_waitcnt lgkmcnt(0)
	v_max_f32_e32 v7, v7, v7
	v_max_f32_e32 v6, v6, v7
	ds_bpermute_b32 v7, v41, v6
	s_waitcnt lgkmcnt(0)
	v_max_f32_e32 v2, v7, v7
	v_max_f32_e32 v42, v6, v2
; #define LAS __attribute__((address_space(3)))
; __device__ __forceinline__ void dma_kv_imgs(LAS unsigned char* Kimg, LAS unsigned char* Vimg, const f16_t* ksrc, const f16_t* vsrc, int wave, int lane, int pitch = NB) {
;     const int rl = lane >> 3, pos = lane & 7;
;     const int kc = pos ^ rl, vc = 2 * ((pos >> 1) ^ ((lane >> 4) & 3)) + (pos & 1);
;     const unsigned kd = (unsigned)__builtin_amdgcn_readfirstlane((int)(unsigned)(uintptr_t)Kimg), vd = (unsigned)__builtin_amdgcn_readfirstlane((int)(unsigned)(uintptr_t)Vimg);
; #pragma unroll
;     for (int i = 0; i < 4; ++i) { const int pc = wave + 8 * i, row = 8 * pc + rl;
;         glds16_asm(ksrc + (size_t)row * pitch + 8 * kc, (unsigned)__builtin_amdgcn_readfirstlane((int)(kd + pc * 1024)));
;         glds16_asm(vsrc + (size_t)row * pitch + 8 * vc, (unsigned)__builtin_amdgcn_readfirstlane((int)(vd + pc * 1024))); }
; __device__ __forceinline__ void xattn_load_q(const f16_t* qp  , const float* gqm, int G, float maxgk, h16x8& q0, h16x8& q1, float& mb) {
;     const h16x8 r0v = *(const h16x8*)qp, r1v = *(const h16x8*)(qp + 32);
;     float q[16], ss = 0.f;
; #pragma unroll
;     for (int j = 0; j < 8; ++j) { q[j] = (float)r0v[j]; q[8 + j] = (float)r1v[j]; ss += q[j] * q[j] + q[8 + j] * q[8 + j]; }
;     ss += __shfl_xor(ss, 16); ss += __shfl_xor(ss, 32);
.LBB0_334:
	s_lshl_b32 s2, s14, 1
	s_or_b32 s2, s2, s43
	s_ashr_i32 s3, s2, 31
	s_lshl_b64 s[4:5], s[2:3], 15
	v_lshl_add_u64 v[2:3], v[90:91], 0, s[4:5]
	s_add_i32 s3, s20, 0
	v_lshl_add_u64 v[4:5], v[92:93], 0, s[4:5]
	v_lshl_add_u64 v[6:7], v[2:3], 0, v[100:101]
	s_mov_b32 s4, m0
	s_mov_b32 m0, s3
	s_nop 0
	global_load_lds_dwordx4 v[6:7], off
	s_mov_b32 m0, s4
	s_add_i32 s3, s20, s40
	v_lshl_add_u64 v[6:7], v[4:5], 0, v[100:101]
	s_mov_b32 s4, m0
	s_mov_b32 m0, s3
	s_nop 0
	global_load_lds_dwordx4 v[6:7], off
	s_mov_b32 m0, s4
	s_add_i32 s3, s34, 0
	v_lshl_add_u64 v[6:7], v[2:3], 0, v[102:103]
	s_mov_b32 s4, m0
	s_mov_b32 m0, s3
	s_nop 0
	global_load_lds_dwordx4 v[6:7], off
	s_mov_b32 m0, s4
	s_add_i32 s3, s34, s40
	v_lshl_add_u64 v[6:7], v[4:5], 0, v[102:103]
	s_mov_b32 s4, m0
	s_mov_b32 m0, s3
	s_nop 0
	global_load_lds_dwordx4 v[6:7], off
	s_mov_b32 m0, s4
	s_add_i32 s3, s35, 0
	v_lshl_add_u64 v[6:7], v[2:3], 0, v[104:105]
	s_mov_b32 s4, m0
	s_mov_b32 m0, s3
	s_nop 0
	global_load_lds_dwordx4 v[6:7], off
	s_mov_b32 m0, s4
	s_add_i32 s3, s35, s40
	v_lshl_add_u64 v[6:7], v[4:5], 0, v[104:105]
	s_mov_b32 s4, m0
	s_mov_b32 m0, s3
	s_nop 0
	global_load_lds_dwordx4 v[6:7], off
	s_mov_b32 m0, s4
	s_add_i32 s3, s36, 0
	v_lshl_add_u64 v[2:3], v[2:3], 0, v[106:107]
	s_mov_b32 s4, m0
	s_mov_b32 m0, s3
	s_nop 0
	global_load_lds_dwordx4 v[2:3], off
	s_mov_b32 m0, s4
	s_add_i32 s3, s36, s40
	s_or_b32 s2, s2, 1
	v_lshl_add_u64 v[2:3], v[4:5], 0, v[106:107]
	s_mov_b32 s4, m0
	s_mov_b32 m0, s3
	s_nop 0
	global_load_lds_dwordx4 v[2:3], off
	s_mov_b32 m0, s4
	s_ashr_i32 s3, s2, 31
	s_lshl_b64 s[2:3], s[2:3], 15
	v_lshl_add_u64 v[2:3], v[90:91], 0, s[2:3]
	v_lshl_add_u64 v[4:5], v[92:93], 0, s[2:3]
	s_add_i32 s2, 0, 0x10000
	v_lshl_add_u64 v[6:7], v[2:3], 0, v[100:101]
	s_add_i32 s3, s20, s2
	s_mov_b32 s4, m0
	s_mov_b32 m0, s3
	s_nop 0
	global_load_lds_dwordx4 v[6:7], off
	s_mov_b32 m0, s4
	v_lshl_add_u64 v[6:7], v[4:5], 0, v[100:101]
	s_add_i32 s3, s20, s41
	s_mov_b32 s4, m0
	s_mov_b32 m0, s3
	s_nop 0
	global_load_lds_dwordx4 v[6:7], off
	s_mov_b32 m0, s4
	v_lshl_add_u64 v[6:7], v[2:3], 0, v[102:103]
	s_add_i32 s3, s34, s2
	s_mov_b32 s4, m0
	s_mov_b32 m0, s3
	s_nop 0
	global_load_lds_dwordx4 v[6:7], off
	s_mov_b32 m0, s4
	v_lshl_add_u64 v[6:7], v[4:5], 0, v[102:103]
	s_add_i32 s3, s34, s41
	s_mov_b32 s4, m0
	s_mov_b32 m0, s3
	s_nop 0
	global_load_lds_dwordx4 v[6:7], off
	s_mov_b32 m0, s4
	v_lshl_add_u64 v[6:7], v[2:3], 0, v[104:105]
	s_add_i32 s3, s35, s2
	s_mov_b32 s4, m0
	s_mov_b32 m0, s3
	s_nop 0
	global_load_lds_dwordx4 v[6:7], off
	s_mov_b32 m0, s4
	v_lshl_add_u64 v[6:7], v[4:5], 0, v[104:105]
	s_add_i32 s3, s35, s41
	s_mov_b32 s4, m0
	s_mov_b32 m0, s3
	s_nop 0
	global_load_lds_dwordx4 v[6:7], off
	s_mov_b32 m0, s4
	s_add_i32 s2, s36, s2
	v_lshl_add_u64 v[2:3], v[2:3], 0, v[106:107]
	s_mov_b32 s3, m0
	s_mov_b32 m0, s2
	s_nop 0
	global_load_lds_dwordx4 v[2:3], off
	s_mov_b32 m0, s3
	s_add_i32 s2, s36, s41
	v_lshl_add_u64 v[2:3], v[4:5], 0, v[106:107]
	s_mov_b32 s3, m0
	s_mov_b32 m0, s2
	s_nop 0
	global_load_lds_dwordx4 v[2:3], off
	s_mov_b32 m0, s3
	s_lshl_b32 s2, s14, 7
	s_add_i32 s2, s2, s31
	s_lshl_b32 s14, s2, 1
	v_lshl_add_u64 v[10:11], v[30:31], 0, s[14:15]
	global_load_dwordx4 v[2:5], v[10:11], off offset:3136
	v_lshl_add_u64 v[12:13], v[32:33], 0, s[14:15]
	global_load_dwordx4 v[6:9], v[12:13], off offset:3136
	global_load_dwordx4 v[44:47], v[10:11], off offset:3072
	global_load_dwordx4 v[48:51], v[12:13], off offset:3072
	s_nop 0
	global_load_dwordx4 v[10:13], v[94:95], off offset:144
	global_load_dwordx4 v[14:17], v[94:95], off offset:128
	global_load_dwordx4 v[18:21], v[94:95], off offset:16
	global_load_dwordx4 v[22:25], v[94:95], off
	s_waitcnt vmcnt(0)
	s_barrier
	s_waitcnt vmcnt(6)
	v_cvt_f32_f16_e32 v26, v9
	v_cvt_f32_f16_sdwa v27, v9 dst_sel:DWORD dst_unused:UNUSED_PAD src0_sel:WORD_1
	v_cvt_f32_f16_e32 v28, v8
	v_cvt_f32_f16_sdwa v29, v8 dst_sel:DWORD dst_unused:UNUSED_PAD src0_sel:WORD_1
	v_cvt_f32_f16_e32 v56, v2
	v_cvt_f32_f16_sdwa v57, v2 dst_sel:DWORD dst_unused:UNUSED_PAD src0_sel:WORD_1
	v_cvt_f32_f16_e32 v8, v3
	v_cvt_f32_f16_sdwa v9, v3 dst_sel:DWORD dst_unused:UNUSED_PAD src0_sel:WORD_1
	s_waitcnt vmcnt(5)
	v_cvt_f32_f16_e32 v64, v44
	v_cvt_f32_f16_sdwa v65, v44 dst_sel:DWORD dst_unused:UNUSED_PAD src0_sel:WORD_1
	v_cvt_f32_f16_e32 v60, v47
	v_cvt_f32_f16_sdwa v61, v47 dst_sel:DWORD dst_unused:UNUSED_PAD src0_sel:WORD_1
	v_cvt_f32_f16_e32 v62, v46
	v_cvt_f32_f16_sdwa v63, v46 dst_sel:DWORD dst_unused:UNUSED_PAD src0_sel:WORD_1
	v_cvt_f32_f16_e32 v46, v45
	v_cvt_f32_f16_sdwa v47, v45 dst_sel:DWORD dst_unused:UNUSED_PAD src0_sel:WORD_1
	v_cvt_f32_f16_e32 v54, v4
	v_cvt_f32_f16_sdwa v55, v4 dst_sel:DWORD dst_unused:UNUSED_PAD src0_sel:WORD_1
	v_pk_mul_f32 v[2:3], v[56:57], v[56:57]
	v_cvt_f32_f16_e32 v52, v5
	v_cvt_f32_f16_sdwa v53, v5 dst_sel:DWORD dst_unused:UNUSED_PAD src0_sel:WORD_1
	v_pk_mul_f32 v[66:67], v[8:9], v[8:9]
	v_pk_fma_f32 v[2:3], v[64:65], v[64:65], v[2:3]
	v_pk_fma_f32 v[66:67], v[46:47], v[46:47], v[66:67]
	v_add_f32_e32 v2, v2, v3
	v_pk_mul_f32 v[44:45], v[54:55], v[54:55]
	v_add_f32_e32 v2, v66, v2
	v_pk_fma_f32 v[44:45], v[62:63], v[62:63], v[44:45]
	v_add_f32_e32 v2, v67, v2
	v_pk_mul_f32 v[4:5], v[52:53], v[52:53]
	v_add_f32_e32 v2, v44, v2
	v_pk_fma_f32 v[4:5], v[60:61], v[60:61], v[4:5]
	v_add_f32_e32 v2, v45, v2
	v_add_f32_e32 v2, v4, v2
	v_add_f32_e32 v2, v5, v2
	ds_bpermute_b32 v3, v40, v2
	s_waitcnt vmcnt(4)
	v_cvt_f32_f16_e32 v44, v51
	v_cvt_f32_f16_sdwa v45, v51 dst_sel:DWORD dst_unused:UNUSED_PAD src0_sel:WORD_1
	v_cvt_f32_f16_e32 v66, v50
	v_cvt_f32_f16_sdwa v67, v50 dst_sel:DWORD dst_unused:UNUSED_PAD src0_sel:WORD_1
	s_waitcnt lgkmcnt(0)
; __device__ __forceinline__ unsigned pkh(float lo, float hi) { f32x2 v = {lo, hi}; h16x2 h = __builtin_convertvector(v, h16x2); return __builtin_bit_cast(unsigned, h); }
; __device__ __forceinline__ void xattn_load_q(const f16_t* qp  , const float* gqm, int G, float maxgk, h16x8& q0, h16x8& q1, float& mb) {
;     ...
;     for (int j = 0; j < 8; ++j) { q[j] = (float)r0v[j]; q[8 + j] = (float)r1v[j]; ss += q[j] * q[j] + q[8 + j] * q[8 + j]; }
;     ss += __shfl_xor(ss, 16); ss += __shfl_xor(ss, 32);
;     const float rn = 1.0f / sqrtf(ss * (1.0f / HD) + EPS);
;     float n2 = 0.f;
; #pragma unroll
;     for (int j = 0; j < 8; ++j) { q[j] *= rn * gqm[8 * G + j]; q[8 + j] *= rn * gqm[32 + 8 * G + j]; n2 += q[j] * q[j] + q[8 + j] * q[8 + j]; }
;     n2 += __shfl_xor(n2, 16); n2 += __shfl_xor(n2, 32);
;     mb = (sqrtf(n2) * maxgk - BOUND_SHIFT) * LOG2E;
;     const float c = 0.125f * LOG2E;
;     u32x4 w0, w1;
;     w0.x = pkh(q[0] * c, q[1] * c); w0.y = pkh(q[2] * c, q[3] * c); w0.z = pkh(q[4] * c, q[5] * c); w0.w = pkh(q[6] * c, q[7] * c);
;     w1.x = pkh(q[8] * c, q[9] * c); w1.y = pkh(q[10] * c, q[11] * c); w1.z = pkh(q[12] * c, q[13] * c); w1.w = pkh(q[14] * c, q[15] * c);
;     q0 = __builtin_bit_cast(h16x8, w0); q1 = __builtin_bit_cast(h16x8, w1);
	v_add_f32_e32 v2, v2, v3
	ds_bpermute_b32 v3, v41, v2
	v_cvt_f32_f16_e32 v50, v49
	v_cvt_f32_f16_sdwa v51, v49 dst_sel:DWORD dst_unused:UNUSED_PAD src0_sel:WORD_1
	v_cvt_f32_f16_e32 v38, v7
	v_cvt_f32_f16_sdwa v39, v7 dst_sel:DWORD dst_unused:UNUSED_PAD src0_sel:WORD_1
	s_waitcnt lgkmcnt(0)
	v_add_f32_e32 v2, v2, v3
	v_fmamk_f32 v2, v2, 0x3c800000, v147
	v_mul_f32_e32 v3, 0x4f800000, v2
	v_cmp_gt_f32_e32 vcc, s38, v2
	v_pk_mul_f32 v[4:5], v[28:29], v[28:29]
	v_cvt_f32_f16_e32 v58, v6
	v_cndmask_b32_e32 v43, v2, v3, vcc
	v_sqrt_f32_e32 v49, v43
	v_pk_mul_f32 v[2:3], v[26:27], v[26:27]
	v_cvt_f32_f16_sdwa v59, v6 dst_sel:DWORD dst_unused:UNUSED_PAD src0_sel:WORD_1
	v_pk_fma_f32 v[68:69], v[44:45], v[44:45], v[2:3]
	v_add_u32_e32 v2, -1, v49
	v_add_u32_e32 v3, 1, v49
	v_fma_f32 v70, -v2, v49, v43
	v_fma_f32 v71, -v3, v49, v43
	v_cmp_ge_f32_e64 s[2:3], 0, v70
	v_pk_mul_f32 v[6:7], v[58:59], v[58:59]
	s_nop 0
	v_cndmask_b32_e64 v2, v49, v2, s[2:3]
	v_cmp_lt_f32_e64 s[2:3], 0, v71
	v_pk_fma_f32 v[70:71], v[66:67], v[66:67], v[4:5]
	s_nop 0
	v_cndmask_b32_e64 v2, v2, v3, s[2:3]
	v_mul_f32_e32 v3, 0x37800000, v2
	v_cndmask_b32_e32 v2, v2, v3, vcc
	v_cmp_class_f32_e32 vcc, v43, v148
	s_nop 1
	v_cndmask_b32_e32 v43, v2, v43, vcc
	v_div_scale_f32 v49, s[2:3], v43, v43, 1.0
	v_rcp_f32_e32 v74, v49
	v_pk_mul_f32 v[2:3], v[38:39], v[38:39]
	s_nop 0
	v_pk_fma_f32 v[72:73], v[50:51], v[50:51], v[2:3]
	v_fma_f32 v2, -v49, v74, 1.0
	v_fmac_f32_e32 v74, v2, v74
	v_div_scale_f32 v2, vcc, 1.0, v43, 1.0
	v_mul_f32_e32 v3, v2, v74
	v_fma_f32 v4, -v49, v3, v2
	v_fmac_f32_e32 v3, v4, v74
	v_fma_f32 v2, -v49, v3, v2
	v_div_fmas_f32 v2, v2, v74, v3
	v_div_fixup_f32 v74, v2, v43, 1.0
	s_waitcnt vmcnt(3)
	v_pk_mul_f32 v[2:3], v[12:13], v[74:75] op_sel_hi:[1,0]
	s_nop 0
	v_pk_mul_f32 v[52:53], v[2:3], v[52:53]
	s_nop 0
	v_pk_mul_f32 v[2:3], v[52:53], s[16:17] op_sel_hi:[1,0]
	s_nop 0
	v_cvt_pk_f16_f32 v5, v2, v3
	v_pk_mul_f32 v[2:3], v[10:11], v[74:75] op_sel_hi:[1,0]
	s_nop 0
	v_pk_mul_f32 v[54:55], v[2:3], v[54:55]
	s_nop 0
	v_pk_mul_f32 v[2:3], v[54:55], s[16:17] op_sel_hi:[1,0]
	s_nop 0
	v_cvt_pk_f16_f32 v4, v2, v3
	s_waitcnt vmcnt(2)
	v_pk_mul_f32 v[2:3], v[16:17], v[74:75] op_sel_hi:[1,0]
	s_nop 0
	v_pk_mul_f32 v[76:77], v[2:3], v[8:9]
	v_pk_mul_f32 v[8:9], v[14:15], v[74:75] op_sel_hi:[1,0]
	v_pk_mul_f32 v[2:3], v[76:77], s[16:17] op_sel_hi:[1,0]
	v_pk_mul_f32 v[56:57], v[8:9], v[56:57]
	v_cvt_pk_f16_f32 v3, v2, v3
	v_pk_mul_f32 v[8:9], v[56:57], s[16:17] op_sel_hi:[1,0]
	s_nop 0
	v_cvt_pk_f16_f32 v2, v8, v9
	s_waitcnt vmcnt(1)
	v_pk_mul_f32 v[8:9], v[20:21], v[74:75] op_sel_hi:[1,0]
	s_nop 0
	v_pk_mul_f32 v[60:61], v[8:9], v[60:61]
	s_nop 0
	v_pk_mul_f32 v[8:9], v[60:61], s[16:17] op_sel_hi:[1,0]
	v_pk_mul_f32 v[60:61], v[60:61], v[60:61]
	v_cvt_pk_f16_f32 v9, v8, v9
	v_pk_fma_f32 v[52:53], v[52:53], v[52:53], v[60:61]
	v_pk_mul_f32 v[60:61], v[18:19], v[74:75] op_sel_hi:[1,0]
	s_nop 0
	v_pk_mul_f32 v[60:61], v[60:61], v[62:63]
	s_nop 0
	v_pk_mul_f32 v[62:63], v[60:61], v[60:61]
	s_nop 0
	v_pk_fma_f32 v[54:55], v[54:55], v[54:55], v[62:63]
	s_waitcnt vmcnt(0)
	v_pk_mul_f32 v[62:63], v[24:25], v[74:75] op_sel_hi:[1,0]
	v_pk_mul_f32 v[74:75], v[22:23], v[74:75] op_sel_hi:[1,0]
	v_pk_mul_f32 v[46:47], v[62:63], v[46:47]
	s_nop 0
	v_pk_mul_f32 v[62:63], v[46:47], v[46:47]
	s_nop 0
	v_pk_fma_f32 v[62:63], v[76:77], v[76:77], v[62:63]
	v_cvt_f32_f16_e32 v76, v48
	v_cvt_f32_f16_sdwa v77, v48 dst_sel:DWORD dst_unused:UNUSED_PAD src0_sel:WORD_1
	v_pk_mul_f32 v[48:49], v[74:75], v[64:65]
	v_pk_fma_f32 v[6:7], v[76:77], v[76:77], v[6:7]
	v_pk_mul_f32 v[64:65], v[48:49], v[48:49]
	v_add_f32_e32 v6, v6, v7
	v_pk_fma_f32 v[56:57], v[56:57], v[56:57], v[64:65]
	v_add_f32_e32 v6, v72, v6
	v_add_f32_e32 v8, v56, v57
	v_add_f32_e32 v8, v62, v8
	v_add_f32_e32 v8, v63, v8
	v_add_f32_e32 v6, v73, v6
	v_add_f32_e32 v8, v54, v8
	v_add_f32_e32 v6, v70, v6
	v_add_f32_e32 v8, v55, v8
	v_add_f32_e32 v6, v71, v6
	v_add_f32_e32 v8, v52, v8
	v_add_f32_e32 v6, v68, v6
	v_add_f32_e32 v43, v53, v8
	v_add_f32_e32 v53, v69, v6
	ds_bpermute_b32 v54, v40, v53
	ds_bpermute_b32 v52, v40, v43
	v_pk_mul_f32 v[6:7], v[60:61], s[16:17] op_sel_hi:[1,0]
	s_waitcnt lgkmcnt(1)
	v_add_f32_e32 v53, v53, v54
	ds_bpermute_b32 v54, v41, v53
	v_cvt_pk_f16_f32 v8, v6, v7
	s_waitcnt lgkmcnt(1)
	v_add_f32_e32 v43, v43, v52
	v_pk_mul_f32 v[6:7], v[46:47], s[16:17] op_sel_hi:[1,0]
	ds_bpermute_b32 v52, v41, v43
	s_waitcnt lgkmcnt(1)
	v_add_f32_e32 v46, v53, v54
	v_fmamk_f32 v46, v46, 0x3c800000, v147
	v_mul_f32_e32 v47, 0x4f800000, v46
	v_cmp_gt_f32_e32 vcc, s38, v46
	v_cvt_pk_f16_f32 v7, v6, v7
	s_waitcnt lgkmcnt(0)
; template <bool CAUSAL, bool SHARED> ...
;     ...
;     const int kof0 = fr * 128 + (((0 + G) ^ (fr & 7)) << 4), kof1 = fr * 128 + (((4 + G) ^ (fr & 7)) << 4);
;     const int vrow = (4 * G + qq) * 128 + p * 8, sw = (2 * G + (qq >> 1)) & 3;
;     const h16x8 ones = {(_Float16)1.0f, (_Float16)1.0f, (_Float16)1.0f, (_Float16)1.0f, (_Float16)1.0f, (_Float16)1.0f, (_Float16)1.0f, (_Float16)1.0f};
;     const f32x4 nma = {-mba, -mba, -mba, -mba}, nmb = {-mbb, -mbb, -mbb, -mbb};
;     f32x4 la = {0.f, 0.f, 0.f, 0.f}, lb = la;
;     h16x8 ka[4], kb[4];
;     ka[0] = *(LAS const h16x8*)(Ka + kof0); ka[1] = *(LAS const h16x8*)(Ka + kof1); ka[2] = *(LAS const h16x8*)(Ka + 2048 + kof0); ka[3] = *(LAS const h16x8*)(Ka + 2048 + kof1);
;     if (!SHARED) { kb[0] = *(LAS const h16x8*)(Kb + kof0); kb[1] = *(LAS const h16x8*)(Kb + kof1); kb[2] = *(LAS const h16x8*)(Kb + 2048 + kof0); kb[3] = *(LAS const h16x8*)(Kb + 2048 + kof1); }
;     for (int ks = 0; ks < nsteps; ++ks) {
;         LAS const unsigned char* va = Va + ks * 4096 + vrow; LAS const unsigned char* vb = Vb + ks * 4096 + vrow;
;         h16x4 fal[4], fah[4], fbl[4], fbh[4];
; #pragma unroll
;         for (int dt = 0; dt < 4; ++dt) { fal[dt] = vtr(va + ((dt ^ sw) << 5)); fah[dt] = vtr(va + 2048 + ((dt ^ sw) << 5));
;             if (!SHARED) { fbl[dt] = vtr(vb + ((dt ^ sw) << 5)); fbh[dt] = vtr(vb + 2048 + ((dt ^ sw) << 5)); } }
;         __builtin_amdgcn_sched_barrier(0);
;         f32x4 sa0, sa1, sb0, sb1;
; __device__ __forceinline__ void xattn_load_q(const f16_t* qp  , const float* gqm, int G, float maxgk, h16x8& q0, h16x8& q1, float& mb) {
;     ...
;     const float rn = 1.0f / sqrtf(ss * (1.0f / HD) + EPS);
;     float n2 = 0.f;
; #pragma unroll
;     for (int j = 0; j < 8; ++j) { q[j] *= rn * gqm[8 * G + j]; q[8 + j] *= rn * gqm[32 + 8 * G + j]; n2 += q[j] * q[j] + q[8 + j] * q[8 + j]; }
;     n2 += __shfl_xor(n2, 16); n2 += __shfl_xor(n2, 32);
;     mb = (sqrtf(n2) * maxgk - BOUND_SHIFT) * LOG2E;
;     const float c = 0.125f * LOG2E;
;     u32x4 w0, w1;
;     w0.x = pkh(q[0] * c, q[1] * c); w0.y = pkh(q[2] * c, q[3] * c); w0.z = pkh(q[4] * c, q[5] * c); w0.w = pkh(q[6] * c, q[7] * c);
;     w1.x = pkh(q[8] * c, q[9] * c); w1.y = pkh(q[10] * c, q[11] * c); w1.z = pkh(q[12] * c, q[13] * c); w1.w = pkh(q[14] * c, q[15] * c);
;     q0 = __builtin_bit_cast(h16x8, w0); q1 = __builtin_bit_cast(h16x8, w1);
	v_add_f32_e32 v6, v43, v52
	v_cndmask_b32_e32 v46, v46, v47, vcc
	v_sqrt_f32_e32 v47, v46
	v_mul_f32_e32 v43, 0x4f800000, v6
	v_cmp_gt_f32_e64 s[2:3], s38, v6
	s_nop 1
	v_cndmask_b32_e64 v43, v6, v43, s[2:3]
	v_add_u32_e32 v6, -1, v47
	v_fma_f32 v52, -v6, v47, v46
	v_cmp_ge_f32_e64 s[4:5], 0, v52
	v_add_u32_e32 v52, 1, v47
	v_sqrt_f32_e32 v54, v43
	v_cndmask_b32_e64 v6, v47, v6, s[4:5]
	v_fma_f32 v47, -v52, v47, v46
	v_cmp_lt_f32_e64 s[4:5], 0, v47
	s_nop 1
	v_cndmask_b32_e64 v6, v6, v52, s[4:5]
	v_mul_f32_e32 v47, 0x37800000, v6
	v_cndmask_b32_e32 v6, v6, v47, vcc
	v_cmp_class_f32_e32 vcc, v46, v148
	s_nop 1
	v_cndmask_b32_e32 v52, v6, v46, vcc
	v_div_scale_f32 v53, s[4:5], v52, v52, 1.0
	v_rcp_f32_e32 v55, v53
	v_pk_mul_f32 v[46:47], v[48:49], s[16:17] op_sel_hi:[1,0]
	s_nop 0
	v_cvt_pk_f16_f32 v6, v46, v47
	v_fma_f32 v46, -v53, v55, 1.0
	v_fmac_f32_e32 v55, v46, v55
	v_div_scale_f32 v46, vcc, 1.0, v52, 1.0
	v_mul_f32_e32 v48, v46, v55
	v_fma_f32 v49, -v53, v48, v46
	v_fmac_f32_e32 v48, v49, v55
	v_fma_f32 v46, -v53, v48, v46
	v_div_fmas_f32 v46, v46, v55, v48
	v_add_u32_e32 v47, -1, v54
	v_div_fixup_f32 v46, v46, v52, 1.0
	v_pk_mul_f32 v[22:23], v[22:23], v[46:47] op_sel_hi:[1,0]
	v_pk_mul_f32 v[14:15], v[14:15], v[46:47] op_sel_hi:[1,0]
	v_pk_mul_f32 v[22:23], v[22:23], v[76:77]
	v_pk_mul_f32 v[24:25], v[24:25], v[46:47] op_sel_hi:[1,0]
	v_pk_mul_f32 v[48:49], v[22:23], v[22:23]
	v_pk_mul_f32 v[52:53], v[14:15], v[58:59]
	v_pk_mul_f32 v[24:25], v[24:25], v[50:51]
	v_pk_mul_f32 v[16:17], v[16:17], v[46:47] op_sel_hi:[1,0]
	v_pk_fma_f32 v[14:15], v[52:53], v[52:53], v[48:49]
	v_pk_mul_f32 v[38:39], v[16:17], v[38:39]
	v_pk_mul_f32 v[16:17], v[24:25], v[24:25]
	v_pk_mul_f32 v[18:19], v[18:19], v[46:47] op_sel_hi:[1,0]
	v_pk_fma_f32 v[16:17], v[38:39], v[38:39], v[16:17]
	v_pk_mul_f32 v[18:19], v[18:19], v[66:67]
	v_pk_mul_f32 v[10:11], v[10:11], v[46:47] op_sel_hi:[1,0]
	v_add_f32_e32 v14, v14, v15
	v_pk_mul_f32 v[10:11], v[10:11], v[28:29]
	v_pk_mul_f32 v[28:29], v[18:19], v[18:19]
	v_pk_mul_f32 v[20:21], v[20:21], v[46:47] op_sel_hi:[1,0]
	v_add_f32_e32 v14, v16, v14
	v_pk_fma_f32 v[28:29], v[10:11], v[10:11], v[28:29]
	v_pk_mul_f32 v[20:21], v[20:21], v[44:45]
	v_pk_mul_f32 v[12:13], v[12:13], v[46:47] op_sel_hi:[1,0]
	v_add_f32_e32 v14, v17, v14
	v_pk_mul_f32 v[12:13], v[12:13], v[26:27]
	v_pk_mul_f32 v[26:27], v[20:21], v[20:21]
	v_add_f32_e32 v14, v28, v14
	v_pk_fma_f32 v[26:27], v[12:13], v[12:13], v[26:27]
	v_add_f32_e32 v14, v29, v14
	v_add_f32_e32 v14, v26, v14
	v_add_f32_e32 v14, v27, v14
	ds_bpermute_b32 v15, v40, v14
	v_fma_f32 v16, -v47, v54, v43
	v_add_u32_e32 v17, 1, v54
	v_cmp_ge_f32_e32 vcc, 0, v16
	v_fma_f32 v26, -v17, v54, v43
	s_waitcnt lgkmcnt(0)
	v_add_f32_e32 v14, v14, v15
	ds_bpermute_b32 v15, v41, v14
	v_cndmask_b32_e32 v16, v54, v47, vcc
	v_cmp_lt_f32_e32 vcc, 0, v26
	v_pk_mul_f32 v[10:11], v[10:11], s[16:17] op_sel_hi:[1,0]
	s_waitcnt lgkmcnt(0)
	v_add_f32_e32 v14, v14, v15
	v_cndmask_b32_e32 v16, v16, v17, vcc
	v_mul_f32_e32 v15, 0x4f800000, v14
	v_cmp_gt_f32_e32 vcc, s38, v14
	v_mul_f32_e32 v17, 0x37800000, v16
	v_cndmask_b32_e64 v16, v16, v17, s[2:3]
	v_cndmask_b32_e32 v14, v14, v15, vcc
	v_sqrt_f32_e32 v15, v14
	v_cmp_class_f32_e64 s[2:3], v43, v148
	s_nop 1
	v_cndmask_b32_e64 v26, v16, v43, s[2:3]
	v_add_u32_e32 v16, -1, v15
	v_fma_f32 v17, -v16, v15, v14
	v_cmp_ge_f32_e64 s[2:3], 0, v17
	v_add_u32_e32 v17, 1, v15
	s_nop 0
	v_cndmask_b32_e64 v16, v15, v16, s[2:3]
	v_fma_f32 v15, -v17, v15, v14
	v_cmp_lt_f32_e64 s[2:3], 0, v15
	s_nop 1
	v_cndmask_b32_e64 v15, v16, v17, s[2:3]
	v_mul_f32_e32 v16, 0x37800000, v15
	v_cndmask_b32_e32 v15, v15, v16, vcc
	v_cmp_class_f32_e32 vcc, v14, v148
	v_pk_mul_f32 v[16:17], v[24:25], s[16:17] op_sel_hi:[1,0]
	s_nop 0
	v_cndmask_b32_e32 v27, v15, v14, vcc
	v_pk_mul_f32 v[14:15], v[22:23], s[16:17] op_sel_hi:[1,0]
	s_nop 0
	v_cvt_pk_f16_f32 v14, v14, v15
	v_cvt_pk_f16_f32 v15, v16, v17
	v_pk_mul_f32 v[16:17], v[18:19], s[16:17] op_sel_hi:[1,0]
	v_pk_mul_f32 v[18:19], v[20:21], s[16:17] op_sel_hi:[1,0]
	v_cvt_pk_f16_f32 v16, v16, v17
	v_cvt_pk_f16_f32 v17, v18, v19
	v_pk_mul_f32 v[18:19], v[52:53], s[16:17] op_sel_hi:[1,0]
	v_pk_mul_f32 v[20:21], v[38:39], s[16:17] op_sel_hi:[1,0]
	v_cvt_pk_f16_f32 v18, v18, v19
	v_cvt_pk_f16_f32 v19, v20, v21
	v_cvt_pk_f16_f32 v20, v10, v11
	v_pk_mul_f32 v[10:11], v[12:13], s[16:17] op_sel_hi:[1,0]
	v_add_u32_e32 v38, v142, v141
	v_cvt_pk_f16_f32 v21, v10, v11
	v_fma_f32 v10, v42, v26, -4.0
	v_mul_f32_e32 v22, 0xbfb8aa3b, v10
	ds_read_b128 v[10:13], v149
	ds_read_b128 v[44:47], v149 offset:2048
	ds_read_b128 v[48:51], v150
	ds_read_b128 v[52:55], v150 offset:2048
	ds_read_b64_tr_b16 v[56:57], v38 offset:32768
	ds_read_b64_tr_b16 v[58:59], v38 offset:34816
	ds_read_b64_tr_b16 v[60:61], v151 offset:32768
	ds_read_b64_tr_b16 v[62:63], v151 offset:34816
	ds_read_b64_tr_b16 v[64:65], v152 offset:32768
	ds_read_b64_tr_b16 v[66:67], v152 offset:34816
	ds_read_b64_tr_b16 v[68:69], v153 offset:32768
	ds_read_b64_tr_b16 v[70:71], v153 offset:34816
	v_fma_f32 v26, v42, v27, -4.0
	v_mul_f32_e32 v26, 0xbfb8aa3b, v26
	v_mov_b32_e32 v23, v22
	v_mov_b32_e32 v24, v22
	v_mov_b32_e32 v25, v22
	v_mov_b32_e32 v27, v26
	v_mov_b32_e32 v28, v26
	v_mov_b32_e32 v29, v26
	s_waitcnt lgkmcnt(11)
	v_mfma_f32_16x16x32_f16 v[72:75], v[10:13], v[6:9], v[22:25]
	v_mfma_f32_16x16x32_f16 v[10:13], v[10:13], v[14:17], v[26:29]
	s_waitcnt lgkmcnt(10)
	v_mfma_f32_16x16x32_f16 v[108:111], v[44:47], v[6:9], v[22:25]
	v_mfma_f32_16x16x32_f16 v[44:47], v[44:47], v[14:17], v[26:29]
	s_waitcnt lgkmcnt(9)
	v_mfma_f32_16x16x32_f16 v[72:75], v[48:51], v[2:5], v[72:75]
	v_mfma_f32_16x16x32_f16 v[48:51], v[48:51], v[18:21], v[10:13]
	s_waitcnt lgkmcnt(8)
; #define LAS __attribute__((address_space(3)))
; template <bool CAUSAL, bool SHARED> ...
;     ...
;     for (int ks = 0; ks < nsteps; ++ks) {
;         LAS const unsigned char* va = Va + ks * 4096 + vrow; LAS const unsigned char* vb = Vb + ks * 4096 + vrow;
;         h16x4 fal[4], fah[4], fbl[4], fbh[4];
; #pragma unroll
;         for (int dt = 0; dt < 4; ++dt) { fal[dt] = vtr(va + ((dt ^ sw) << 5)); fah[dt] = vtr(va + 2048 + ((dt ^ sw) << 5));
;             if (!SHARED) { fbl[dt] = vtr(vb + ((dt ^ sw) << 5)); fbh[dt] = vtr(vb + 2048 + ((dt ^ sw) << 5)); } }
;         __builtin_amdgcn_sched_barrier(0);
;         f32x4 sa0, sa1, sb0, sb1;
;         sa0 = __builtin_amdgcn_mfma_f32_16x16x32_f16(ka[0], qa0, nma, 0, 0, 0); sb0 = __builtin_amdgcn_mfma_f32_16x16x32_f16(SHARED ? ka[0] : kb[0], qb0, nmb, 0, 0, 0);
;         sa1 = __builtin_amdgcn_mfma_f32_16x16x32_f16(ka[2], qa0, nma, 0, 0, 0); sb1 = __builtin_amdgcn_mfma_f32_16x16x32_f16(SHARED ? ka[2] : kb[2], qb0, nmb, 0, 0, 0);
;         sa0 = __builtin_amdgcn_mfma_f32_16x16x32_f16(ka[1], qa1, sa0, 0, 0, 0); sb0 = __builtin_amdgcn_mfma_f32_16x16x32_f16(SHARED ? ka[1] : kb[1], qb1, sb0, 0, 0, 0);
;         sa1 = __builtin_amdgcn_mfma_f32_16x16x32_f16(ka[3], qa1, sa1, 0, 0, 0); sb1 = __builtin_amdgcn_mfma_f32_16x16x32_f16(SHARED ? ka[3] : kb[3], qb1, sb1, 0, 0, 0);
;         __builtin_amdgcn_sched_barrier(0);
;         if (ks + 1 < nsteps) { LAS const unsigned char* kn = Ka + (ks + 1) * 4096;
;             ka[0] = *(LAS const h16x8*)(kn + kof0); ka[1] = *(LAS const h16x8*)(kn + kof1); ka[2] = *(LAS const h16x8*)(kn + 2048 + kof0); ka[3] = *(LAS const h16x8*)(kn + 2048 + kof1);
;             if (!SHARED) { LAS const unsigned char* kn2 = Kb + (ks + 1) * 4096;
;                 kb[0] = *(LAS const h16x8*)(kn2 + kof0); kb[1] = *(LAS const h16x8*)(kn2 + kof1); kb[2] = *(LAS const h16x8*)(kn2 + 2048 + kof0); kb[3] = *(LAS const h16x8*)(kn2 + 2048 + kof1); } }
;         __builtin_amdgcn_sched_barrier(0);
;         f32x4 pa0, pa1, pb0, pb1;
; #pragma unroll
;         for (int e = 0; e < 4; ++e) { pa0[e] = __builtin_amdgcn_exp2f(sa0[e]); pa1[e] = __builtin_amdgcn_exp2f(sa1[e]);
;                                       pb0[e] = __builtin_amdgcn_exp2f(sb0[e]); pb1[e] = __builtin_amdgcn_exp2f(sb1[e]); }
;         if (CAUSAL) { const int kr = ks * 32 + 4 * G;
; #pragma unroll
	v_mfma_f32_16x16x32_f16 v[10:13], v[52:55], v[2:5], v[108:111]
	v_mfma_f32_16x16x32_f16 v[44:47], v[52:55], v[18:21], v[44:47]
	ds_read_b128 v[52:55], v150 offset:6144
	s_nop 0
	ds_read_b128 v[108:111], v150 offset:4096
	ds_read_b128 v[112:115], v149 offset:6144
	ds_read_b128 v[116:119], v149 offset:4096
	ds_read_b64_tr_b16 v[168:169], v38 offset:36864
	ds_read_b64_tr_b16 v[170:171], v38 offset:38912
	ds_read_b64_tr_b16 v[172:173], v151 offset:36864
	ds_read_b64_tr_b16 v[174:175], v151 offset:38912
	ds_read_b64_tr_b16 v[176:177], v152 offset:36864
	ds_read_b64_tr_b16 v[178:179], v152 offset:38912
	ds_read_b64_tr_b16 v[180:181], v153 offset:36864
	ds_read_b64_tr_b16 v[182:183], v153 offset:38912
	v_exp_f32_e32 v39, v72
	v_exp_f32_e32 v43, v10
	v_exp_f32_e32 v76, v44
	v_exp_f32_e32 v44, v73
	v_exp_f32_e32 v77, v11
	v_exp_f32_e32 v155, v12
	v_exp_f32_e32 v160, v50
	v_exp_f32_e32 v50, v13
	v_mov_b64_e32 v[12:13], s[10:11]
	v_exp_f32_e32 v48, v48
	v_exp_f32_e32 v49, v49
	v_exp_f32_e32 v80, v45
	v_exp_f32_e32 v45, v74
	v_exp_f32_e32 v161, v46
	v_exp_f32_e32 v46, v75
	v_mov_b64_e32 v[10:11], s[8:9]
	v_cvt_pk_f16_f32 v72, v39, v44
	v_cvt_pk_f16_f32 v74, v43, v77
	v_exp_f32_e32 v39, v51
	v_exp_f32_e32 v43, v47
	v_cvt_pk_f16_f32 v73, v45, v46
	v_cvt_pk_f16_f32 v75, v155, v50
	v_cvt_pk_f16_f32 v44, v48, v49
	v_cvt_pk_f16_f32 v45, v160, v39
	v_cvt_pk_f16_f32 v46, v76, v80
	v_cvt_pk_f16_f32 v47, v161, v43
	v_mfma_f32_16x16x32_f16 v[156:159], v[10:13], v[72:75], 0
	s_waitcnt lgkmcnt(14)
	v_mfma_f32_16x16x32_f16 v[48:51], v[56:59], v[72:75], 0
	v_mfma_f32_16x16x32_f16 v[56:59], v[56:59], v[44:47], 0
	v_mfma_f32_16x16x32_f16 v[160:163], v[60:63], v[72:75], 0
	v_mfma_f32_16x16x32_f16 v[60:63], v[60:63], v[44:47], 0
	v_mfma_f32_16x16x32_f16 v[164:167], v[64:67], v[72:75], 0
	v_mfma_f32_16x16x32_f16 v[64:67], v[64:67], v[44:47], 0
	s_waitcnt lgkmcnt(12)
	v_mfma_f32_16x16x32_f16 v[72:75], v[68:71], v[72:75], 0
	v_mfma_f32_16x16x32_f16 v[68:71], v[68:71], v[44:47], 0
	v_mfma_f32_16x16x32_f16 v[44:47], v[10:13], v[44:47], 0
	s_waitcnt lgkmcnt(8)
	v_mfma_f32_16x16x32_f16 v[184:187], v[116:119], v[6:9], v[22:25]
	v_mfma_f32_16x16x32_f16 v[116:119], v[116:119], v[14:17], v[26:29]
	v_mfma_f32_16x16x32_f16 v[188:191], v[112:115], v[6:9], v[22:25]
	v_mfma_f32_16x16x32_f16 v[112:115], v[112:115], v[14:17], v[26:29]
	v_mfma_f32_16x16x32_f16 v[184:187], v[108:111], v[2:5], v[184:187]
	v_mfma_f32_16x16x32_f16 v[108:111], v[108:111], v[18:21], v[116:119]
	v_mfma_f32_16x16x32_f16 v[116:119], v[52:55], v[2:5], v[188:191]
	v_mfma_f32_16x16x32_f16 v[52:55], v[52:55], v[18:21], v[112:115]
	s_nop 3
	ds_read_b128 v[112:115], v150 offset:10240
	ds_read_b128 v[188:191], v150 offset:8192
	ds_read_b128 v[192:195], v149 offset:10240
	ds_read_b128 v[196:199], v149 offset:8192
	v_exp_f32_e32 v39, v184
	v_exp_f32_e32 v43, v116
	v_exp_f32_e32 v77, v52
	v_exp_f32_e32 v52, v185
	v_exp_f32_e32 v80, v117
	v_exp_f32_e32 v76, v108
	v_exp_f32_e32 v108, v109
	v_exp_f32_e32 v109, v53
	v_exp_f32_e32 v53, v186
	v_exp_f32_e32 v155, v118
	v_exp_f32_e32 v110, v110
	v_exp_f32_e32 v117, v187
	v_exp_f32_e32 v184, v54
	v_exp_f32_e32 v54, v119
	v_cvt_pk_f16_f32 v116, v39, v52
	v_cvt_pk_f16_f32 v118, v43, v80
	v_exp_f32_e32 v39, v111
	v_exp_f32_e32 v43, v55
	v_cvt_pk_f16_f32 v117, v53, v117
	v_cvt_pk_f16_f32 v119, v155, v54
	v_cvt_pk_f16_f32 v52, v76, v108
	v_cvt_pk_f16_f32 v53, v110, v39
	v_cvt_pk_f16_f32 v54, v77, v109
	v_cvt_pk_f16_f32 v55, v184, v43
	v_mfma_f32_16x16x32_f16 v[156:159], v[10:13], v[116:119], v[156:159]
	s_waitcnt lgkmcnt(10)
	v_mfma_f32_16x16x32_f16 v[48:51], v[168:171], v[116:119], v[48:51]
	v_mfma_f32_16x16x32_f16 v[56:59], v[168:171], v[52:55], v[56:59]
	s_waitcnt lgkmcnt(8)
	v_mfma_f32_16x16x32_f16 v[108:111], v[172:175], v[116:119], v[160:163]
	v_mfma_f32_16x16x32_f16 v[60:63], v[172:175], v[52:55], v[60:63]
	s_waitcnt lgkmcnt(6)
	v_mfma_f32_16x16x32_f16 v[160:163], v[176:179], v[116:119], v[164:167]
	s_waitcnt lgkmcnt(4)
	v_mfma_f32_16x16x32_f16 v[72:75], v[180:183], v[116:119], v[72:75]
	ds_read_b64_tr_b16 v[116:117], v38 offset:40960
	ds_read_b64_tr_b16 v[118:119], v38 offset:43008
	ds_read_b64_tr_b16 v[164:165], v151 offset:40960
	ds_read_b64_tr_b16 v[166:167], v151 offset:43008
	ds_read_b64_tr_b16 v[168:169], v152 offset:40960
	ds_read_b64_tr_b16 v[170:171], v152 offset:43008
	ds_read_b64_tr_b16 v[172:173], v153 offset:40960
	ds_read_b64_tr_b16 v[174:175], v153 offset:43008
	v_mfma_f32_16x16x32_f16 v[64:67], v[176:179], v[52:55], v[64:67]
	v_mfma_f32_16x16x32_f16 v[68:71], v[180:183], v[52:55], v[68:71]
	v_mfma_f32_16x16x32_f16 v[44:47], v[10:13], v[52:55], v[44:47]
	s_waitcnt lgkmcnt(8)
	v_mfma_f32_16x16x32_f16 v[52:55], v[196:199], v[6:9], v[22:25]
	v_mfma_f32_16x16x32_f16 v[176:179], v[196:199], v[14:17], v[26:29]
	v_mfma_f32_16x16x32_f16 v[180:183], v[192:195], v[6:9], v[22:25]
	v_mfma_f32_16x16x32_f16 v[184:187], v[192:195], v[14:17], v[26:29]
	v_mfma_f32_16x16x32_f16 v[52:55], v[188:191], v[2:5], v[52:55]
	v_mfma_f32_16x16x32_f16 v[176:179], v[188:191], v[18:21], v[176:179]
	v_mfma_f32_16x16x32_f16 v[180:183], v[112:115], v[2:5], v[180:183]
	v_mfma_f32_16x16x32_f16 v[112:115], v[112:115], v[18:21], v[184:187]
	s_nop 3
	ds_read_b128 v[184:187], v150 offset:14336
	ds_read_b128 v[188:191], v150 offset:12288
	ds_read_b128 v[192:195], v149 offset:14336
	ds_read_b128 v[196:199], v149 offset:12288
	v_exp_f32_e32 v39, v52
	v_exp_f32_e32 v43, v180
	v_exp_f32_e32 v52, v53
	v_exp_f32_e32 v80, v181
	v_exp_f32_e32 v53, v54
	v_exp_f32_e32 v54, v55
	v_exp_f32_e32 v76, v176
	v_exp_f32_e32 v77, v112
	v_exp_f32_e32 v112, v177
	v_exp_f32_e32 v155, v113
	v_exp_f32_e32 v113, v182
	v_exp_f32_e32 v176, v178
	v_exp_f32_e32 v177, v114
	v_exp_f32_e32 v55, v183
	v_cvt_pk_f16_f32 v52, v39, v52
	v_cvt_pk_f16_f32 v53, v53, v54
	v_cvt_pk_f16_f32 v54, v43, v80
	v_exp_f32_e32 v39, v179
	v_exp_f32_e32 v43, v115
	v_cvt_pk_f16_f32 v55, v113, v55
	v_cvt_pk_f16_f32 v112, v76, v112
	v_cvt_pk_f16_f32 v113, v176, v39
	v_cvt_pk_f16_f32 v114, v77, v155
	v_cvt_pk_f16_f32 v115, v177, v43
	v_mfma_f32_16x16x32_f16 v[156:159], v[10:13], v[52:55], v[156:159]
	s_waitcnt lgkmcnt(10)
; #define LAS __attribute__((address_space(3)))
; template <bool CAUSAL, bool SHARED> ...
;     ...
;     for (int ks = 0; ks < nsteps; ++ks) {
;         LAS const unsigned char* va = Va + ks * 4096 + vrow; LAS const unsigned char* vb = Vb + ks * 4096 + vrow;
;         h16x4 fal[4], fah[4], fbl[4], fbh[4];
; #pragma unroll
;         for (int dt = 0; dt < 4; ++dt) { fal[dt] = vtr(va + ((dt ^ sw) << 5)); fah[dt] = vtr(va + 2048 + ((dt ^ sw) << 5));
;             if (!SHARED) { fbl[dt] = vtr(vb + ((dt ^ sw) << 5)); fbh[dt] = vtr(vb + 2048 + ((dt ^ sw) << 5)); } }
;         __builtin_amdgcn_sched_barrier(0);
;         f32x4 sa0, sa1, sb0, sb1;
;         sa0 = __builtin_amdgcn_mfma_f32_16x16x32_f16(ka[0], qa0, nma, 0, 0, 0); sb0 = __builtin_amdgcn_mfma_f32_16x16x32_f16(SHARED ? ka[0] : kb[0], qb0, nmb, 0, 0, 0);
;         sa1 = __builtin_amdgcn_mfma_f32_16x16x32_f16(ka[2], qa0, nma, 0, 0, 0); sb1 = __builtin_amdgcn_mfma_f32_16x16x32_f16(SHARED ? ka[2] : kb[2], qb0, nmb, 0, 0, 0);
;         sa0 = __builtin_amdgcn_mfma_f32_16x16x32_f16(ka[1], qa1, sa0, 0, 0, 0); sb0 = __builtin_amdgcn_mfma_f32_16x16x32_f16(SHARED ? ka[1] : kb[1], qb1, sb0, 0, 0, 0);
;         sa1 = __builtin_amdgcn_mfma_f32_16x16x32_f16(ka[3], qa1, sa1, 0, 0, 0); sb1 = __builtin_amdgcn_mfma_f32_16x16x32_f16(SHARED ? ka[3] : kb[3], qb1, sb1, 0, 0, 0);
;         __builtin_amdgcn_sched_barrier(0);
;         if (ks + 1 < nsteps) { LAS const unsigned char* kn = Ka + (ks + 1) * 4096;
;             ka[0] = *(LAS const h16x8*)(kn + kof0); ka[1] = *(LAS const h16x8*)(kn + kof1); ka[2] = *(LAS const h16x8*)(kn + 2048 + kof0); ka[3] = *(LAS const h16x8*)(kn + 2048 + kof1);
;             if (!SHARED) { LAS const unsigned char* kn2 = Kb + (ks + 1) * 4096;
;                 kb[0] = *(LAS const h16x8*)(kn2 + kof0); kb[1] = *(LAS const h16x8*)(kn2 + kof1); kb[2] = *(LAS const h16x8*)(kn2 + 2048 + kof0); kb[3] = *(LAS const h16x8*)(kn2 + 2048 + kof1); } }
;         __builtin_amdgcn_sched_barrier(0);
;         f32x4 pa0, pa1, pb0, pb1;
; #pragma unroll
;         for (int e = 0; e < 4; ++e) { pa0[e] = __builtin_amdgcn_exp2f(sa0[e]); pa1[e] = __builtin_amdgcn_exp2f(sa1[e]);
;                                       pb0[e] = __builtin_amdgcn_exp2f(sb0[e]); pb1[e] = __builtin_amdgcn_exp2f(sb1[e]); }
;         if (CAUSAL) { const int kr = ks * 32 + 4 * G;
; #pragma unroll
	v_mfma_f32_16x16x32_f16 v[48:51], v[116:119], v[52:55], v[48:51]
	v_mfma_f32_16x16x32_f16 v[56:59], v[116:119], v[112:115], v[56:59]
	s_waitcnt lgkmcnt(8)
	v_mfma_f32_16x16x32_f16 v[108:111], v[164:167], v[52:55], v[108:111]
	v_mfma_f32_16x16x32_f16 v[60:63], v[164:167], v[112:115], v[60:63]
	s_waitcnt lgkmcnt(6)
	v_mfma_f32_16x16x32_f16 v[116:119], v[168:171], v[52:55], v[160:163]
	v_mfma_f32_16x16x32_f16 v[64:67], v[168:171], v[112:115], v[64:67]
	s_waitcnt lgkmcnt(4)
	v_mfma_f32_16x16x32_f16 v[52:55], v[172:175], v[52:55], v[72:75]
	s_nop 2
	ds_read_b64_tr_b16 v[72:73], v38 offset:45056
	ds_read_b64_tr_b16 v[74:75], v38 offset:47104
	ds_read_b64_tr_b16 v[160:161], v151 offset:45056
	ds_read_b64_tr_b16 v[162:163], v151 offset:47104
	ds_read_b64_tr_b16 v[164:165], v152 offset:45056
	ds_read_b64_tr_b16 v[166:167], v152 offset:47104
	ds_read_b64_tr_b16 v[168:169], v153 offset:45056
	ds_read_b64_tr_b16 v[170:171], v153 offset:47104
	v_mfma_f32_16x16x32_f16 v[68:71], v[172:175], v[112:115], v[68:71]
	v_mfma_f32_16x16x32_f16 v[44:47], v[10:13], v[112:115], v[44:47]
	s_waitcnt lgkmcnt(8)
	v_mfma_f32_16x16x32_f16 v[112:115], v[196:199], v[6:9], v[22:25]
	v_mfma_f32_16x16x32_f16 v[172:175], v[196:199], v[14:17], v[26:29]
	v_mfma_f32_16x16x32_f16 v[176:179], v[192:195], v[6:9], v[22:25]
	v_mfma_f32_16x16x32_f16 v[180:183], v[192:195], v[14:17], v[26:29]
	v_mfma_f32_16x16x32_f16 v[112:115], v[188:191], v[2:5], v[112:115]
	v_mfma_f32_16x16x32_f16 v[172:175], v[188:191], v[18:21], v[172:175]
	v_mfma_f32_16x16x32_f16 v[176:179], v[184:187], v[2:5], v[176:179]
	v_mfma_f32_16x16x32_f16 v[180:183], v[184:187], v[18:21], v[180:183]
	ds_read_b128 v[184:187], v150 offset:18432
	ds_read_b128 v[188:191], v150 offset:16384
	ds_read_b128 v[192:195], v149 offset:18432
	ds_read_b128 v[196:199], v149 offset:16384
	s_nop 0
	v_exp_f32_e32 v39, v112
	s_nop 0
	v_exp_f32_e32 v43, v176
	v_exp_f32_e32 v80, v113
	v_exp_f32_e32 v155, v177
	v_exp_f32_e32 v113, v114
	v_exp_f32_e32 v114, v115
	v_exp_f32_e32 v76, v172
	v_exp_f32_e32 v77, v180
	v_exp_f32_e32 v172, v173
	v_exp_f32_e32 v176, v181
	v_exp_f32_e32 v173, v178
	v_exp_f32_e32 v174, v174
	v_exp_f32_e32 v177, v182
	v_exp_f32_e32 v115, v179
	v_cvt_pk_f16_f32 v112, v39, v80
	v_cvt_pk_f16_f32 v113, v113, v114
	v_cvt_pk_f16_f32 v114, v43, v155
	v_exp_f32_e32 v39, v175
	v_exp_f32_e32 v43, v183
	v_cvt_pk_f16_f32 v115, v173, v115
	v_cvt_pk_f16_f32 v172, v76, v172
	v_cvt_pk_f16_f32 v173, v174, v39
	v_cvt_pk_f16_f32 v174, v77, v176
	v_cvt_pk_f16_f32 v175, v177, v43
	v_mfma_f32_16x16x32_f16 v[156:159], v[10:13], v[112:115], v[156:159]
	s_waitcnt lgkmcnt(10)
	v_mfma_f32_16x16x32_f16 v[48:51], v[72:75], v[112:115], v[48:51]
	v_mfma_f32_16x16x32_f16 v[56:59], v[72:75], v[172:175], v[56:59]
	s_waitcnt lgkmcnt(8)
	v_mfma_f32_16x16x32_f16 v[72:75], v[160:163], v[112:115], v[108:111]
	v_mfma_f32_16x16x32_f16 v[60:63], v[160:163], v[172:175], v[60:63]
	s_waitcnt lgkmcnt(6)
	v_mfma_f32_16x16x32_f16 v[108:111], v[164:167], v[112:115], v[116:119]
	v_mfma_f32_16x16x32_f16 v[64:67], v[164:167], v[172:175], v[64:67]
	s_waitcnt lgkmcnt(4)
	v_mfma_f32_16x16x32_f16 v[52:55], v[168:171], v[112:115], v[52:55]
	ds_read_b64_tr_b16 v[112:113], v38 offset:49152
	ds_read_b64_tr_b16 v[114:115], v38 offset:51200
	ds_read_b64_tr_b16 v[116:117], v151 offset:49152
	ds_read_b64_tr_b16 v[118:119], v151 offset:51200
	ds_read_b64_tr_b16 v[160:161], v152 offset:49152
	ds_read_b64_tr_b16 v[162:163], v152 offset:51200
	ds_read_b64_tr_b16 v[164:165], v153 offset:49152
	ds_read_b64_tr_b16 v[166:167], v153 offset:51200
	v_mfma_f32_16x16x32_f16 v[68:71], v[168:171], v[172:175], v[68:71]
	v_mfma_f32_16x16x32_f16 v[44:47], v[10:13], v[172:175], v[44:47]
	s_waitcnt lgkmcnt(8)
	v_mfma_f32_16x16x32_f16 v[168:171], v[196:199], v[6:9], v[22:25]
	v_mfma_f32_16x16x32_f16 v[172:175], v[196:199], v[14:17], v[26:29]
	v_mfma_f32_16x16x32_f16 v[176:179], v[192:195], v[6:9], v[22:25]
	v_mfma_f32_16x16x32_f16 v[180:183], v[192:195], v[14:17], v[26:29]
	v_mfma_f32_16x16x32_f16 v[168:171], v[188:191], v[2:5], v[168:171]
	v_mfma_f32_16x16x32_f16 v[172:175], v[188:191], v[18:21], v[172:175]
	v_mfma_f32_16x16x32_f16 v[176:179], v[184:187], v[2:5], v[176:179]
	v_mfma_f32_16x16x32_f16 v[180:183], v[184:187], v[18:21], v[180:183]
	ds_read_b128 v[184:187], v150 offset:22528
	ds_read_b128 v[188:191], v150 offset:20480
	ds_read_b128 v[192:195], v149 offset:22528
	ds_read_b128 v[196:199], v149 offset:20480
	s_nop 0
	v_exp_f32_e32 v39, v168
	s_nop 0
	v_exp_f32_e32 v43, v176
	v_exp_f32_e32 v80, v169
	v_exp_f32_e32 v155, v177
	v_exp_f32_e32 v169, v170
	v_exp_f32_e32 v170, v171
	v_exp_f32_e32 v76, v172
	v_exp_f32_e32 v77, v180
	v_exp_f32_e32 v172, v173
	v_exp_f32_e32 v176, v181
	v_exp_f32_e32 v173, v178
	v_exp_f32_e32 v174, v174
	v_exp_f32_e32 v177, v182
	v_exp_f32_e32 v171, v179
	v_cvt_pk_f16_f32 v168, v39, v80
	v_cvt_pk_f16_f32 v169, v169, v170
	v_cvt_pk_f16_f32 v170, v43, v155
	v_exp_f32_e32 v39, v175
	v_exp_f32_e32 v43, v183
	v_cvt_pk_f16_f32 v171, v173, v171
	v_cvt_pk_f16_f32 v172, v76, v172
	v_cvt_pk_f16_f32 v173, v174, v39
	v_cvt_pk_f16_f32 v174, v77, v176
	v_cvt_pk_f16_f32 v175, v177, v43
	s_waitcnt lgkmcnt(10)
	v_mfma_f32_16x16x32_f16 v[48:51], v[112:115], v[168:171], v[48:51]
	v_mfma_f32_16x16x32_f16 v[56:59], v[112:115], v[172:175], v[56:59]
	s_waitcnt lgkmcnt(8)
	v_mfma_f32_16x16x32_f16 v[72:75], v[116:119], v[168:171], v[72:75]
	v_mfma_f32_16x16x32_f16 v[60:63], v[116:119], v[172:175], v[60:63]
	s_waitcnt lgkmcnt(6)
	v_mfma_f32_16x16x32_f16 v[108:111], v[160:163], v[168:171], v[108:111]
	v_mfma_f32_16x16x32_f16 v[64:67], v[160:163], v[172:175], v[64:67]
	s_waitcnt lgkmcnt(4)
; #define LAS __attribute__((address_space(3)))
; template <bool CAUSAL, bool SHARED> ...
;     ...
;     for (int ks = 0; ks < nsteps; ++ks) {
;         LAS const unsigned char* va = Va + ks * 4096 + vrow; LAS const unsigned char* vb = Vb + ks * 4096 + vrow;
;         h16x4 fal[4], fah[4], fbl[4], fbh[4];
; #pragma unroll
;         for (int dt = 0; dt < 4; ++dt) { fal[dt] = vtr(va + ((dt ^ sw) << 5)); fah[dt] = vtr(va + 2048 + ((dt ^ sw) << 5));
;             if (!SHARED) { fbl[dt] = vtr(vb + ((dt ^ sw) << 5)); fbh[dt] = vtr(vb + 2048 + ((dt ^ sw) << 5)); } }
;         __builtin_amdgcn_sched_barrier(0);
;         f32x4 sa0, sa1, sb0, sb1;
;         sa0 = __builtin_amdgcn_mfma_f32_16x16x32_f16(ka[0], qa0, nma, 0, 0, 0); sb0 = __builtin_amdgcn_mfma_f32_16x16x32_f16(SHARED ? ka[0] : kb[0], qb0, nmb, 0, 0, 0);
;         sa1 = __builtin_amdgcn_mfma_f32_16x16x32_f16(ka[2], qa0, nma, 0, 0, 0); sb1 = __builtin_amdgcn_mfma_f32_16x16x32_f16(SHARED ? ka[2] : kb[2], qb0, nmb, 0, 0, 0);
;         sa0 = __builtin_amdgcn_mfma_f32_16x16x32_f16(ka[1], qa1, sa0, 0, 0, 0); sb0 = __builtin_amdgcn_mfma_f32_16x16x32_f16(SHARED ? ka[1] : kb[1], qb1, sb0, 0, 0, 0);
;         sa1 = __builtin_amdgcn_mfma_f32_16x16x32_f16(ka[3], qa1, sa1, 0, 0, 0); sb1 = __builtin_amdgcn_mfma_f32_16x16x32_f16(SHARED ? ka[3] : kb[3], qb1, sb1, 0, 0, 0);
;         __builtin_amdgcn_sched_barrier(0);
;         if (ks + 1 < nsteps) { LAS const unsigned char* kn = Ka + (ks + 1) * 4096;
;             ka[0] = *(LAS const h16x8*)(kn + kof0); ka[1] = *(LAS const h16x8*)(kn + kof1); ka[2] = *(LAS const h16x8*)(kn + 2048 + kof0); ka[3] = *(LAS const h16x8*)(kn + 2048 + kof1);
;             if (!SHARED) { LAS const unsigned char* kn2 = Kb + (ks + 1) * 4096;
;                 kb[0] = *(LAS const h16x8*)(kn2 + kof0); kb[1] = *(LAS const h16x8*)(kn2 + kof1); kb[2] = *(LAS const h16x8*)(kn2 + 2048 + kof0); kb[3] = *(LAS const h16x8*)(kn2 + 2048 + kof1); } }
;         __builtin_amdgcn_sched_barrier(0);
;         f32x4 pa0, pa1, pb0, pb1;
; #pragma unroll
;         for (int e = 0; e < 4; ++e) { pa0[e] = __builtin_amdgcn_exp2f(sa0[e]); pa1[e] = __builtin_amdgcn_exp2f(sa1[e]);
;                                       pb0[e] = __builtin_amdgcn_exp2f(sb0[e]); pb1[e] = __builtin_amdgcn_exp2f(sb1[e]); }
;         if (CAUSAL) { const int kr = ks * 32 + 4 * G;
; #pragma unroll
	v_mfma_f32_16x16x32_f16 v[52:55], v[164:167], v[168:171], v[52:55]
	v_mfma_f32_16x16x32_f16 v[68:71], v[164:167], v[172:175], v[68:71]
	ds_read_b64_tr_b16 v[112:113], v38 offset:53248
	ds_read_b64_tr_b16 v[114:115], v38 offset:55296
	ds_read_b64_tr_b16 v[116:117], v151 offset:53248
	ds_read_b64_tr_b16 v[118:119], v151 offset:55296
	ds_read_b64_tr_b16 v[160:161], v152 offset:53248
	ds_read_b64_tr_b16 v[162:163], v152 offset:55296
	ds_read_b64_tr_b16 v[164:165], v153 offset:53248
	ds_read_b64_tr_b16 v[166:167], v153 offset:55296
	v_mfma_f32_16x16x32_f16 v[156:159], v[10:13], v[168:171], v[156:159]
	v_mfma_f32_16x16x32_f16 v[44:47], v[10:13], v[172:175], v[44:47]
	s_waitcnt lgkmcnt(8)
	v_mfma_f32_16x16x32_f16 v[168:171], v[196:199], v[6:9], v[22:25]
	v_mfma_f32_16x16x32_f16 v[172:175], v[196:199], v[14:17], v[26:29]
	v_mfma_f32_16x16x32_f16 v[176:179], v[192:195], v[6:9], v[22:25]
	v_mfma_f32_16x16x32_f16 v[180:183], v[192:195], v[14:17], v[26:29]
	v_mfma_f32_16x16x32_f16 v[168:171], v[188:191], v[2:5], v[168:171]
	v_mfma_f32_16x16x32_f16 v[172:175], v[188:191], v[18:21], v[172:175]
	v_mfma_f32_16x16x32_f16 v[176:179], v[184:187], v[2:5], v[176:179]
	v_mfma_f32_16x16x32_f16 v[180:183], v[184:187], v[18:21], v[180:183]
	ds_read_b128 v[184:187], v150 offset:26624
	ds_read_b128 v[188:191], v150 offset:24576
	ds_read_b128 v[192:195], v149 offset:26624
	ds_read_b128 v[196:199], v149 offset:24576
	s_nop 0
	v_exp_f32_e32 v39, v168
	s_nop 0
	v_exp_f32_e32 v43, v176
	v_exp_f32_e32 v80, v169
	v_exp_f32_e32 v155, v177
	v_exp_f32_e32 v169, v170
	v_exp_f32_e32 v170, v171
	v_exp_f32_e32 v76, v172
	v_exp_f32_e32 v77, v180
	v_exp_f32_e32 v172, v173
	v_exp_f32_e32 v176, v181
	v_exp_f32_e32 v173, v178
	v_exp_f32_e32 v174, v174
	v_exp_f32_e32 v177, v182
	v_exp_f32_e32 v171, v179
	v_cvt_pk_f16_f32 v168, v39, v80
	v_cvt_pk_f16_f32 v169, v169, v170
	v_cvt_pk_f16_f32 v170, v43, v155
	v_exp_f32_e32 v39, v175
	v_exp_f32_e32 v43, v183
	v_cvt_pk_f16_f32 v171, v173, v171
	v_cvt_pk_f16_f32 v172, v76, v172
	v_cvt_pk_f16_f32 v173, v174, v39
	v_cvt_pk_f16_f32 v174, v77, v176
	v_cvt_pk_f16_f32 v175, v177, v43
	s_waitcnt lgkmcnt(10)
	v_mfma_f32_16x16x32_f16 v[48:51], v[112:115], v[168:171], v[48:51]
	v_mfma_f32_16x16x32_f16 v[56:59], v[112:115], v[172:175], v[56:59]
	s_waitcnt lgkmcnt(8)
	v_mfma_f32_16x16x32_f16 v[72:75], v[116:119], v[168:171], v[72:75]
	v_mfma_f32_16x16x32_f16 v[60:63], v[116:119], v[172:175], v[60:63]
	s_waitcnt lgkmcnt(6)
	v_mfma_f32_16x16x32_f16 v[108:111], v[160:163], v[168:171], v[108:111]
	v_mfma_f32_16x16x32_f16 v[64:67], v[160:163], v[172:175], v[64:67]
	s_waitcnt lgkmcnt(4)
	v_mfma_f32_16x16x32_f16 v[52:55], v[164:167], v[168:171], v[52:55]
	v_mfma_f32_16x16x32_f16 v[68:71], v[164:167], v[172:175], v[68:71]
	ds_read_b64_tr_b16 v[112:113], v38 offset:57344
	ds_read_b64_tr_b16 v[114:115], v38 offset:59392
	ds_read_b64_tr_b16 v[116:117], v151 offset:57344
	ds_read_b64_tr_b16 v[118:119], v151 offset:59392
	ds_read_b64_tr_b16 v[160:161], v152 offset:57344
	ds_read_b64_tr_b16 v[162:163], v152 offset:59392
	ds_read_b64_tr_b16 v[164:165], v153 offset:57344
	ds_read_b64_tr_b16 v[166:167], v153 offset:59392
	v_mfma_f32_16x16x32_f16 v[156:159], v[10:13], v[168:171], v[156:159]
	v_mfma_f32_16x16x32_f16 v[44:47], v[10:13], v[172:175], v[44:47]
	s_waitcnt lgkmcnt(8)
	v_mfma_f32_16x16x32_f16 v[168:171], v[196:199], v[6:9], v[22:25]
	v_mfma_f32_16x16x32_f16 v[172:175], v[196:199], v[14:17], v[26:29]
	v_mfma_f32_16x16x32_f16 v[176:179], v[192:195], v[6:9], v[22:25]
	v_mfma_f32_16x16x32_f16 v[180:183], v[192:195], v[14:17], v[26:29]
	v_mfma_f32_16x16x32_f16 v[168:171], v[188:191], v[2:5], v[168:171]
	v_mfma_f32_16x16x32_f16 v[172:175], v[188:191], v[18:21], v[172:175]
	v_mfma_f32_16x16x32_f16 v[176:179], v[184:187], v[2:5], v[176:179]
	v_mfma_f32_16x16x32_f16 v[180:183], v[184:187], v[18:21], v[180:183]
	ds_read_b128 v[184:187], v150 offset:30720
	ds_read_b128 v[188:191], v150 offset:28672
	ds_read_b128 v[192:195], v149 offset:30720
	ds_read_b128 v[196:199], v149 offset:28672
	s_nop 0
	v_exp_f32_e32 v39, v168
	s_nop 0
	v_exp_f32_e32 v43, v176
	v_exp_f32_e32 v80, v169
	v_exp_f32_e32 v155, v177
	v_exp_f32_e32 v169, v170
	v_exp_f32_e32 v170, v171
	v_exp_f32_e32 v76, v172
	v_exp_f32_e32 v77, v180
	v_exp_f32_e32 v172, v173
	v_exp_f32_e32 v176, v181
	v_exp_f32_e32 v173, v178
	v_exp_f32_e32 v174, v174
	v_exp_f32_e32 v177, v182
	v_exp_f32_e32 v171, v179
	v_cvt_pk_f16_f32 v168, v39, v80
	v_cvt_pk_f16_f32 v169, v169, v170
	v_cvt_pk_f16_f32 v170, v43, v155
	v_exp_f32_e32 v39, v175
	v_exp_f32_e32 v43, v183
	v_cvt_pk_f16_f32 v171, v173, v171
	v_cvt_pk_f16_f32 v172, v76, v172
	v_cvt_pk_f16_f32 v173, v174, v39
	v_cvt_pk_f16_f32 v174, v77, v176
	v_cvt_pk_f16_f32 v175, v177, v43
	s_waitcnt lgkmcnt(10)
	v_mfma_f32_16x16x32_f16 v[48:51], v[112:115], v[168:171], v[48:51]
	v_mfma_f32_16x16x32_f16 v[56:59], v[112:115], v[172:175], v[56:59]
	s_waitcnt lgkmcnt(8)
	v_mfma_f32_16x16x32_f16 v[72:75], v[116:119], v[168:171], v[72:75]
	v_mfma_f32_16x16x32_f16 v[60:63], v[116:119], v[172:175], v[60:63]
	s_waitcnt lgkmcnt(6)
	v_mfma_f32_16x16x32_f16 v[108:111], v[160:163], v[168:171], v[108:111]
	v_mfma_f32_16x16x32_f16 v[64:67], v[160:163], v[172:175], v[64:67]
	s_waitcnt lgkmcnt(4)
; __device__ __forceinline__ unsigned pkh(float lo, float hi) { f32x2 v = {lo, hi}; h16x2 h = __builtin_convertvector(v, h16x2); return __builtin_bit_cast(unsigned, h); }
; __device__ __forceinline__ h16x8 cat8(h16x4 lo, h16x4 hi) { return (h16x8){lo[0], lo[1], lo[2], lo[3], hi[0], hi[1], hi[2], hi[3]}; }
; __device__ __forceinline__ int pair16_dim(int G, int dt0) { return (G & 1) ? 16 * (dt0 + 1) + 4 * (G - 1) : 16 * dt0 + 4 * G; }
; __device__ __forceinline__ void store_o16(f16_t* rowp, const f32x4 (&o)[4], float il, int G) {
; #pragma unroll
;     for (int pr = 0; pr < 2; ++pr) { const int dt0 = 2 * pr;
;         u32x2 a, b; a.x = pkh(o[dt0][0] * il, o[dt0][1] * il); a.y = pkh(o[dt0][2] * il, o[dt0][3] * il); b.x = pkh(o[dt0 + 1][0] * il, o[dt0 + 1][1] * il); b.y = pkh(o[dt0 + 1][2] * il, o[dt0 + 1][3] * il);
;         *(u32x4*)(rowp + pair16_dim(G, dt0)) = pair16(a, b); }
; }
; template <bool CAUSAL, bool SHARED> ...
;     ...
;         la = __builtin_amdgcn_mfma_f32_16x16x32_f16(ones, pfa, la, 0, 0, 0); lb = __builtin_amdgcn_mfma_f32_16x16x32_f16(ones, pfb, lb, 0, 0, 0);
; #pragma unroll
;         for (int dt = 0; dt < 4; ++dt) {
;             const h16x8 fa = cat8(fal[dt], fah[dt]);
;             const h16x8 fb = SHARED ? fa : cat8(fbl[dt], fbh[dt]);
;             oa[dt] = __builtin_amdgcn_mfma_f32_16x16x32_f16(fa, pfa, oa[dt], 0, 0, 0);
;             ob[dt] = __builtin_amdgcn_mfma_f32_16x16x32_f16(fb, pfb, ob[dt], 0, 0, 0);
;         }
;     }
;     lsa_out = la[0]; lsb_out = lb[0];
	v_mfma_f32_16x16x32_f16 v[52:55], v[164:167], v[168:171], v[52:55]
	v_mfma_f32_16x16x32_f16 v[68:71], v[164:167], v[172:175], v[68:71]
	ds_read_b64_tr_b16 v[112:113], v38 offset:61440
	ds_read_b64_tr_b16 v[114:115], v38 offset:63488
	ds_read_b64_tr_b16 v[116:117], v151 offset:61440
	ds_read_b64_tr_b16 v[118:119], v151 offset:63488
	ds_read_b64_tr_b16 v[160:161], v152 offset:61440
	ds_read_b64_tr_b16 v[162:163], v152 offset:63488
	ds_read_b64_tr_b16 v[164:165], v153 offset:61440
	ds_read_b64_tr_b16 v[166:167], v153 offset:63488
	v_mfma_f32_16x16x32_f16 v[156:159], v[10:13], v[168:171], v[156:159]
	v_mfma_f32_16x16x32_f16 v[44:47], v[10:13], v[172:175], v[44:47]
	s_waitcnt lgkmcnt(8)
	v_mfma_f32_16x16x32_f16 v[168:171], v[196:199], v[6:9], v[22:25]
	v_mfma_f32_16x16x32_f16 v[172:175], v[196:199], v[14:17], v[26:29]
	v_mfma_f32_16x16x32_f16 v[6:9], v[192:195], v[6:9], v[22:25]
	v_mfma_f32_16x16x32_f16 v[14:17], v[192:195], v[14:17], v[26:29]
	v_mfma_f32_16x16x32_f16 v[22:25], v[188:191], v[2:5], v[168:171]
	v_mfma_f32_16x16x32_f16 v[26:29], v[188:191], v[18:21], v[172:175]
	v_mfma_f32_16x16x32_f16 v[2:5], v[184:187], v[2:5], v[6:9]
	v_mfma_f32_16x16x32_f16 v[6:9], v[184:187], v[18:21], v[14:17]
	s_nop 7
	v_exp_f32_e32 v21, v7
	v_exp_f32_e32 v7, v4
	v_exp_f32_e32 v5, v5
	v_exp_f32_e32 v14, v22
	v_exp_f32_e32 v15, v2
	v_exp_f32_e32 v20, v6
	v_exp_f32_e32 v2, v23
	v_exp_f32_e32 v6, v3
	v_exp_f32_e32 v3, v24
	v_exp_f32_e32 v4, v25
	v_exp_f32_e32 v18, v26
	v_exp_f32_e32 v19, v27
	v_exp_f32_e32 v22, v28
	v_exp_f32_e32 v23, v8
	v_cvt_pk_f16_f32 v5, v7, v5
	v_exp_f32_e32 v7, v29
	v_exp_f32_e32 v9, v9
	v_cvt_pk_f16_f32 v2, v14, v2
	v_cvt_pk_f16_f32 v3, v3, v4
	v_cvt_pk_f16_f32 v4, v15, v6
	v_cvt_pk_f16_f32 v6, v18, v19
	v_cvt_pk_f16_f32 v7, v22, v7
	v_mfma_f32_16x16x32_f16 v[14:17], v[10:13], v[2:5], v[156:159]
	v_cvt_pk_f16_f32 v8, v20, v21
	v_cvt_pk_f16_f32 v9, v23, v9
	s_add_u32 s4, s21, s14
	s_waitcnt lgkmcnt(6)
	v_mfma_f32_16x16x32_f16 v[16:19], v[112:115], v[2:5], v[48:51]
	s_addc_u32 s5, s22, 0
	v_lshl_add_u64 v[28:29], s[4:5], 0, v[34:35]
	v_lshl_add_u64 v[38:39], s[4:5], 0, v[36:37]
	v_mfma_f32_16x16x32_f16 v[20:23], v[112:115], v[6:9], v[56:59]
	v_lshlrev_b32_e32 v80, 1, v82
	s_and_b64 s[2:3], exec, s[18:19]
	s_mov_b32 s14, 1
	s_waitcnt lgkmcnt(4)
	v_mfma_f32_16x16x32_f16 v[24:27], v[116:119], v[2:5], v[72:75]
	s_mov_b64 s[18:19], 0
	v_lshl_add_u64 v[28:29], v[28:29], 0, v[80:81]
	v_lshl_add_u64 v[38:39], v[38:39], 0, v[80:81]
	v_mfma_f32_16x16x32_f16 v[48:51], v[116:119], v[6:9], v[60:63]
	s_waitcnt lgkmcnt(2)
	v_mfma_f32_16x16x32_f16 v[56:59], v[160:163], v[2:5], v[108:111]
	v_mfma_f32_16x16x32_f16 v[60:63], v[160:163], v[6:9], v[64:67]
	s_waitcnt lgkmcnt(0)
	v_mfma_f32_16x16x32_f16 v[2:5], v[164:167], v[2:5], v[52:55]
	v_mfma_f32_16x16x32_f16 v[52:55], v[164:167], v[6:9], v[68:71]
	v_mfma_f32_16x16x32_f16 v[6:9], v[10:13], v[6:9], v[44:47]
	s_nop 7
	v_div_scale_f32 v7, s[4:5], v14, v14, 1.0
	v_div_scale_f32 v9, s[4:5], v6, v6, 1.0
	v_rcp_f32_e32 v11, v7
	v_rcp_f32_e32 v12, v9
	v_div_scale_f32 v8, vcc, 1.0, v14, 1.0
	v_fma_f32 v13, -v7, v11, 1.0
	v_fma_f32 v15, -v9, v12, 1.0
	v_fmac_f32_e32 v11, v13, v11
	v_div_scale_f32 v10, s[4:5], 1.0, v6, 1.0
	v_fmac_f32_e32 v12, v15, v12
	v_mul_f32_e32 v13, v8, v11
	v_mul_f32_e32 v15, v10, v12
	v_fma_f32 v43, -v7, v13, v8
	v_fma_f32 v44, -v9, v15, v10
	v_fmac_f32_e32 v13, v43, v11
	v_fmac_f32_e32 v15, v44, v12
	v_fma_f32 v7, -v7, v13, v8
	v_fma_f32 v9, -v9, v15, v10
	v_div_fmas_f32 v7, v7, v11, v13
	s_mov_b64 vcc, s[4:5]
	v_div_fixup_f32 v8, v7, v14, 1.0
	v_div_fmas_f32 v7, v9, v12, v15
	v_div_fixup_f32 v10, v7, v6, 1.0
	v_pk_mul_f32 v[6:7], v[8:9], v[16:17] op_sel_hi:[0,1]
	v_pk_mul_f32 v[12:13], v[8:9], v[18:19] op_sel_hi:[0,1]
	v_pk_mul_f32 v[14:15], v[8:9], v[24:25] op_sel_hi:[0,1]
	v_pk_mul_f32 v[16:17], v[8:9], v[26:27] op_sel_hi:[0,1]
	v_pk_mul_f32 v[18:19], v[8:9], v[56:57] op_sel_hi:[0,1]
	v_pk_mul_f32 v[24:25], v[8:9], v[58:59] op_sel_hi:[0,1]
	v_pk_mul_f32 v[26:27], v[8:9], v[2:3] op_sel_hi:[0,1]
	v_pk_mul_f32 v[44:45], v[8:9], v[4:5] op_sel_hi:[0,1]
	v_cvt_pk_f16_f32 v2, v6, v7
	v_cvt_pk_f16_f32 v3, v12, v13
	v_cvt_pk_f16_f32 v4, v14, v15
	v_cvt_pk_f16_f32 v5, v16, v17
	v_cvt_pk_f16_f32 v6, v18, v19
	v_pk_mul_f32 v[12:13], v[20:21], v[10:11] op_sel_hi:[1,0]
	v_pk_mul_f32 v[14:15], v[22:23], v[10:11] op_sel_hi:[1,0]
	v_pk_mul_f32 v[16:17], v[48:49], v[10:11] op_sel_hi:[1,0]
	v_pk_mul_f32 v[18:19], v[50:51], v[10:11] op_sel_hi:[1,0]
	v_cvt_pk_f16_f32 v7, v24, v25
	v_cvt_pk_f16_f32 v8, v26, v27
	v_pk_mul_f32 v[20:21], v[60:61], v[10:11] op_sel_hi:[1,0]
	v_pk_mul_f32 v[22:23], v[62:63], v[10:11] op_sel_hi:[1,0]
	v_pk_mul_f32 v[24:25], v[52:53], v[10:11] op_sel_hi:[1,0]
	v_pk_mul_f32 v[26:27], v[54:55], v[10:11] op_sel_hi:[1,0]
	v_cvt_pk_f16_f32 v10, v12, v13
	v_cvt_pk_f16_f32 v11, v14, v15
	v_cvt_pk_f16_f32 v12, v16, v17
	v_cvt_pk_f16_f32 v13, v18, v19
	v_cvt_pk_f16_f32 v9, v44, v45
	v_permlane16_swap_b32_e32 v2, v4
	v_permlane16_swap_b32_e32 v3, v5
	v_cvt_pk_f16_f32 v14, v20, v21
	v_cvt_pk_f16_f32 v15, v22, v23
	v_cvt_pk_f16_f32 v16, v24, v25
	v_cvt_pk_f16_f32 v17, v26, v27
	v_permlane16_swap_b32_e32 v10, v12
	v_permlane16_swap_b32_e32 v11, v13
	s_mov_b64 vcc, s[2:3]
	v_permlane16_swap_b32_e32 v6, v8
	v_permlane16_swap_b32_e32 v7, v9
	global_store_dwordx4 v[28:29], v[2:5], off sc1
	global_store_dwordx4 v[28:29], v[6:9], off offset:64 sc1
	v_permlane16_swap_b32_e32 v14, v16
	v_permlane16_swap_b32_e32 v15, v17
	global_store_dwordx4 v[38:39], v[10:13], off sc1
	global_store_dwordx4 v[38:39], v[14:17], off offset:64 sc1
	s_barrier
	s_cbranch_vccnz .LBB0_334
	s_add_i32 s42, s42, s88
	s_cmpk_gt_i32 s42, 0xff
	s_cbranch_scc0 .LBB0_323

; #define LAS __attribute__((address_space(3)))
;     __device__ __forceinline__ void operator()(f32x4 (&acc)[2][2][4][2], const Unit& u, const Order& S, int wr, int wc, int fr_, int fq_, LAS unsigned char* xl, int ui) const {
;     ...
;         for (int ai = 0; ai < 2; ++ai) {
;             const f32x4 ss4 = *(const LAS f32x4*)(cst + 1024 + trow0 + ai * HALF);
; #pragma unroll
;             for (int m = 0; m < 4; ++m) {
;                 const float sc = __builtin_amdgcn_rsqf(ss4[m] * (1.0f / DM) + EPS);
; #pragma unroll
;                 for (int bj = 0; bj < 2; ++bj)
; #pragma unroll
;                     for (int n = 0; n < 2; ++n) acc[ai][bj][m][n] *= sc;
;             }
;         }
;         LAS float* bnd = (LAS float*)xl;
;         const int tcol = wc * 32 + 4 * fq;
;         if (fr == 15) {
; #pragma unroll
;             for (int ai = 0; ai < 2; ++ai)
; #pragma unroll
;                 for (int bj = 0; bj < 2; ++bj)
; #pragma unroll
;                     for (int n = 0; n < 2; ++n) { *(LAS f32x4*)(bnd + ((2 * ai + wr) * 2 + 0) * 256 + bj * HALF + tcol + 16 * n) = acc[ai][bj][2][n]; *(LAS f32x4*)(bnd + ((2 * ai + wr) * 2 + 1) * 256 + bj * HALF + tcol + 16 * n) = acc[ai][bj][3][n]; }
;         }
;         { float* bq = bnd_g + (size_t)(u.pm * S.nN + u.pn) * 1024 + tcol;
;           if (wr == 0 && fr == 0) {
; #pragma unroll
;               for (int bj = 0; bj < 2; ++bj)
; #pragma unroll
;                   for (int n = 0; n < 2; ++n) { *(f32x4*)(bq + 0 * 256 + bj * HALF + 16 * n) = acc[0][bj][0][n]; *(f32x4*)(bq + 1 * 256 + bj * HALF + 16 * n) = acc[0][bj][1][n]; } }
;           if (wr == 1 && fr == 15) {
; #pragma unroll
;               for (int bj = 0; bj < 2; ++bj)
; #pragma unroll
;                   for (int n = 0; n < 2; ++n) { *(f32x4*)(bq + 2 * 256 + bj * HALF + 16 * n) = acc[1][bj][2][n]; *(f32x4*)(bq + 3 * 256 + bj * HALF + 16 * n) = acc[1][bj][3][n]; } } }
.LBB0_498:
	s_or_b64 exec, exec, s[2:3]
	v_fmamk_f32 v58, v150, 0x3a800000, v214
	v_rsq_f32_e32 v58, v58
	s_mul_i32 s2, s14, 22
	s_add_i32 s2, s2, s4
	s_ashr_i32 s3, s2, 31
	v_pk_mul_f32 v[160:161], v[120:121], v[58:59] op_sel_hi:[1,0]
	v_pk_mul_f32 v[158:159], v[118:119], v[58:59] op_sel_hi:[1,0]
	v_pk_mul_f32 v[64:65], v[116:117], v[58:59] op_sel_hi:[1,0]
	v_pk_mul_f32 v[62:63], v[114:115], v[58:59] op_sel_hi:[1,0]
	v_pk_mul_f32 v[164:165], v[104:105], v[58:59] op_sel_hi:[1,0]
	v_fmamk_f32 v59, v151, 0x3a800000, v214
	v_rsq_f32_e32 v104, v59
	s_lshl_b64 s[2:3], s[2:3], 12
	s_add_u32 s2, s60, s2
	s_addc_u32 s3, s61, s3
	v_ashrrev_i32_e32 v205, 31, v204
	v_pk_mul_f32 v[150:151], v[98:99], v[104:105] op_sel_hi:[1,0]
	v_lshl_add_u64 v[98:99], v[204:205], 2, s[2:3]
	v_cmp_eq_u32_e64 s[2:3], 0, v166
	v_pk_mul_f32 v[162:163], v[102:103], v[58:59] op_sel_hi:[1,0]
	v_pk_mul_f32 v[72:73], v[72:73], v[58:59] op_sel_hi:[1,0]
	v_pk_mul_f32 v[70:71], v[70:71], v[58:59] op_sel_hi:[1,0]
	v_pk_mul_f32 v[156:157], v[112:113], v[104:105] op_sel_hi:[1,0]
	v_pk_mul_f32 v[154:155], v[110:111], v[104:105] op_sel_hi:[1,0]
	v_pk_mul_f32 v[60:61], v[108:109], v[104:105] op_sel_hi:[1,0]
	v_pk_mul_f32 v[58:59], v[106:107], v[104:105] op_sel_hi:[1,0]
	v_pk_mul_f32 v[152:153], v[100:101], v[104:105] op_sel_hi:[1,0]
	v_pk_mul_f32 v[80:81], v[80:81], v[104:105] op_sel_hi:[1,0]
	v_pk_mul_f32 v[78:79], v[78:79], v[104:105] op_sel_hi:[1,0]
	s_and_b64 s[6:7], s[34:35], s[2:3]
	s_and_saveexec_b64 s[2:3], s[6:7]
	s_cbranch_execz .LBB0_500
	global_store_dwordx4 v[98:99], v[158:161], off sc1
	global_store_dwordx4 v[98:99], v[154:157], off offset:1024 sc1
	global_store_dwordx4 v[98:99], v[62:65], off offset:64 sc1
	global_store_dwordx4 v[98:99], v[58:61], off offset:1088 sc1
	global_store_dwordx4 v[98:99], v[162:165], off offset:512 sc1
	global_store_dwordx4 v[98:99], v[150:153], off offset:1536 sc1
	global_store_dwordx4 v[98:99], v[70:73], off offset:576 sc1
	global_store_dwordx4 v[98:99], v[78:81], off offset:1600 sc1
.LBB0_500:
	s_or_b64 exec, exec, s[2:3]
	s_and_b64 s[6:7], s[22:23], vcc
	s_and_saveexec_b64 s[2:3], s[6:7]
	s_cbranch_execz .LBB0_502
	global_store_dwordx4 v[98:99], v[86:89], off offset:2048 sc1
	global_store_dwordx4 v[98:99], v[94:97], off offset:3072 sc1
	global_store_dwordx4 v[98:99], v[18:21], off offset:2112 sc1
	global_store_dwordx4 v[98:99], v[30:33], off offset:3136 sc1
	global_store_dwordx4 v[98:99], v[82:85], off offset:2560 sc1
	global_store_dwordx4 v[98:99], v[90:93], off offset:3584 sc1
	global_store_dwordx4 v[98:99], v[22:25], off offset:2624 sc1
	global_store_dwordx4 v[98:99], v[26:29], off offset:3648 sc1

; #define LAS __attribute__((address_space(3)))
; template <bool CAUSAL, bool SHARED> ...
;     ...
;     const int kof0 = fr * 128 + (((0 + G) ^ (fr & 7)) << 4), kof1 = fr * 128 + (((4 + G) ^ (fr & 7)) << 4);
;     const int vrow = (4 * G + qq) * 128 + p * 8, sw = (2 * G + (qq >> 1)) & 3;
;     const h16x8 ones = {(_Float16)1.0f, (_Float16)1.0f, (_Float16)1.0f, (_Float16)1.0f, (_Float16)1.0f, (_Float16)1.0f, (_Float16)1.0f, (_Float16)1.0f};
;     const f32x4 nma = {-mba, -mba, -mba, -mba}, nmb = {-mbb, -mbb, -mbb, -mbb};
;     f32x4 la = {0.f, 0.f, 0.f, 0.f}, lb = la;
;     h16x8 ka[4], kb[4];
;     ka[0] = *(LAS const h16x8*)(Ka + kof0); ka[1] = *(LAS const h16x8*)(Ka + kof1); ka[2] = *(LAS const h16x8*)(Ka + 2048 + kof0); ka[3] = *(LAS const h16x8*)(Ka + 2048 + kof1);
;     if (!SHARED) { kb[0] = *(LAS const h16x8*)(Kb + kof0); kb[1] = *(LAS const h16x8*)(Kb + kof1); kb[2] = *(LAS const h16x8*)(Kb + 2048 + kof0); kb[3] = *(LAS const h16x8*)(Kb + 2048 + kof1); }
;     for (int ks = 0; ks < nsteps; ++ks) {
;         LAS const unsigned char* va = Va + ks * 4096 + vrow; LAS const unsigned char* vb = Vb + ks * 4096 + vrow;
;         h16x4 fal[4], fah[4], fbl[4], fbh[4];
; #pragma unroll
;         for (int dt = 0; dt < 4; ++dt) { fal[dt] = vtr(va + ((dt ^ sw) << 5)); fah[dt] = vtr(va + 2048 + ((dt ^ sw) << 5));
;             if (!SHARED) { fbl[dt] = vtr(vb + ((dt ^ sw) << 5)); fbh[dt] = vtr(vb + 2048 + ((dt ^ sw) << 5)); } }
;         __builtin_amdgcn_sched_barrier(0);
;         f32x4 sa0, sa1, sb0, sb1;
; __device__ __forceinline__ void moba_finish_q(h16x8 r0v, h16x8 r1v, float maxgk, h16x8& q0, h16x8& q1, float& mb) {
;     float q[16], n2 = 0.f;
; #pragma unroll
;     for (int j = 0; j < 8; ++j) { q[j] = (float)r0v[j]; q[8 + j] = (float)r1v[j]; n2 += q[j] * q[j] + q[8 + j] * q[8 + j]; }
;     n2 += __shfl_xor(n2, 16); n2 += __shfl_xor(n2, 32);
;     mb = (sqrtf(n2) * maxgk - BOUND_SHIFT) * LOG2E;
;     const float c = 0.125f * LOG2E;
;     u32x4 w0, w1;
;     w0.x = pkh(q[0] * c, q[1] * c); w0.y = pkh(q[2] * c, q[3] * c); w0.z = pkh(q[4] * c, q[5] * c); w0.w = pkh(q[6] * c, q[7] * c);
;     w1.x = pkh(q[8] * c, q[9] * c); w1.y = pkh(q[10] * c, q[11] * c); w1.z = pkh(q[12] * c, q[13] * c); w1.w = pkh(q[14] * c, q[15] * c);
;     q0 = __builtin_bit_cast(h16x8, w0); q1 = __builtin_bit_cast(h16x8, w1);
.LBB0_1149:
	v_pk_mul_f32 v[18:19], v[20:21], s[56:57] op_sel_hi:[1,0]
	v_pk_mul_f32 v[20:21], v[22:23], s[56:57] op_sel_hi:[1,0]
	v_cvt_pk_f16_f32 v18, v18, v19
	v_cvt_pk_f16_f32 v19, v20, v21
	v_pk_mul_f32 v[20:21], v[28:29], s[56:57] op_sel_hi:[1,0]
	v_pk_mul_f32 v[22:23], v[32:33], s[56:57] op_sel_hi:[1,0]
	v_cvt_pk_f16_f32 v20, v20, v21
	v_cvt_pk_f16_f32 v21, v22, v23
	v_pk_mul_f32 v[22:23], v[24:25], s[56:57] op_sel_hi:[1,0]
	v_pk_mul_f32 v[24:25], v[36:37], s[56:57] op_sel_hi:[1,0]
	v_cvt_pk_f16_f32 v22, v22, v23
	s_waitcnt lgkmcnt(1)
	v_add_f32_e32 v23, v119, v120
	v_mul_f32_e32 v28, 0x4f800000, v23
	v_cmp_gt_f32_e64 s[54:55], s22, v23
	v_pk_mul_f32 v[26:27], v[26:27], s[56:57] op_sel_hi:[1,0]
	v_pk_mul_f32 v[32:33], v[74:75], s[56:57] op_sel_hi:[1,0]
	v_cndmask_b32_e64 v28, v23, v28, s[54:55]
	v_sqrt_f32_e32 v29, v28
	v_cvt_pk_f16_f32 v23, v24, v25
	v_pk_mul_f32 v[24:25], v[30:31], s[56:57] op_sel_hi:[1,0]
	v_pk_mul_f32 v[34:35], v[34:35], s[56:57] op_sel_hi:[1,0]
	v_cvt_pk_f16_f32 v24, v24, v25
	v_add_u32_e32 v25, -1, v29
	v_fma_f32 v30, -v25, v29, v28
	v_cmp_ge_f32_e32 vcc, 0, v30
	v_add_u32_e32 v30, 1, v29
	v_add_u32_e32 v46, v109, v81
	v_cndmask_b32_e32 v25, v29, v25, vcc
	v_fma_f32 v29, -v30, v29, v28
	v_cmp_lt_f32_e32 vcc, 0, v29
	s_cmp_eq_u32 s69, 0
	s_cselect_b32 s41, s31, s35
	v_cndmask_b32_e32 v25, v25, v30, vcc
	v_mul_f32_e32 v29, 0x37800000, v25
	v_cndmask_b32_e64 v25, v25, v29, s[54:55]
	v_cmp_class_f32_e32 vcc, v28, v101
	v_pk_mul_f32 v[30:31], v[72:73], s[56:57] op_sel_hi:[1,0]
	v_cmp_gt_i32_e64 s[52:53], s41, v1
	v_cndmask_b32_e32 v25, v25, v28, vcc
	v_fma_f32 v36, v92, v25, -4.0
	v_cvt_pk_f16_f32 v25, v26, v27
	v_pk_mul_f32 v[26:27], v[38:39], s[56:57] op_sel_hi:[1,0]
	v_pk_mul_f32 v[28:29], v[40:41], s[56:57] op_sel_hi:[1,0]
	v_cvt_pk_f16_f32 v26, v26, v27
	v_cvt_pk_f16_f32 v27, v28, v29
	v_pk_mul_f32 v[28:29], v[44:45], s[56:57] op_sel_hi:[1,0]
	s_nop 0
	v_cvt_pk_f16_f32 v28, v28, v29
	v_cvt_pk_f16_f32 v29, v30, v31
	v_pk_mul_f32 v[30:31], v[42:43], s[56:57] op_sel_hi:[1,0]
	s_nop 0
	v_cvt_pk_f16_f32 v30, v30, v31
	s_waitcnt lgkmcnt(0)
	v_add_f32_e32 v31, v117, v118
	v_mul_f32_e32 v37, 0x4f800000, v31
	v_cmp_gt_f32_e32 vcc, s22, v31
	s_nop 1
	v_cndmask_b32_e32 v37, v31, v37, vcc
	v_sqrt_f32_e32 v38, v37
	v_cvt_pk_f16_f32 v31, v32, v33
	v_pk_mul_f32 v[32:33], v[70:71], s[56:57] op_sel_hi:[1,0]
	s_nop 0
	v_cvt_pk_f16_f32 v32, v32, v33
	v_add_u32_e32 v33, -1, v38
	v_fma_f32 v39, -v33, v38, v37
	v_cmp_ge_f32_e64 s[54:55], 0, v39
	v_add_u32_e32 v39, 1, v38
	s_nop 0
	v_cndmask_b32_e64 v33, v38, v33, s[54:55]
	v_fma_f32 v38, -v39, v38, v37
	v_cmp_lt_f32_e64 s[54:55], 0, v38
	s_nop 1
	v_cndmask_b32_e64 v33, v33, v39, s[54:55]
	v_mul_f32_e32 v38, 0x37800000, v33
	v_cndmask_b32_e32 v33, v33, v38, vcc
	v_cmp_class_f32_e32 vcc, v37, v101
	v_mul_f32_e32 v38, 0xbfb8aa3b, v36
	v_mov_b32_e32 v39, v38
	v_cndmask_b32_e32 v33, v33, v37, vcc
	v_fma_f32 v42, v92, v33, -4.0
	v_cvt_pk_f16_f32 v33, v34, v35
	ds_read_b128 v[34:37], v110
	ds_read_b128 v[70:73], v110 offset:2048
	ds_read_b128 v[118:121], v111
	ds_read_b128 v[122:125], v111 offset:2048
	ds_read_b64_tr_b16 v[126:127], v46 offset:32768
	ds_read_b64_tr_b16 v[128:129], v46 offset:34816
	ds_read_b64_tr_b16 v[130:131], v112 offset:32768
	ds_read_b64_tr_b16 v[132:133], v112 offset:34816
	ds_read_b64_tr_b16 v[134:135], v113 offset:32768
	ds_read_b64_tr_b16 v[136:137], v113 offset:34816
	ds_read_b64_tr_b16 v[138:139], v114 offset:32768
	ds_read_b64_tr_b16 v[140:141], v114 offset:34816
	v_mul_f32_e32 v42, 0xbfb8aa3b, v42
	v_mov_b32_e32 v40, v38
	v_mov_b32_e32 v41, v38
	v_mov_b32_e32 v43, v42
	v_mov_b32_e32 v44, v42
	v_mov_b32_e32 v45, v42
	s_waitcnt lgkmcnt(11)
	v_mfma_f32_16x16x32_f16 v[142:145], v[34:37], v[18:21], v[38:41]
	v_mfma_f32_16x16x32_f16 v[34:37], v[34:37], v[26:29], v[42:45]
	s_waitcnt lgkmcnt(10)
	v_mfma_f32_16x16x32_f16 v[146:149], v[70:73], v[18:21], v[38:41]
	v_mfma_f32_16x16x32_f16 v[70:73], v[70:73], v[26:29], v[42:45]
	s_waitcnt lgkmcnt(9)
	v_mfma_f32_16x16x32_f16 v[34:37], v[118:121], v[30:33], v[34:37]
	v_mfma_f32_16x16x32_f16 v[142:145], v[118:121], v[22:25], v[142:145]
	s_waitcnt lgkmcnt(8)
	v_mfma_f32_16x16x32_f16 v[118:121], v[122:125], v[22:25], v[146:149]
	v_mfma_f32_16x16x32_f16 v[70:73], v[122:125], v[30:33], v[70:73]
	ds_read_b128 v[122:125], v111 offset:6144
	s_nop 0
	ds_read_b128 v[146:149], v111 offset:4096
	ds_read_b128 v[150:153], v110 offset:6144
	ds_read_b128 v[154:157], v110 offset:4096
	ds_read_b64_tr_b16 v[170:171], v46 offset:36864
	ds_read_b64_tr_b16 v[172:173], v46 offset:38912
	ds_read_b64_tr_b16 v[174:175], v112 offset:36864
	ds_read_b64_tr_b16 v[176:177], v112 offset:38912
	ds_read_b64_tr_b16 v[178:179], v113 offset:36864
	ds_read_b64_tr_b16 v[180:181], v113 offset:38912
	ds_read_b64_tr_b16 v[182:183], v114 offset:36864
	ds_read_b64_tr_b16 v[184:185], v114 offset:38912
	v_exp_f32_e32 v74, v142
	v_exp_f32_e32 v75, v118
	v_exp_f32_e32 v34, v34
	v_exp_f32_e32 v117, v70
	v_exp_f32_e32 v70, v143
	v_exp_f32_e32 v118, v119
	v_exp_f32_e32 v35, v35
	v_exp_f32_e32 v142, v71
	v_exp_f32_e32 v71, v144
	v_exp_f32_e32 v119, v120
	v_exp_f32_e32 v36, v36
	v_exp_f32_e32 v143, v72
	v_exp_f32_e32 v72, v145
	v_exp_f32_e32 v120, v121
	v_exp_f32_e32 v37, v37
	s_mov_b32 s69, s68
	v_exp_f32_e32 v121, v73
	v_cvt_pk_f16_f32 v71, v71, v72
	v_cvt_pk_f16_f32 v72, v75, v118
	v_cvt_pk_f16_f32 v73, v119, v120
	v_cvt_pk_f16_f32 v118, v34, v35
	v_cvt_pk_f16_f32 v119, v36, v37
	s_mov_b32 s70, s68
	s_mov_b32 s71, s68
	v_mov_b64_e32 v[34:35], s[68:69]
	v_mov_b64_e32 v[36:37], s[70:71]
	v_cvt_pk_f16_f32 v70, v74, v70
	v_cvt_pk_f16_f32 v120, v117, v142
	v_cvt_pk_f16_f32 v121, v143, v121
	v_mfma_f32_16x16x32_f16 v[142:145], v[34:37], v[70:73], 0
	s_waitcnt lgkmcnt(14)
; #define LAS __attribute__((address_space(3)))
; template <bool CAUSAL, bool SHARED> ...
;     ...
;     for (int ks = 0; ks < nsteps; ++ks) {
;         LAS const unsigned char* va = Va + ks * 4096 + vrow; LAS const unsigned char* vb = Vb + ks * 4096 + vrow;
;         h16x4 fal[4], fah[4], fbl[4], fbh[4];
; #pragma unroll
;         for (int dt = 0; dt < 4; ++dt) { fal[dt] = vtr(va + ((dt ^ sw) << 5)); fah[dt] = vtr(va + 2048 + ((dt ^ sw) << 5));
;             if (!SHARED) { fbl[dt] = vtr(vb + ((dt ^ sw) << 5)); fbh[dt] = vtr(vb + 2048 + ((dt ^ sw) << 5)); } }
;         __builtin_amdgcn_sched_barrier(0);
;         f32x4 sa0, sa1, sb0, sb1;
;         sa0 = __builtin_amdgcn_mfma_f32_16x16x32_f16(ka[0], qa0, nma, 0, 0, 0); sb0 = __builtin_amdgcn_mfma_f32_16x16x32_f16(SHARED ? ka[0] : kb[0], qb0, nmb, 0, 0, 0);
;         sa1 = __builtin_amdgcn_mfma_f32_16x16x32_f16(ka[2], qa0, nma, 0, 0, 0); sb1 = __builtin_amdgcn_mfma_f32_16x16x32_f16(SHARED ? ka[2] : kb[2], qb0, nmb, 0, 0, 0);
;         sa0 = __builtin_amdgcn_mfma_f32_16x16x32_f16(ka[1], qa1, sa0, 0, 0, 0); sb0 = __builtin_amdgcn_mfma_f32_16x16x32_f16(SHARED ? ka[1] : kb[1], qb1, sb0, 0, 0, 0);
;         sa1 = __builtin_amdgcn_mfma_f32_16x16x32_f16(ka[3], qa1, sa1, 0, 0, 0); sb1 = __builtin_amdgcn_mfma_f32_16x16x32_f16(SHARED ? ka[3] : kb[3], qb1, sb1, 0, 0, 0);
;         __builtin_amdgcn_sched_barrier(0);
;         if (ks + 1 < nsteps) { LAS const unsigned char* kn = Ka + (ks + 1) * 4096;
;             ka[0] = *(LAS const h16x8*)(kn + kof0); ka[1] = *(LAS const h16x8*)(kn + kof1); ka[2] = *(LAS const h16x8*)(kn + 2048 + kof0); ka[3] = *(LAS const h16x8*)(kn + 2048 + kof1);
;             if (!SHARED) { LAS const unsigned char* kn2 = Kb + (ks + 1) * 4096;
;                 kb[0] = *(LAS const h16x8*)(kn2 + kof0); kb[1] = *(LAS const h16x8*)(kn2 + kof1); kb[2] = *(LAS const h16x8*)(kn2 + 2048 + kof0); kb[3] = *(LAS const h16x8*)(kn2 + 2048 + kof1); } }
;         __builtin_amdgcn_sched_barrier(0);
;         f32x4 pa0, pa1, pb0, pb1;
; #pragma unroll
;         for (int e = 0; e < 4; ++e) { pa0[e] = __builtin_amdgcn_exp2f(sa0[e]); pa1[e] = __builtin_amdgcn_exp2f(sa1[e]);
;                                       pb0[e] = __builtin_amdgcn_exp2f(sb0[e]); pb1[e] = __builtin_amdgcn_exp2f(sb1[e]); }
;         if (CAUSAL) { const int kr = ks * 32 + 4 * G;
; #pragma unroll
	v_mfma_f32_16x16x32_f16 v[158:161], v[126:129], v[70:73], 0
	v_mfma_f32_16x16x32_f16 v[126:129], v[126:129], v[118:121], 0
	v_mfma_f32_16x16x32_f16 v[162:165], v[130:133], v[70:73], 0
	v_mfma_f32_16x16x32_f16 v[130:133], v[130:133], v[118:121], 0
	v_mfma_f32_16x16x32_f16 v[166:169], v[134:137], v[70:73], 0
	v_mfma_f32_16x16x32_f16 v[134:137], v[134:137], v[118:121], 0
	s_waitcnt lgkmcnt(12)
	v_mfma_f32_16x16x32_f16 v[70:73], v[138:141], v[70:73], 0
	v_mfma_f32_16x16x32_f16 v[138:141], v[138:141], v[118:121], 0
	v_mfma_f32_16x16x32_f16 v[118:121], v[34:37], v[118:121], 0
	s_waitcnt lgkmcnt(8)
	v_mfma_f32_16x16x32_f16 v[186:189], v[154:157], v[18:21], v[38:41]
	v_mfma_f32_16x16x32_f16 v[154:157], v[154:157], v[26:29], v[42:45]
	v_mfma_f32_16x16x32_f16 v[190:193], v[150:153], v[18:21], v[38:41]
	v_mfma_f32_16x16x32_f16 v[150:153], v[150:153], v[26:29], v[42:45]
	v_mfma_f32_16x16x32_f16 v[186:189], v[146:149], v[22:25], v[186:189]
	v_mfma_f32_16x16x32_f16 v[146:149], v[146:149], v[30:33], v[154:157]
	v_mfma_f32_16x16x32_f16 v[154:157], v[122:125], v[22:25], v[190:193]
	v_mfma_f32_16x16x32_f16 v[122:125], v[122:125], v[30:33], v[150:153]
	s_nop 3
	ds_read_b128 v[150:153], v111 offset:10240
	ds_read_b128 v[190:193], v111 offset:8192
	ds_read_b128 v[194:197], v110 offset:10240
	ds_read_b128 v[198:201], v110 offset:8192
	v_exp_f32_e32 v74, v186
	v_exp_f32_e32 v75, v154
	v_exp_f32_e32 v117, v146
	v_exp_f32_e32 v186, v122
	v_exp_f32_e32 v122, v187
	v_exp_f32_e32 v146, v155
	v_exp_f32_e32 v147, v147
	v_exp_f32_e32 v187, v123
	v_exp_f32_e32 v123, v188
	v_exp_f32_e32 v188, v156
	v_exp_f32_e32 v202, v148
	v_exp_f32_e32 v148, v189
	v_exp_f32_e32 v189, v124
	v_exp_f32_e32 v124, v157
	v_cvt_pk_f16_f32 v154, v74, v122
	v_cvt_pk_f16_f32 v156, v75, v146
	v_exp_f32_e32 v74, v149
	v_exp_f32_e32 v75, v125
	v_cvt_pk_f16_f32 v155, v123, v148
	v_cvt_pk_f16_f32 v157, v188, v124
	v_cvt_pk_f16_f32 v122, v117, v147
	v_cvt_pk_f16_f32 v123, v202, v74
	v_cvt_pk_f16_f32 v124, v186, v187
	v_cvt_pk_f16_f32 v125, v189, v75
	v_mfma_f32_16x16x32_f16 v[142:145], v[34:37], v[154:157], v[142:145]
	s_waitcnt lgkmcnt(10)
	v_mfma_f32_16x16x32_f16 v[146:149], v[170:173], v[154:157], v[158:161]
	v_mfma_f32_16x16x32_f16 v[126:129], v[170:173], v[122:125], v[126:129]
	s_waitcnt lgkmcnt(8)
	v_mfma_f32_16x16x32_f16 v[158:161], v[174:177], v[154:157], v[162:165]
	v_mfma_f32_16x16x32_f16 v[130:133], v[174:177], v[122:125], v[130:133]
	s_waitcnt lgkmcnt(6)
	v_mfma_f32_16x16x32_f16 v[162:165], v[178:181], v[154:157], v[166:169]
	s_waitcnt lgkmcnt(4)
	v_mfma_f32_16x16x32_f16 v[70:73], v[182:185], v[154:157], v[70:73]
	ds_read_b64_tr_b16 v[154:155], v46 offset:40960
	ds_read_b64_tr_b16 v[156:157], v46 offset:43008
	ds_read_b64_tr_b16 v[166:167], v112 offset:40960
	ds_read_b64_tr_b16 v[168:169], v112 offset:43008
	ds_read_b64_tr_b16 v[170:171], v113 offset:40960
	ds_read_b64_tr_b16 v[172:173], v113 offset:43008
	ds_read_b64_tr_b16 v[174:175], v114 offset:40960
	ds_read_b64_tr_b16 v[176:177], v114 offset:43008
	v_mfma_f32_16x16x32_f16 v[134:137], v[178:181], v[122:125], v[134:137]
	v_mfma_f32_16x16x32_f16 v[138:141], v[182:185], v[122:125], v[138:141]
	v_mfma_f32_16x16x32_f16 v[118:121], v[34:37], v[122:125], v[118:121]
	s_waitcnt lgkmcnt(8)
	v_mfma_f32_16x16x32_f16 v[122:125], v[198:201], v[18:21], v[38:41]
	v_mfma_f32_16x16x32_f16 v[178:181], v[198:201], v[26:29], v[42:45]
	v_mfma_f32_16x16x32_f16 v[182:185], v[194:197], v[18:21], v[38:41]
	v_mfma_f32_16x16x32_f16 v[186:189], v[194:197], v[26:29], v[42:45]
	v_mfma_f32_16x16x32_f16 v[122:125], v[190:193], v[22:25], v[122:125]
	v_mfma_f32_16x16x32_f16 v[178:181], v[190:193], v[30:33], v[178:181]
	v_mfma_f32_16x16x32_f16 v[182:185], v[150:153], v[22:25], v[182:185]
	v_mfma_f32_16x16x32_f16 v[150:153], v[150:153], v[30:33], v[186:189]
	s_nop 3
	ds_read_b128 v[186:189], v111 offset:14336
	ds_read_b128 v[190:193], v111 offset:12288
	ds_read_b128 v[194:197], v110 offset:14336
	ds_read_b128 v[198:201], v110 offset:12288
	v_exp_f32_e32 v74, v122
	v_exp_f32_e32 v75, v182
	v_exp_f32_e32 v117, v178
	v_exp_f32_e32 v178, v150
	v_exp_f32_e32 v122, v123
	v_exp_f32_e32 v150, v183
	v_exp_f32_e32 v123, v124
	v_exp_f32_e32 v124, v125
	v_exp_f32_e32 v179, v179
	v_exp_f32_e32 v182, v151
	v_exp_f32_e32 v151, v184
	v_exp_f32_e32 v180, v180
	v_exp_f32_e32 v183, v152
	v_exp_f32_e32 v125, v185
	v_cvt_pk_f16_f32 v122, v74, v122
	v_cvt_pk_f16_f32 v123, v123, v124
	v_cvt_pk_f16_f32 v124, v75, v150
	v_exp_f32_e32 v74, v181
	v_exp_f32_e32 v75, v153
	v_cvt_pk_f16_f32 v125, v151, v125
	v_cvt_pk_f16_f32 v150, v117, v179
	v_cvt_pk_f16_f32 v151, v180, v74
	v_cvt_pk_f16_f32 v152, v178, v182
	v_cvt_pk_f16_f32 v153, v183, v75
	v_mfma_f32_16x16x32_f16 v[142:145], v[34:37], v[122:125], v[142:145]
	s_waitcnt lgkmcnt(10)
	v_mfma_f32_16x16x32_f16 v[146:149], v[154:157], v[122:125], v[146:149]
	v_mfma_f32_16x16x32_f16 v[126:129], v[154:157], v[150:153], v[126:129]
	s_waitcnt lgkmcnt(8)
	v_mfma_f32_16x16x32_f16 v[154:157], v[166:169], v[122:125], v[158:161]
	v_mfma_f32_16x16x32_f16 v[130:133], v[166:169], v[150:153], v[130:133]
	s_waitcnt lgkmcnt(6)
	v_mfma_f32_16x16x32_f16 v[158:161], v[170:173], v[122:125], v[162:165]
	v_mfma_f32_16x16x32_f16 v[134:137], v[170:173], v[150:153], v[134:137]
	s_waitcnt lgkmcnt(4)
	v_mfma_f32_16x16x32_f16 v[70:73], v[174:177], v[122:125], v[70:73]
	v_mfma_f32_16x16x32_f16 v[122:125], v[174:177], v[150:153], v[138:141]
	s_nop 2
	ds_read_b64_tr_b16 v[138:139], v46 offset:45056
	ds_read_b64_tr_b16 v[140:141], v46 offset:47104
	ds_read_b64_tr_b16 v[162:163], v112 offset:45056
	ds_read_b64_tr_b16 v[164:165], v112 offset:47104
	ds_read_b64_tr_b16 v[166:167], v113 offset:45056
	ds_read_b64_tr_b16 v[168:169], v113 offset:47104
	ds_read_b64_tr_b16 v[170:171], v114 offset:45056
	ds_read_b64_tr_b16 v[172:173], v114 offset:47104
	v_mfma_f32_16x16x32_f16 v[118:121], v[34:37], v[150:153], v[118:121]
	s_waitcnt lgkmcnt(8)
; #define LAS __attribute__((address_space(3)))
; template <bool CAUSAL, bool SHARED> ...
;     ...
;     for (int ks = 0; ks < nsteps; ++ks) {
;         LAS const unsigned char* va = Va + ks * 4096 + vrow; LAS const unsigned char* vb = Vb + ks * 4096 + vrow;
;         h16x4 fal[4], fah[4], fbl[4], fbh[4];
; #pragma unroll
;         for (int dt = 0; dt < 4; ++dt) { fal[dt] = vtr(va + ((dt ^ sw) << 5)); fah[dt] = vtr(va + 2048 + ((dt ^ sw) << 5));
;             if (!SHARED) { fbl[dt] = vtr(vb + ((dt ^ sw) << 5)); fbh[dt] = vtr(vb + 2048 + ((dt ^ sw) << 5)); } }
;         __builtin_amdgcn_sched_barrier(0);
;         f32x4 sa0, sa1, sb0, sb1;
;         sa0 = __builtin_amdgcn_mfma_f32_16x16x32_f16(ka[0], qa0, nma, 0, 0, 0); sb0 = __builtin_amdgcn_mfma_f32_16x16x32_f16(SHARED ? ka[0] : kb[0], qb0, nmb, 0, 0, 0);
;         sa1 = __builtin_amdgcn_mfma_f32_16x16x32_f16(ka[2], qa0, nma, 0, 0, 0); sb1 = __builtin_amdgcn_mfma_f32_16x16x32_f16(SHARED ? ka[2] : kb[2], qb0, nmb, 0, 0, 0);
;         sa0 = __builtin_amdgcn_mfma_f32_16x16x32_f16(ka[1], qa1, sa0, 0, 0, 0); sb0 = __builtin_amdgcn_mfma_f32_16x16x32_f16(SHARED ? ka[1] : kb[1], qb1, sb0, 0, 0, 0);
;         sa1 = __builtin_amdgcn_mfma_f32_16x16x32_f16(ka[3], qa1, sa1, 0, 0, 0); sb1 = __builtin_amdgcn_mfma_f32_16x16x32_f16(SHARED ? ka[3] : kb[3], qb1, sb1, 0, 0, 0);
;         __builtin_amdgcn_sched_barrier(0);
;         if (ks + 1 < nsteps) { LAS const unsigned char* kn = Ka + (ks + 1) * 4096;
;             ka[0] = *(LAS const h16x8*)(kn + kof0); ka[1] = *(LAS const h16x8*)(kn + kof1); ka[2] = *(LAS const h16x8*)(kn + 2048 + kof0); ka[3] = *(LAS const h16x8*)(kn + 2048 + kof1);
;             if (!SHARED) { LAS const unsigned char* kn2 = Kb + (ks + 1) * 4096;
;                 kb[0] = *(LAS const h16x8*)(kn2 + kof0); kb[1] = *(LAS const h16x8*)(kn2 + kof1); kb[2] = *(LAS const h16x8*)(kn2 + 2048 + kof0); kb[3] = *(LAS const h16x8*)(kn2 + 2048 + kof1); } }
;         __builtin_amdgcn_sched_barrier(0);
;         f32x4 pa0, pa1, pb0, pb1;
; #pragma unroll
;         for (int e = 0; e < 4; ++e) { pa0[e] = __builtin_amdgcn_exp2f(sa0[e]); pa1[e] = __builtin_amdgcn_exp2f(sa1[e]);
;                                       pb0[e] = __builtin_amdgcn_exp2f(sb0[e]); pb1[e] = __builtin_amdgcn_exp2f(sb1[e]); }
;         if (CAUSAL) { const int kr = ks * 32 + 4 * G;
; #pragma unroll
	v_mfma_f32_16x16x32_f16 v[150:153], v[198:201], v[18:21], v[38:41]
	v_mfma_f32_16x16x32_f16 v[174:177], v[198:201], v[26:29], v[42:45]
	v_mfma_f32_16x16x32_f16 v[178:181], v[194:197], v[18:21], v[38:41]
	v_mfma_f32_16x16x32_f16 v[182:185], v[194:197], v[26:29], v[42:45]
	v_mfma_f32_16x16x32_f16 v[150:153], v[190:193], v[22:25], v[150:153]
	v_mfma_f32_16x16x32_f16 v[174:177], v[190:193], v[30:33], v[174:177]
	v_mfma_f32_16x16x32_f16 v[178:181], v[186:189], v[22:25], v[178:181]
	v_mfma_f32_16x16x32_f16 v[182:185], v[186:189], v[30:33], v[182:185]
	ds_read_b128 v[186:189], v111 offset:18432
	ds_read_b128 v[190:193], v111 offset:16384
	ds_read_b128 v[194:197], v110 offset:18432
	ds_read_b128 v[198:201], v110 offset:16384
	s_nop 0
	v_exp_f32_e32 v74, v150
	s_nop 0
	v_exp_f32_e32 v75, v178
	v_exp_f32_e32 v117, v174
	v_exp_f32_e32 v150, v151
	v_exp_f32_e32 v174, v179
	v_exp_f32_e32 v151, v152
	v_exp_f32_e32 v152, v153
	v_exp_f32_e32 v178, v182
	v_exp_f32_e32 v175, v175
	v_exp_f32_e32 v179, v183
	v_exp_f32_e32 v180, v180
	v_exp_f32_e32 v176, v176
	v_exp_f32_e32 v182, v184
	v_exp_f32_e32 v153, v181
	v_cvt_pk_f16_f32 v150, v74, v150
	v_cvt_pk_f16_f32 v151, v151, v152
	v_cvt_pk_f16_f32 v152, v75, v174
	v_exp_f32_e32 v74, v177
	v_exp_f32_e32 v75, v185
	v_cvt_pk_f16_f32 v153, v180, v153
	v_cvt_pk_f16_f32 v174, v117, v175
	v_cvt_pk_f16_f32 v175, v176, v74
	v_cvt_pk_f16_f32 v176, v178, v179
	v_cvt_pk_f16_f32 v177, v182, v75
	v_mfma_f32_16x16x32_f16 v[142:145], v[34:37], v[150:153], v[142:145]
	s_waitcnt lgkmcnt(10)
	v_mfma_f32_16x16x32_f16 v[146:149], v[138:141], v[150:153], v[146:149]
	v_mfma_f32_16x16x32_f16 v[126:129], v[138:141], v[174:177], v[126:129]
	s_waitcnt lgkmcnt(8)
	v_mfma_f32_16x16x32_f16 v[138:141], v[162:165], v[150:153], v[154:157]
	v_mfma_f32_16x16x32_f16 v[130:133], v[162:165], v[174:177], v[130:133]
	s_waitcnt lgkmcnt(6)
	v_mfma_f32_16x16x32_f16 v[154:157], v[166:169], v[150:153], v[158:161]
	v_mfma_f32_16x16x32_f16 v[134:137], v[166:169], v[174:177], v[134:137]
	s_waitcnt lgkmcnt(4)
	v_mfma_f32_16x16x32_f16 v[70:73], v[170:173], v[150:153], v[70:73]
	ds_read_b64_tr_b16 v[150:151], v46 offset:49152
	ds_read_b64_tr_b16 v[152:153], v46 offset:51200
	ds_read_b64_tr_b16 v[158:159], v112 offset:49152
	ds_read_b64_tr_b16 v[160:161], v112 offset:51200
	ds_read_b64_tr_b16 v[162:163], v113 offset:49152
	ds_read_b64_tr_b16 v[164:165], v113 offset:51200
	ds_read_b64_tr_b16 v[166:167], v114 offset:49152
	ds_read_b64_tr_b16 v[168:169], v114 offset:51200
	v_mfma_f32_16x16x32_f16 v[122:125], v[170:173], v[174:177], v[122:125]
	v_mfma_f32_16x16x32_f16 v[118:121], v[34:37], v[174:177], v[118:121]
	s_waitcnt lgkmcnt(8)
	v_mfma_f32_16x16x32_f16 v[170:173], v[198:201], v[18:21], v[38:41]
	v_mfma_f32_16x16x32_f16 v[174:177], v[198:201], v[26:29], v[42:45]
	v_mfma_f32_16x16x32_f16 v[178:181], v[194:197], v[18:21], v[38:41]
	v_mfma_f32_16x16x32_f16 v[182:185], v[194:197], v[26:29], v[42:45]
	v_mfma_f32_16x16x32_f16 v[170:173], v[190:193], v[22:25], v[170:173]
	v_mfma_f32_16x16x32_f16 v[174:177], v[190:193], v[30:33], v[174:177]
	v_mfma_f32_16x16x32_f16 v[178:181], v[186:189], v[22:25], v[178:181]
	v_mfma_f32_16x16x32_f16 v[182:185], v[186:189], v[30:33], v[182:185]
	ds_read_b128 v[186:189], v111 offset:22528
	ds_read_b128 v[190:193], v111 offset:20480
	ds_read_b128 v[194:197], v110 offset:22528
	ds_read_b128 v[198:201], v110 offset:20480
	s_nop 0
	v_exp_f32_e32 v74, v170
	s_nop 0
	v_exp_f32_e32 v75, v178
	v_exp_f32_e32 v117, v174
	v_exp_f32_e32 v170, v171
	v_exp_f32_e32 v174, v179
	v_exp_f32_e32 v171, v172
	v_exp_f32_e32 v172, v173
	v_exp_f32_e32 v178, v182
	v_exp_f32_e32 v175, v175
	v_exp_f32_e32 v179, v183
	v_exp_f32_e32 v180, v180
	v_exp_f32_e32 v176, v176
	v_exp_f32_e32 v182, v184
	v_exp_f32_e32 v173, v181
	v_cvt_pk_f16_f32 v170, v74, v170
	v_cvt_pk_f16_f32 v171, v171, v172
	v_cvt_pk_f16_f32 v172, v75, v174
	v_exp_f32_e32 v74, v177
	v_exp_f32_e32 v75, v185
	v_cvt_pk_f16_f32 v173, v180, v173
	v_cvt_pk_f16_f32 v174, v117, v175
	v_cvt_pk_f16_f32 v175, v176, v74
	v_cvt_pk_f16_f32 v176, v178, v179
	v_cvt_pk_f16_f32 v177, v182, v75
	s_waitcnt lgkmcnt(10)
	v_mfma_f32_16x16x32_f16 v[146:149], v[150:153], v[170:173], v[146:149]
	v_mfma_f32_16x16x32_f16 v[126:129], v[150:153], v[174:177], v[126:129]
	s_waitcnt lgkmcnt(8)
	v_mfma_f32_16x16x32_f16 v[138:141], v[158:161], v[170:173], v[138:141]
	v_mfma_f32_16x16x32_f16 v[130:133], v[158:161], v[174:177], v[130:133]
	s_waitcnt lgkmcnt(6)
	v_mfma_f32_16x16x32_f16 v[150:153], v[162:165], v[170:173], v[154:157]
	v_mfma_f32_16x16x32_f16 v[134:137], v[162:165], v[174:177], v[134:137]
	s_waitcnt lgkmcnt(4)
	v_mfma_f32_16x16x32_f16 v[70:73], v[166:169], v[170:173], v[70:73]
	v_mfma_f32_16x16x32_f16 v[122:125], v[166:169], v[174:177], v[122:125]
	ds_read_b64_tr_b16 v[154:155], v46 offset:53248
	ds_read_b64_tr_b16 v[156:157], v46 offset:55296
	ds_read_b64_tr_b16 v[158:159], v112 offset:53248
	ds_read_b64_tr_b16 v[160:161], v112 offset:55296
	ds_read_b64_tr_b16 v[162:163], v113 offset:53248
	ds_read_b64_tr_b16 v[164:165], v113 offset:55296
	ds_read_b64_tr_b16 v[166:167], v114 offset:53248
	ds_read_b64_tr_b16 v[168:169], v114 offset:55296
	v_mfma_f32_16x16x32_f16 v[142:145], v[34:37], v[170:173], v[142:145]
	v_mfma_f32_16x16x32_f16 v[118:121], v[34:37], v[174:177], v[118:121]
	s_waitcnt lgkmcnt(8)
; #define LAS __attribute__((address_space(3)))
; template <bool CAUSAL, bool SHARED> ...
;     ...
;     for (int ks = 0; ks < nsteps; ++ks) {
;         LAS const unsigned char* va = Va + ks * 4096 + vrow; LAS const unsigned char* vb = Vb + ks * 4096 + vrow;
;         h16x4 fal[4], fah[4], fbl[4], fbh[4];
; #pragma unroll
;         for (int dt = 0; dt < 4; ++dt) { fal[dt] = vtr(va + ((dt ^ sw) << 5)); fah[dt] = vtr(va + 2048 + ((dt ^ sw) << 5));
;             if (!SHARED) { fbl[dt] = vtr(vb + ((dt ^ sw) << 5)); fbh[dt] = vtr(vb + 2048 + ((dt ^ sw) << 5)); } }
;         __builtin_amdgcn_sched_barrier(0);
;         f32x4 sa0, sa1, sb0, sb1;
;         sa0 = __builtin_amdgcn_mfma_f32_16x16x32_f16(ka[0], qa0, nma, 0, 0, 0); sb0 = __builtin_amdgcn_mfma_f32_16x16x32_f16(SHARED ? ka[0] : kb[0], qb0, nmb, 0, 0, 0);
;         sa1 = __builtin_amdgcn_mfma_f32_16x16x32_f16(ka[2], qa0, nma, 0, 0, 0); sb1 = __builtin_amdgcn_mfma_f32_16x16x32_f16(SHARED ? ka[2] : kb[2], qb0, nmb, 0, 0, 0);
;         sa0 = __builtin_amdgcn_mfma_f32_16x16x32_f16(ka[1], qa1, sa0, 0, 0, 0); sb0 = __builtin_amdgcn_mfma_f32_16x16x32_f16(SHARED ? ka[1] : kb[1], qb1, sb0, 0, 0, 0);
;         sa1 = __builtin_amdgcn_mfma_f32_16x16x32_f16(ka[3], qa1, sa1, 0, 0, 0); sb1 = __builtin_amdgcn_mfma_f32_16x16x32_f16(SHARED ? ka[3] : kb[3], qb1, sb1, 0, 0, 0);
;         __builtin_amdgcn_sched_barrier(0);
;         if (ks + 1 < nsteps) { LAS const unsigned char* kn = Ka + (ks + 1) * 4096;
;             ka[0] = *(LAS const h16x8*)(kn + kof0); ka[1] = *(LAS const h16x8*)(kn + kof1); ka[2] = *(LAS const h16x8*)(kn + 2048 + kof0); ka[3] = *(LAS const h16x8*)(kn + 2048 + kof1);
;             if (!SHARED) { LAS const unsigned char* kn2 = Kb + (ks + 1) * 4096;
;                 kb[0] = *(LAS const h16x8*)(kn2 + kof0); kb[1] = *(LAS const h16x8*)(kn2 + kof1); kb[2] = *(LAS const h16x8*)(kn2 + 2048 + kof0); kb[3] = *(LAS const h16x8*)(kn2 + 2048 + kof1); } }
;         __builtin_amdgcn_sched_barrier(0);
;         f32x4 pa0, pa1, pb0, pb1;
; #pragma unroll
;         for (int e = 0; e < 4; ++e) { pa0[e] = __builtin_amdgcn_exp2f(sa0[e]); pa1[e] = __builtin_amdgcn_exp2f(sa1[e]);
;                                       pb0[e] = __builtin_amdgcn_exp2f(sb0[e]); pb1[e] = __builtin_amdgcn_exp2f(sb1[e]); }
;         if (CAUSAL) { const int kr = ks * 32 + 4 * G;
; #pragma unroll
	v_mfma_f32_16x16x32_f16 v[170:173], v[198:201], v[18:21], v[38:41]
	v_mfma_f32_16x16x32_f16 v[174:177], v[198:201], v[26:29], v[42:45]
	v_mfma_f32_16x16x32_f16 v[178:181], v[194:197], v[18:21], v[38:41]
	v_mfma_f32_16x16x32_f16 v[182:185], v[194:197], v[26:29], v[42:45]
	v_mfma_f32_16x16x32_f16 v[170:173], v[190:193], v[22:25], v[170:173]
	v_mfma_f32_16x16x32_f16 v[174:177], v[190:193], v[30:33], v[174:177]
	v_mfma_f32_16x16x32_f16 v[178:181], v[186:189], v[22:25], v[178:181]
	v_mfma_f32_16x16x32_f16 v[182:185], v[186:189], v[30:33], v[182:185]
	ds_read_b128 v[186:189], v111 offset:26624
	ds_read_b128 v[190:193], v111 offset:24576
	ds_read_b128 v[194:197], v110 offset:26624
	ds_read_b128 v[198:201], v110 offset:24576
	s_nop 0
	v_exp_f32_e32 v74, v170
	s_nop 0
	v_exp_f32_e32 v75, v178
	v_exp_f32_e32 v117, v174
	v_exp_f32_e32 v170, v171
	v_exp_f32_e32 v174, v179
	v_exp_f32_e32 v171, v172
	v_exp_f32_e32 v172, v173
	v_exp_f32_e32 v178, v182
	v_exp_f32_e32 v175, v175
	v_exp_f32_e32 v179, v183
	v_exp_f32_e32 v180, v180
	v_exp_f32_e32 v176, v176
	v_exp_f32_e32 v182, v184
	v_exp_f32_e32 v173, v181
	v_cvt_pk_f16_f32 v170, v74, v170
	v_cvt_pk_f16_f32 v171, v171, v172
	v_cvt_pk_f16_f32 v172, v75, v174
	v_exp_f32_e32 v74, v177
	v_exp_f32_e32 v75, v185
	v_cvt_pk_f16_f32 v173, v180, v173
	v_cvt_pk_f16_f32 v174, v117, v175
	v_cvt_pk_f16_f32 v175, v176, v74
	v_cvt_pk_f16_f32 v176, v178, v179
	v_cvt_pk_f16_f32 v177, v182, v75
	s_waitcnt lgkmcnt(10)
	v_mfma_f32_16x16x32_f16 v[146:149], v[154:157], v[170:173], v[146:149]
	v_mfma_f32_16x16x32_f16 v[126:129], v[154:157], v[174:177], v[126:129]
	s_waitcnt lgkmcnt(8)
	v_mfma_f32_16x16x32_f16 v[138:141], v[158:161], v[170:173], v[138:141]
	v_mfma_f32_16x16x32_f16 v[130:133], v[158:161], v[174:177], v[130:133]
	s_waitcnt lgkmcnt(6)
	v_mfma_f32_16x16x32_f16 v[150:153], v[162:165], v[170:173], v[150:153]
	v_mfma_f32_16x16x32_f16 v[134:137], v[162:165], v[174:177], v[134:137]
	s_waitcnt lgkmcnt(4)
	v_mfma_f32_16x16x32_f16 v[70:73], v[166:169], v[170:173], v[70:73]
	v_mfma_f32_16x16x32_f16 v[122:125], v[166:169], v[174:177], v[122:125]
	ds_read_b64_tr_b16 v[154:155], v46 offset:57344
	ds_read_b64_tr_b16 v[156:157], v46 offset:59392
	ds_read_b64_tr_b16 v[158:159], v112 offset:57344
	ds_read_b64_tr_b16 v[160:161], v112 offset:59392
	ds_read_b64_tr_b16 v[162:163], v113 offset:57344
	ds_read_b64_tr_b16 v[164:165], v113 offset:59392
	ds_read_b64_tr_b16 v[166:167], v114 offset:57344
	ds_read_b64_tr_b16 v[168:169], v114 offset:59392
	v_mfma_f32_16x16x32_f16 v[142:145], v[34:37], v[170:173], v[142:145]
	v_mfma_f32_16x16x32_f16 v[118:121], v[34:37], v[174:177], v[118:121]
	s_waitcnt lgkmcnt(8)
	v_mfma_f32_16x16x32_f16 v[170:173], v[198:201], v[18:21], v[38:41]
	v_mfma_f32_16x16x32_f16 v[174:177], v[198:201], v[26:29], v[42:45]
	v_mfma_f32_16x16x32_f16 v[178:181], v[194:197], v[18:21], v[38:41]
	v_mfma_f32_16x16x32_f16 v[182:185], v[194:197], v[26:29], v[42:45]
	v_mfma_f32_16x16x32_f16 v[170:173], v[190:193], v[22:25], v[170:173]
	v_mfma_f32_16x16x32_f16 v[174:177], v[190:193], v[30:33], v[174:177]
	v_mfma_f32_16x16x32_f16 v[178:181], v[186:189], v[22:25], v[178:181]
	v_mfma_f32_16x16x32_f16 v[182:185], v[186:189], v[30:33], v[182:185]
	ds_read_b128 v[186:189], v111 offset:30720
	ds_read_b128 v[190:193], v111 offset:28672
	ds_read_b128 v[194:197], v110 offset:30720
	ds_read_b128 v[198:201], v110 offset:28672
	s_nop 0
	v_exp_f32_e32 v74, v170
	s_nop 0
	v_exp_f32_e32 v75, v178
	v_exp_f32_e32 v117, v174
	v_exp_f32_e32 v170, v171
	v_exp_f32_e32 v174, v179
	v_exp_f32_e32 v171, v172
	v_exp_f32_e32 v172, v173
	v_exp_f32_e32 v178, v182
	v_exp_f32_e32 v175, v175
	v_exp_f32_e32 v179, v183
	v_exp_f32_e32 v180, v180
	v_exp_f32_e32 v176, v176
	v_exp_f32_e32 v182, v184
	v_exp_f32_e32 v173, v181
	v_cvt_pk_f16_f32 v170, v74, v170
	v_cvt_pk_f16_f32 v171, v171, v172
	v_cvt_pk_f16_f32 v172, v75, v174
	v_exp_f32_e32 v74, v177
	v_exp_f32_e32 v75, v185
	v_cvt_pk_f16_f32 v173, v180, v173
	v_cvt_pk_f16_f32 v174, v117, v175
	v_cvt_pk_f16_f32 v175, v176, v74
	v_cvt_pk_f16_f32 v176, v178, v179
	v_cvt_pk_f16_f32 v177, v182, v75
	s_waitcnt lgkmcnt(10)
	v_mfma_f32_16x16x32_f16 v[146:149], v[154:157], v[170:173], v[146:149]
	v_mfma_f32_16x16x32_f16 v[126:129], v[154:157], v[174:177], v[126:129]
	s_waitcnt lgkmcnt(8)
	v_mfma_f32_16x16x32_f16 v[138:141], v[158:161], v[170:173], v[138:141]
	v_mfma_f32_16x16x32_f16 v[130:133], v[158:161], v[174:177], v[130:133]
	s_waitcnt lgkmcnt(6)
	v_mfma_f32_16x16x32_f16 v[150:153], v[162:165], v[170:173], v[150:153]
	v_mfma_f32_16x16x32_f16 v[134:137], v[162:165], v[174:177], v[134:137]
	s_waitcnt lgkmcnt(4)
	v_mfma_f32_16x16x32_f16 v[70:73], v[166:169], v[170:173], v[70:73]
	v_mfma_f32_16x16x32_f16 v[122:125], v[166:169], v[174:177], v[122:125]
	ds_read_b64_tr_b16 v[154:155], v46 offset:61440
	ds_read_b64_tr_b16 v[156:157], v46 offset:63488
	ds_read_b64_tr_b16 v[158:159], v112 offset:61440
	ds_read_b64_tr_b16 v[160:161], v112 offset:63488
	ds_read_b64_tr_b16 v[162:163], v113 offset:61440
	ds_read_b64_tr_b16 v[164:165], v113 offset:63488
	ds_read_b64_tr_b16 v[166:167], v114 offset:61440
	ds_read_b64_tr_b16 v[168:169], v114 offset:63488
	v_mfma_f32_16x16x32_f16 v[142:145], v[34:37], v[170:173], v[142:145]
	v_mfma_f32_16x16x32_f16 v[118:121], v[34:37], v[174:177], v[118:121]
	s_waitcnt lgkmcnt(8)
; __device__ __forceinline__ unsigned pkh(float lo, float hi) { f32x2 v = {lo, hi}; h16x2 h = __builtin_convertvector(v, h16x2); return __builtin_bit_cast(unsigned, h); }
; __device__ __forceinline__ h16x8 cat8(h16x4 lo, h16x4 hi) { return (h16x8){lo[0], lo[1], lo[2], lo[3], hi[0], hi[1], hi[2], hi[3]}; }
; template <bool CAUSAL, bool SHARED> ...
;     ...
;         la = __builtin_amdgcn_mfma_f32_16x16x32_f16(ones, pfa, la, 0, 0, 0); lb = __builtin_amdgcn_mfma_f32_16x16x32_f16(ones, pfb, lb, 0, 0, 0);
; #pragma unroll
;         for (int dt = 0; dt < 4; ++dt) {
;             const h16x8 fa = cat8(fal[dt], fah[dt]);
;             const h16x8 fb = SHARED ? fa : cat8(fbl[dt], fbh[dt]);
;             oa[dt] = __builtin_amdgcn_mfma_f32_16x16x32_f16(fa, pfa, oa[dt], 0, 0, 0);
;             ob[dt] = __builtin_amdgcn_mfma_f32_16x16x32_f16(fb, pfb, ob[dt], 0, 0, 0);
;         }
;     }
;     lsa_out = la[0]; lsb_out = lb[0];
; template <bool ENGINE, int ESTEPS>
; __device__ __forceinline__ void moba_sparse(const Frame& F, const Args& a, int rep) {
;     ...
;                 const float ila = 1.0f / lsa, ilb = 1.0f / lsb;
;                 if (!ENGINE) { asm volatile("" :: "v"(lsa), "v"(lsb), "v"(oa[0][0]), "v"(ob[0][0])); }
;                 { const size_t pia = ((size_t)bh * SEQ + ta) * 3 + (cea & 3u), pib = ((size_t)bh * SEQ + tb) * 3 + (ceb & 3u);
;                   u32x4 sa[2], sb[2];
; #pragma unroll
;                   for (int pr = 0; pr < 2; ++pr) { const int dt0 = 2 * pr; u32x2 x, y;
;                       x.x = pkh(oa[dt0][0] * ila, oa[dt0][1] * ila); x.y = pkh(oa[dt0][2] * ila, oa[dt0][3] * ila); y.x = pkh(oa[dt0 + 1][0] * ila, oa[dt0 + 1][1] * ila); y.y = pkh(oa[dt0 + 1][2] * ila, oa[dt0 + 1][3] * ila); sa[pr] = pair16(x, y);
;                       x.x = pkh(ob[dt0][0] * ilb, ob[dt0][1] * ilb); x.y = pkh(ob[dt0][2] * ilb, ob[dt0][3] * ilb); y.x = pkh(ob[dt0 + 1][0] * ilb, ob[dt0 + 1][1] * ilb); y.y = pkh(ob[dt0 + 1][2] * ilb, ob[dt0 + 1][3] * ilb); sb[pr] = pair16(x, y); }
;                   if (va && ENGINE) { *(u32x4*)(PO + pia * HD + pair16_dim(G, 0)) = sa[0]; *(u32x4*)(PO + pia * HD + pair16_dim(G, 2)) = sa[1]; if (G == 0) PL[pia] = lsa; }
;                   if (vb && ENGINE) { *(u32x4*)(PO + pib * HD + pair16_dim(G, 0)) = sb[0]; *(u32x4*)(PO + pib * HD + pair16_dim(G, 2)) = sb[1]; if (G == 0) PL[pib] = lsb; } }
	v_mfma_f32_16x16x32_f16 v[170:173], v[198:201], v[18:21], v[38:41]
	v_mfma_f32_16x16x32_f16 v[174:177], v[198:201], v[26:29], v[42:45]
	v_mfma_f32_16x16x32_f16 v[18:21], v[194:197], v[18:21], v[38:41]
	v_mfma_f32_16x16x32_f16 v[26:29], v[194:197], v[26:29], v[42:45]
	v_mfma_f32_16x16x32_f16 v[38:41], v[190:193], v[22:25], v[170:173]
	v_mfma_f32_16x16x32_f16 v[18:21], v[186:189], v[22:25], v[18:21]
	v_mfma_f32_16x16x32_f16 v[22:25], v[186:189], v[30:33], v[26:29]
	v_mfma_f32_16x16x32_f16 v[42:45], v[190:193], v[30:33], v[174:177]
	s_nop 4
	v_exp_f32_e32 v26, v38
	v_exp_f32_e32 v18, v18
	v_exp_f32_e32 v28, v22
	v_exp_f32_e32 v22, v39
	v_exp_f32_e32 v19, v19
	v_exp_f32_e32 v30, v23
	v_exp_f32_e32 v23, v40
	v_exp_f32_e32 v20, v20
	v_exp_f32_e32 v32, v24
	v_exp_f32_e32 v24, v41
	v_exp_f32_e32 v21, v21
	v_exp_f32_e32 v27, v42
	v_exp_f32_e32 v29, v43
	v_exp_f32_e32 v31, v44
	v_exp_f32_e32 v33, v45
	v_exp_f32_e32 v38, v25
	v_cvt_pk_f16_f32 v22, v26, v22
	v_cvt_pk_f16_f32 v23, v23, v24
	v_cvt_pk_f16_f32 v24, v18, v19
	v_cvt_pk_f16_f32 v25, v20, v21
	v_cvt_pk_f16_f32 v26, v27, v29
	v_cvt_pk_f16_f32 v27, v31, v33
	v_mfma_f32_16x16x32_f16 v[18:21], v[34:37], v[22:25], v[142:145]
	v_cvt_pk_f16_f32 v28, v28, v30
	v_cvt_pk_f16_f32 v29, v32, v38
	s_waitcnt lgkmcnt(6)
	v_mfma_f32_16x16x32_f16 v[30:33], v[154:157], v[22:25], v[146:149]
	v_mfma_f32_16x16x32_f16 v[38:41], v[154:157], v[26:29], v[126:129]
	s_nop 2
	v_div_scale_f32 v19, s[42:43], v18, v18, 1.0
	s_waitcnt lgkmcnt(4)
	v_mfma_f32_16x16x32_f16 v[42:45], v[158:161], v[22:25], v[138:141]
	v_mfma_f32_16x16x32_f16 v[126:129], v[158:161], v[26:29], v[130:133]
	s_waitcnt lgkmcnt(2)
	v_mfma_f32_16x16x32_f16 v[130:133], v[162:165], v[22:25], v[150:153]
	s_waitcnt lgkmcnt(0)
	v_mfma_f32_16x16x32_f16 v[70:73], v[166:169], v[22:25], v[70:73]
	v_mfma_f32_16x16x32_f16 v[20:23], v[34:37], v[26:29], v[118:121]
	v_mfma_f32_16x16x32_f16 v[134:137], v[162:165], v[26:29], v[134:137]
	v_mfma_f32_16x16x32_f16 v[122:125], v[166:169], v[26:29], v[122:125]
	s_nop 5
	v_rcp_f32_e32 v21, v19
	s_nop 0
	v_fma_f32 v22, -v19, v21, 1.0
	v_fmac_f32_e32 v21, v22, v21
	v_div_scale_f32 v22, vcc, 1.0, v18, 1.0
	v_mul_f32_e32 v23, v22, v21
	v_fma_f32 v24, -v19, v23, v22
	v_fmac_f32_e32 v23, v24, v21
	v_fma_f32 v19, -v19, v23, v22
	v_div_fmas_f32 v19, v19, v21, v23
	v_div_fixup_f32 v46, v19, v18, 1.0
	v_div_scale_f32 v19, s[42:43], v20, v20, 1.0
	v_rcp_f32_e32 v21, v19
	s_nop 0
	v_fma_f32 v22, -v19, v21, 1.0
	v_fmac_f32_e32 v21, v22, v21
	v_div_scale_f32 v22, vcc, 1.0, v20, 1.0
	v_mul_f32_e32 v23, v22, v21
	v_fma_f32 v24, -v19, v23, v22
	v_fmac_f32_e32 v23, v24, v21
	v_fma_f32 v19, -v19, v23, v22
	v_div_fmas_f32 v19, v19, v21, v23
	v_pk_mul_f32 v[22:23], v[46:47], v[30:31] op_sel_hi:[0,1]
	v_cvt_pk_f16_f32 v26, v22, v23
	v_pk_mul_f32 v[22:23], v[46:47], v[32:33] op_sel_hi:[0,1]
	v_cvt_pk_f16_f32 v27, v22, v23
	v_pk_mul_f32 v[22:23], v[46:47], v[42:43] op_sel_hi:[0,1]
	v_div_fixup_f32 v74, v19, v20, 1.0
	v_cvt_pk_f16_f32 v28, v22, v23
	v_pk_mul_f32 v[22:23], v[46:47], v[44:45] op_sel_hi:[0,1]
	v_cvt_pk_f16_f32 v29, v22, v23
	v_pk_mul_f32 v[22:23], v[38:39], v[74:75] op_sel_hi:[1,0]
	v_pk_mul_f32 v[24:25], v[40:41], v[74:75] op_sel_hi:[1,0]
	v_cvt_pk_f16_f32 v22, v22, v23
	v_cvt_pk_f16_f32 v23, v24, v25
	v_pk_mul_f32 v[24:25], v[126:127], v[74:75] op_sel_hi:[1,0]
	v_pk_mul_f32 v[30:31], v[128:129], v[74:75] op_sel_hi:[1,0]
	v_cvt_pk_f16_f32 v24, v24, v25
	v_cvt_pk_f16_f32 v25, v30, v31
	v_pk_mul_f32 v[30:31], v[46:47], v[130:131] op_sel_hi:[0,1]
	v_cvt_pk_f16_f32 v34, v30, v31
	v_pk_mul_f32 v[30:31], v[46:47], v[132:133] op_sel_hi:[0,1]
	v_cvt_pk_f16_f32 v35, v30, v31
	v_pk_mul_f32 v[30:31], v[46:47], v[70:71] op_sel_hi:[0,1]
	v_cvt_pk_f16_f32 v36, v30, v31
	v_pk_mul_f32 v[30:31], v[46:47], v[72:73] op_sel_hi:[0,1]
	v_cvt_pk_f16_f32 v37, v30, v31
	v_pk_mul_f32 v[30:31], v[134:135], v[74:75] op_sel_hi:[1,0]
	v_pk_mul_f32 v[32:33], v[136:137], v[74:75] op_sel_hi:[1,0]
	v_cvt_pk_f16_f32 v30, v30, v31
	v_cvt_pk_f16_f32 v31, v32, v33
	v_pk_mul_f32 v[32:33], v[122:123], v[74:75] op_sel_hi:[1,0]
	v_pk_mul_f32 v[38:39], v[124:125], v[74:75] op_sel_hi:[1,0]
	v_cvt_pk_f16_f32 v32, v32, v33
	v_cvt_pk_f16_f32 v33, v38, v39
	v_permlane16_swap_b32_e32 v26, v28
	v_permlane16_swap_b32_e32 v27, v29
	v_permlane16_swap_b32_e32 v22, v24
	v_permlane16_swap_b32_e32 v23, v25
	v_permlane16_swap_b32_e32 v34, v36
	v_permlane16_swap_b32_e32 v35, v37
	v_permlane16_swap_b32_e32 v30, v32
	v_permlane16_swap_b32_e32 v31, v33
	s_and_saveexec_b64 s[54:55], s[52:53]
	s_cbranch_execz .LBB0_1152
	v_lshrrev_b32_e32 v46, 2, v106
	v_lshl_add_u64 v[40:41], s[0:1], 0, v[46:47]
	v_and_b32_e32 v46, 3, v106
	v_mad_u64_u32 v[38:39], s[42:43], v40, 3, v[46:47]
	v_mad_i32_i24 v39, v41, 3, v39
	v_lshlrev_b64 v[40:41], 7, v[38:39]
	v_lshl_add_u64 v[40:41], v[62:63], 0, v[40:41]
	global_store_dwordx4 v[40:41], v[26:29], off sc1
	global_store_dwordx4 v[40:41], v[34:37], off offset:64 sc1
	s_and_b64 exec, exec, s[10:11]
	s_cbranch_execz .LBB0_1152
	v_lshl_add_u64 v[26:27], v[38:39], 2, s[62:63]
	global_store_dword v[26:27], v18, off
.LBB0_1152:
	s_or_b64 exec, exec, s[54:55]
	v_cmp_gt_i32_e32 vcc, s41, v51
	s_and_saveexec_b64 s[52:53], vcc
	s_cbranch_execz .LBB0_1155
	v_lshrrev_b32_e32 v46, 2, v105
	v_lshl_add_u64 v[26:27], s[0:1], 0, v[46:47]
	v_and_b32_e32 v46, 3, v105
	v_mad_u64_u32 v[18:19], s[42:43], v26, 3, v[46:47]
	v_mad_i32_i24 v19, v27, 3, v19
	v_lshlrev_b64 v[26:27], 7, v[18:19]
	v_lshl_add_u64 v[26:27], v[62:63], 0, v[26:27]
	global_store_dwordx4 v[26:27], v[22:25], off sc1
	global_store_dwordx4 v[26:27], v[30:33], off offset:64 sc1
	s_and_b64 exec, exec, s[10:11]
	s_cbranch_execz .LBB0_1155
	v_lshl_add_u64 v[18:19], v[18:19], 2, s[62:63]
	global_store_dword v[18:19], v20, off

; #define LAS __attribute__((address_space(3)))
;     __device__ __forceinline__ void operator()(f32x4 (&acc)[2][2][4][2], const Unit& u, const Order& S, int wr, int wc, int fr_, int fq_, LAS unsigned char* xl, int ui) const {
;     ...
;         for (int ai = 0; ai < 2; ++ai) {
;             const f32x4 ss4 = *(const LAS f32x4*)(cst + 1024 + trow0 + ai * HALF);
; #pragma unroll
;             for (int m = 0; m < 4; ++m) {
;                 const float sc = __builtin_amdgcn_rsqf(ss4[m] * (1.0f / DM) + EPS);
; #pragma unroll
;                 for (int bj = 0; bj < 2; ++bj)
; #pragma unroll
;                     for (int n = 0; n < 2; ++n) acc[ai][bj][m][n] *= sc;
;             }
;         }
;         LAS float* bnd = (LAS float*)xl;
;         const int tcol = wc * 32 + 4 * fq;
;         if (fr == 15) {
; #pragma unroll
;             for (int ai = 0; ai < 2; ++ai)
; #pragma unroll
;                 for (int bj = 0; bj < 2; ++bj)
; #pragma unroll
;                     for (int n = 0; n < 2; ++n) { *(LAS f32x4*)(bnd + ((2 * ai + wr) * 2 + 0) * 256 + bj * HALF + tcol + 16 * n) = acc[ai][bj][2][n]; *(LAS f32x4*)(bnd + ((2 * ai + wr) * 2 + 1) * 256 + bj * HALF + tcol + 16 * n) = acc[ai][bj][3][n]; }
;         }
;         { float* bq = bnd_g + (size_t)(u.pm * S.nN + u.pn) * 1024 + tcol;
;           if (wr == 0 && fr == 0) {
; #pragma unroll
;               for (int bj = 0; bj < 2; ++bj)
; #pragma unroll
;                   for (int n = 0; n < 2; ++n) { *(f32x4*)(bq + 0 * 256 + bj * HALF + 16 * n) = acc[0][bj][0][n]; *(f32x4*)(bq + 1 * 256 + bj * HALF + 16 * n) = acc[0][bj][1][n]; } }
;           if (wr == 1 && fr == 15) {
; #pragma unroll
;               for (int bj = 0; bj < 2; ++bj)
; #pragma unroll
;                   for (int n = 0; n < 2; ++n) { *(f32x4*)(bq + 2 * 256 + bj * HALF + 16 * n) = acc[1][bj][2][n]; *(f32x4*)(bq + 3 * 256 + bj * HALF + 16 * n) = acc[1][bj][3][n]; } } }
.LBB0_1421:
	s_or_b64 exec, exec, s[2:3]
	v_fmamk_f32 v66, v148, 0x3a800000, v211
	v_rsq_f32_e32 v66, v66
	s_mul_i32 s2, s14, 22
	s_add_i32 s2, s2, s4
	s_ashr_i32 s3, s2, 31
	v_pk_mul_f32 v[162:163], v[124:125], v[66:67] op_sel_hi:[1,0]
	v_pk_mul_f32 v[160:161], v[122:123], v[66:67] op_sel_hi:[1,0]
	v_pk_mul_f32 v[72:73], v[120:121], v[66:67] op_sel_hi:[1,0]
	v_pk_mul_f32 v[70:71], v[118:119], v[66:67] op_sel_hi:[1,0]
	v_pk_mul_f32 v[158:159], v[104:105], v[66:67] op_sel_hi:[1,0]
	v_fmamk_f32 v67, v149, 0x3a800000, v211
	v_rsq_f32_e32 v104, v67
	s_lshl_b64 s[2:3], s[2:3], 12
	s_add_u32 s2, s60, s2
	s_addc_u32 s3, s61, s3
	v_ashrrev_i32_e32 v203, 31, v202
	v_pk_mul_f32 v[148:149], v[98:99], v[104:105] op_sel_hi:[1,0]
	v_lshl_add_u64 v[98:99], v[202:203], 2, s[2:3]
	v_cmp_eq_u32_e64 s[2:3], 0, v164
	v_pk_mul_f32 v[156:157], v[102:103], v[66:67] op_sel_hi:[1,0]
	v_pk_mul_f32 v[76:77], v[76:77], v[66:67] op_sel_hi:[1,0]
	v_pk_mul_f32 v[74:75], v[74:75], v[66:67] op_sel_hi:[1,0]
	v_pk_mul_f32 v[154:155], v[112:113], v[104:105] op_sel_hi:[1,0]
	v_pk_mul_f32 v[152:153], v[110:111], v[104:105] op_sel_hi:[1,0]
	v_pk_mul_f32 v[68:69], v[108:109], v[104:105] op_sel_hi:[1,0]
	v_pk_mul_f32 v[66:67], v[106:107], v[104:105] op_sel_hi:[1,0]
	v_pk_mul_f32 v[150:151], v[100:101], v[104:105] op_sel_hi:[1,0]
	v_pk_mul_f32 v[80:81], v[80:81], v[104:105] op_sel_hi:[1,0]
	v_pk_mul_f32 v[78:79], v[78:79], v[104:105] op_sel_hi:[1,0]
	s_and_b64 s[6:7], s[38:39], s[2:3]
	s_and_saveexec_b64 s[2:3], s[6:7]
	s_cbranch_execz .LBB0_1423
	global_store_dwordx4 v[98:99], v[160:163], off sc1
	global_store_dwordx4 v[98:99], v[152:155], off offset:1024 sc1
	global_store_dwordx4 v[98:99], v[70:73], off offset:64 sc1
	global_store_dwordx4 v[98:99], v[66:69], off offset:1088 sc1
	global_store_dwordx4 v[98:99], v[156:159], off offset:512 sc1
	global_store_dwordx4 v[98:99], v[148:151], off offset:1536 sc1
	global_store_dwordx4 v[98:99], v[74:77], off offset:576 sc1
	global_store_dwordx4 v[98:99], v[78:81], off offset:1600 sc1
.LBB0_1423:
	s_or_b64 exec, exec, s[2:3]
	s_and_b64 s[6:7], s[26:27], vcc
	s_and_saveexec_b64 s[2:3], s[6:7]
	s_cbranch_execz .LBB0_1425
	global_store_dwordx4 v[98:99], v[86:89], off offset:2048 sc1
	global_store_dwordx4 v[98:99], v[94:97], off offset:3072 sc1
	global_store_dwordx4 v[98:99], v[18:21], off offset:2112 sc1
	global_store_dwordx4 v[98:99], v[30:33], off offset:3136 sc1
	global_store_dwordx4 v[98:99], v[82:85], off offset:2560 sc1
	global_store_dwordx4 v[98:99], v[90:93], off offset:3584 sc1
	global_store_dwordx4 v[98:99], v[22:25], off offset:2624 sc1
	global_store_dwordx4 v[98:99], v[26:29], off offset:3648 sc1

; __device__ __forceinline__ unsigned pkh(float lo, float hi) { f32x2 v = {lo, hi}; h16x2 h = __builtin_convertvector(v, h16x2); return __builtin_bit_cast(unsigned, h); }
; __device__ __forceinline__ unsigned pk8(float a, float b, float c, float d) { int w = __builtin_amdgcn_cvt_pk_fp8_f32(a, b, 0, false); w = __builtin_amdgcn_cvt_pk_fp8_f32(c, d, w, true); return (unsigned)w; }
;     __device__ __forceinline__ void operator()(f32x4 (&acc)[2][2][4][2], const Unit& u, const Order& S, int wr, int wc, int fr_, int fq_, LAS unsigned char*, int) const {
;     ...
;                 for (int bj = 0; bj < 2; ++bj) {
;                     const h16x8 bs = *(const h16x8*)(h16 + off + bj * HALF);
;                     f32x4 o0 = acc[ai][bj][m][0] * pre, o1 = acc[ai][bj][m][1] * pre;
; #pragma unroll
;                     for (int e = 0; e < 4; ++e) { o0[e] += (float)bs[e]; o1[e] += (float)bs[4 + e]; }
;                     if (out32) { if (!dry) { __builtin_nontemporal_store(o0, (f32x4*)(out32 + off + bj * HALF)); __builtin_nontemporal_store(o1, (f32x4*)(out32 + off + bj * HALF + 4)); } }
;                     else if (!dry) {
;                         sq += (o0[0] * o0[0] + o0[1] * o0[1]) + (o0[2] * o0[2] + o0[3] * o0[3]) + (o1[0] * o1[0] + o1[1] * o1[1]) + (o1[2] * o1[2] + o1[3] * o1[3]);
;                         u32x4 w; w.x = pkh(o0[0], o0[1]); w.y = pkh(o0[2], o0[3]); w.z = pkh(o1[0], o1[1]); w.w = pkh(o1[2], o1[3]);
;                         *(u32x4*)(h16 + off + bj * HALF) = w;
;                         if (h8) { u32x2 q; q.x = pk8(o0[0] * F8_SA, o0[1] * F8_SA, o0[2] * F8_SA, o0[3] * F8_SA); q.y = pk8(o1[0] * F8_SA, o1[1] * F8_SA, o1[2] * F8_SA, o1[3] * F8_SA); *(u32x2*)(h8 + off + bj * HALF) = q; } }
.LBB0_1595:
	s_andn2_b64 vcc, exec, s[4:5]
	s_nop 0
	v_mov_b32_e32 v160, 0
	s_cbranch_vccnz .LBB0_1597
	v_pk_mul_f32 v[160:161], v[126:127], v[126:127]
	v_pk_mul_f32 v[162:163], v[150:151], v[150:151]
	v_pk_fma_f32 v[160:161], v[122:123], v[122:123], v[160:161]
	v_pk_fma_f32 v[162:163], v[124:125], v[124:125], v[162:163]
	v_add_f32_e32 v160, v160, v161
	v_add_f32_e32 v160, v163, v160
	v_add_f32_e32 v160, v162, v160
	v_cvt_pk_f16_f32 v162, v122, v126
	v_cvt_pk_f16_f32 v163, v123, v127
	v_cvt_pk_f16_f32 v164, v125, v151
	v_cvt_pk_f16_f32 v165, v124, v150
	global_store_dwordx4 v[148:149], v[162:165], off sc1

; __device__ __forceinline__ unsigned pkh(float lo, float hi) { f32x2 v = {lo, hi}; h16x2 h = __builtin_convertvector(v, h16x2); return __builtin_bit_cast(unsigned, h); }
; __device__ __forceinline__ unsigned pk8(float a, float b, float c, float d) { int w = __builtin_amdgcn_cvt_pk_fp8_f32(a, b, 0, false); w = __builtin_amdgcn_cvt_pk_fp8_f32(c, d, w, true); return (unsigned)w; }
;     __device__ __forceinline__ void operator()(f32x4 (&acc)[2][2][4][2], const Unit& u, const Order& S, int wr, int wc, int fr_, int fq_, LAS unsigned char*, int) const {
;     ...
;                 for (int bj = 0; bj < 2; ++bj) {
;                     const h16x8 bs = *(const h16x8*)(h16 + off + bj * HALF);
;                     f32x4 o0 = acc[ai][bj][m][0] * pre, o1 = acc[ai][bj][m][1] * pre;
; #pragma unroll
;                     for (int e = 0; e < 4; ++e) { o0[e] += (float)bs[e]; o1[e] += (float)bs[4 + e]; }
;                     if (out32) { if (!dry) { __builtin_nontemporal_store(o0, (f32x4*)(out32 + off + bj * HALF)); __builtin_nontemporal_store(o1, (f32x4*)(out32 + off + bj * HALF + 4)); } }
;                     else if (!dry) {
;                         sq += (o0[0] * o0[0] + o0[1] * o0[1]) + (o0[2] * o0[2] + o0[3] * o0[3]) + (o1[0] * o1[0] + o1[1] * o1[1]) + (o1[2] * o1[2] + o1[3] * o1[3]);
;                         u32x4 w; w.x = pkh(o0[0], o0[1]); w.y = pkh(o0[2], o0[3]); w.z = pkh(o1[0], o1[1]); w.w = pkh(o1[2], o1[3]);
;                         *(u32x4*)(h16 + off + bj * HALF) = w;
;                         if (h8) { u32x2 q; q.x = pk8(o0[0] * F8_SA, o0[1] * F8_SA, o0[2] * F8_SA, o0[3] * F8_SA); q.y = pk8(o1[0] * F8_SA, o1[1] * F8_SA, o1[2] * F8_SA, o1[3] * F8_SA); *(u32x2*)(h8 + off + bj * HALF) = q; } }
.LBB0_1599:
	s_andn2_b64 vcc, exec, s[4:5]
	s_cbranch_vccnz .LBB0_1601
	v_pk_mul_f32 v[120:121], v[118:119], v[118:119]
	v_pk_mul_f32 v[122:123], v[112:113], v[112:113]
	v_pk_fma_f32 v[120:121], v[114:115], v[114:115], v[120:121]
	v_pk_fma_f32 v[122:123], v[116:117], v[116:117], v[122:123]
	v_add_f32_e32 v120, v120, v121
	v_add_f32_e32 v120, v123, v120
	v_add_f32_e32 v120, v122, v120
	v_add_f32_e32 v160, v160, v120
	v_cvt_pk_f16_f32 v118, v114, v118
	v_cvt_pk_f16_f32 v119, v115, v119
	v_cvt_pk_f16_f32 v120, v117, v113
	v_cvt_pk_f16_f32 v121, v116, v112
	global_store_dwordx4 v[148:149], v[118:121], off offset:256 sc1

; __device__ __forceinline__ unsigned pkh(float lo, float hi) { f32x2 v = {lo, hi}; h16x2 h = __builtin_convertvector(v, h16x2); return __builtin_bit_cast(unsigned, h); }
; __device__ __forceinline__ unsigned pk8(float a, float b, float c, float d) { int w = __builtin_amdgcn_cvt_pk_fp8_f32(a, b, 0, false); w = __builtin_amdgcn_cvt_pk_fp8_f32(c, d, w, true); return (unsigned)w; }
;     __device__ __forceinline__ void operator()(f32x4 (&acc)[2][2][4][2], const Unit& u, const Order& S, int wr, int wc, int fr_, int fq_, LAS unsigned char*, int) const {
;     ...
;                 for (int bj = 0; bj < 2; ++bj) {
;                     const h16x8 bs = *(const h16x8*)(h16 + off + bj * HALF);
;                     f32x4 o0 = acc[ai][bj][m][0] * pre, o1 = acc[ai][bj][m][1] * pre;
; #pragma unroll
;                     for (int e = 0; e < 4; ++e) { o0[e] += (float)bs[e]; o1[e] += (float)bs[4 + e]; }
;                     if (out32) { if (!dry) { __builtin_nontemporal_store(o0, (f32x4*)(out32 + off + bj * HALF)); __builtin_nontemporal_store(o1, (f32x4*)(out32 + off + bj * HALF + 4)); } }
;                     else if (!dry) {
;                         sq += (o0[0] * o0[0] + o0[1] * o0[1]) + (o0[2] * o0[2] + o0[3] * o0[3]) + (o1[0] * o1[0] + o1[1] * o1[1]) + (o1[2] * o1[2] + o1[3] * o1[3]);
;                         u32x4 w; w.x = pkh(o0[0], o0[1]); w.y = pkh(o0[2], o0[3]); w.z = pkh(o1[0], o1[1]); w.w = pkh(o1[2], o1[3]);
;                         *(u32x4*)(h16 + off + bj * HALF) = w;
;                         if (h8) { u32x2 q; q.x = pk8(o0[0] * F8_SA, o0[1] * F8_SA, o0[2] * F8_SA, o0[3] * F8_SA); q.y = pk8(o1[0] * F8_SA, o1[1] * F8_SA, o1[2] * F8_SA, o1[3] * F8_SA); *(u32x2*)(h8 + off + bj * HALF) = q; } }
.LBB0_1607:
	s_andn2_b64 vcc, exec, s[38:39]
	s_nop 0
	v_mov_b32_e32 v116, 0
	s_cbranch_vccnz .LBB0_1609
	v_pk_mul_f32 v[116:117], v[110:111], v[110:111]
	v_pk_mul_f32 v[118:119], v[114:115], v[114:115]
	v_pk_fma_f32 v[116:117], v[106:107], v[106:107], v[116:117]
	v_pk_fma_f32 v[118:119], v[108:109], v[108:109], v[118:119]
	v_add_f32_e32 v116, v116, v117
	v_add_f32_e32 v116, v119, v116
	v_add_f32_e32 v116, v118, v116
	v_cvt_pk_f16_f32 v118, v106, v110
	v_cvt_pk_f16_f32 v119, v107, v111
	v_cvt_pk_f16_f32 v120, v109, v115
	v_cvt_pk_f16_f32 v121, v108, v114
	global_store_dwordx4 v[112:113], v[118:121], off sc1

; __device__ __forceinline__ unsigned pkh(float lo, float hi) { f32x2 v = {lo, hi}; h16x2 h = __builtin_convertvector(v, h16x2); return __builtin_bit_cast(unsigned, h); }
; __device__ __forceinline__ unsigned pk8(float a, float b, float c, float d) { int w = __builtin_amdgcn_cvt_pk_fp8_f32(a, b, 0, false); w = __builtin_amdgcn_cvt_pk_fp8_f32(c, d, w, true); return (unsigned)w; }
;     __device__ __forceinline__ void operator()(f32x4 (&acc)[2][2][4][2], const Unit& u, const Order& S, int wr, int wc, int fr_, int fq_, LAS unsigned char*, int) const {
;     ...
;                 for (int bj = 0; bj < 2; ++bj) {
;                     const h16x8 bs = *(const h16x8*)(h16 + off + bj * HALF);
;                     f32x4 o0 = acc[ai][bj][m][0] * pre, o1 = acc[ai][bj][m][1] * pre;
; #pragma unroll
;                     for (int e = 0; e < 4; ++e) { o0[e] += (float)bs[e]; o1[e] += (float)bs[4 + e]; }
;                     if (out32) { if (!dry) { __builtin_nontemporal_store(o0, (f32x4*)(out32 + off + bj * HALF)); __builtin_nontemporal_store(o1, (f32x4*)(out32 + off + bj * HALF + 4)); } }
;                     else if (!dry) {
;                         sq += (o0[0] * o0[0] + o0[1] * o0[1]) + (o0[2] * o0[2] + o0[3] * o0[3]) + (o1[0] * o1[0] + o1[1] * o1[1]) + (o1[2] * o1[2] + o1[3] * o1[3]);
;                         u32x4 w; w.x = pkh(o0[0], o0[1]); w.y = pkh(o0[2], o0[3]); w.z = pkh(o1[0], o1[1]); w.w = pkh(o1[2], o1[3]);
;                         *(u32x4*)(h16 + off + bj * HALF) = w;
;                         if (h8) { u32x2 q; q.x = pk8(o0[0] * F8_SA, o0[1] * F8_SA, o0[2] * F8_SA, o0[3] * F8_SA); q.y = pk8(o1[0] * F8_SA, o1[1] * F8_SA, o1[2] * F8_SA, o1[3] * F8_SA); *(u32x2*)(h8 + off + bj * HALF) = q; } }
.LBB0_1613:
	v_pk_mul_f32 v[104:105], v[102:103], v[102:103]
	v_pk_mul_f32 v[106:107], v[96:97], v[96:97]
	v_pk_fma_f32 v[104:105], v[98:99], v[98:99], v[104:105]
	v_pk_fma_f32 v[106:107], v[100:101], v[100:101], v[106:107]
	v_add_f32_e32 v104, v104, v105
	v_add_f32_e32 v104, v107, v104
	v_add_f32_e32 v104, v106, v104
	v_add_f32_e32 v116, v116, v104
	v_cvt_pk_f16_f32 v102, v98, v102
	v_cvt_pk_f16_f32 v103, v99, v103
	v_cvt_pk_f16_f32 v104, v101, v97
	v_cvt_pk_f16_f32 v105, v100, v96
	global_store_dwordx4 v[112:113], v[102:105], off offset:256 sc1
	s_and_b64 vcc, exec, s[6:7]
	s_cbranch_vccnz .LBB0_1617

; __device__ __forceinline__ unsigned pkh(float lo, float hi) { f32x2 v = {lo, hi}; h16x2 h = __builtin_convertvector(v, h16x2); return __builtin_bit_cast(unsigned, h); }
; __device__ __forceinline__ unsigned pk8(float a, float b, float c, float d) { int w = __builtin_amdgcn_cvt_pk_fp8_f32(a, b, 0, false); w = __builtin_amdgcn_cvt_pk_fp8_f32(c, d, w, true); return (unsigned)w; }
;     __device__ __forceinline__ void operator()(f32x4 (&acc)[2][2][4][2], const Unit& u, const Order& S, int wr, int wc, int fr_, int fq_, LAS unsigned char*, int) const {
;     ...
;                 for (int bj = 0; bj < 2; ++bj) {
;                     const h16x8 bs = *(const h16x8*)(h16 + off + bj * HALF);
;                     f32x4 o0 = acc[ai][bj][m][0] * pre, o1 = acc[ai][bj][m][1] * pre;
; #pragma unroll
;                     for (int e = 0; e < 4; ++e) { o0[e] += (float)bs[e]; o1[e] += (float)bs[4 + e]; }
;                     if (out32) { if (!dry) { __builtin_nontemporal_store(o0, (f32x4*)(out32 + off + bj * HALF)); __builtin_nontemporal_store(o1, (f32x4*)(out32 + off + bj * HALF + 4)); } }
;                     else if (!dry) {
;                         sq += (o0[0] * o0[0] + o0[1] * o0[1]) + (o0[2] * o0[2] + o0[3] * o0[3]) + (o1[0] * o1[0] + o1[1] * o1[1]) + (o1[2] * o1[2] + o1[3] * o1[3]);
;                         u32x4 w; w.x = pkh(o0[0], o0[1]); w.y = pkh(o0[2], o0[3]); w.z = pkh(o1[0], o1[1]); w.w = pkh(o1[2], o1[3]);
;                         *(u32x4*)(h16 + off + bj * HALF) = w;
;                         if (h8) { u32x2 q; q.x = pk8(o0[0] * F8_SA, o0[1] * F8_SA, o0[2] * F8_SA, o0[3] * F8_SA); q.y = pk8(o1[0] * F8_SA, o1[1] * F8_SA, o1[2] * F8_SA, o1[3] * F8_SA); *(u32x2*)(h8 + off + bj * HALF) = q; } }
.LBB0_1619:
	s_andn2_b64 vcc, exec, s[38:39]
	s_nop 0
	v_mov_b32_e32 v100, 0
	s_cbranch_vccnz .LBB0_1621
	v_pk_mul_f32 v[100:101], v[94:95], v[94:95]
	v_pk_mul_f32 v[102:103], v[98:99], v[98:99]
	v_pk_fma_f32 v[100:101], v[90:91], v[90:91], v[100:101]
	v_pk_fma_f32 v[102:103], v[92:93], v[92:93], v[102:103]
	v_add_f32_e32 v100, v100, v101
	v_add_f32_e32 v100, v103, v100
	v_add_f32_e32 v100, v102, v100
	v_cvt_pk_f16_f32 v102, v90, v94
	v_cvt_pk_f16_f32 v103, v91, v95
	v_cvt_pk_f16_f32 v104, v93, v99
	v_cvt_pk_f16_f32 v105, v92, v98
	global_store_dwordx4 v[96:97], v[102:105], off sc1

; __device__ __forceinline__ unsigned pkh(float lo, float hi) { f32x2 v = {lo, hi}; h16x2 h = __builtin_convertvector(v, h16x2); return __builtin_bit_cast(unsigned, h); }
; __device__ __forceinline__ unsigned pk8(float a, float b, float c, float d) { int w = __builtin_amdgcn_cvt_pk_fp8_f32(a, b, 0, false); w = __builtin_amdgcn_cvt_pk_fp8_f32(c, d, w, true); return (unsigned)w; }
;     __device__ __forceinline__ void operator()(f32x4 (&acc)[2][2][4][2], const Unit& u, const Order& S, int wr, int wc, int fr_, int fq_, LAS unsigned char*, int) const {
;     ...
;                 for (int bj = 0; bj < 2; ++bj) {
;                     const h16x8 bs = *(const h16x8*)(h16 + off + bj * HALF);
;                     f32x4 o0 = acc[ai][bj][m][0] * pre, o1 = acc[ai][bj][m][1] * pre;
; #pragma unroll
;                     for (int e = 0; e < 4; ++e) { o0[e] += (float)bs[e]; o1[e] += (float)bs[4 + e]; }
;                     if (out32) { if (!dry) { __builtin_nontemporal_store(o0, (f32x4*)(out32 + off + bj * HALF)); __builtin_nontemporal_store(o1, (f32x4*)(out32 + off + bj * HALF + 4)); } }
;                     else if (!dry) {
;                         sq += (o0[0] * o0[0] + o0[1] * o0[1]) + (o0[2] * o0[2] + o0[3] * o0[3]) + (o1[0] * o1[0] + o1[1] * o1[1]) + (o1[2] * o1[2] + o1[3] * o1[3]);
;                         u32x4 w; w.x = pkh(o0[0], o0[1]); w.y = pkh(o0[2], o0[3]); w.z = pkh(o1[0], o1[1]); w.w = pkh(o1[2], o1[3]);
;                         *(u32x4*)(h16 + off + bj * HALF) = w;
;                         if (h8) { u32x2 q; q.x = pk8(o0[0] * F8_SA, o0[1] * F8_SA, o0[2] * F8_SA, o0[3] * F8_SA); q.y = pk8(o1[0] * F8_SA, o1[1] * F8_SA, o1[2] * F8_SA, o1[3] * F8_SA); *(u32x2*)(h8 + off + bj * HALF) = q; } }
.LBB0_1625:
	v_pk_mul_f32 v[88:89], v[86:87], v[86:87]
	v_pk_mul_f32 v[90:91], v[80:81], v[80:81]
	v_pk_fma_f32 v[88:89], v[82:83], v[82:83], v[88:89]
	v_pk_fma_f32 v[90:91], v[84:85], v[84:85], v[90:91]
	v_add_f32_e32 v88, v88, v89
	v_add_f32_e32 v88, v91, v88
	v_add_f32_e32 v88, v90, v88
	v_add_f32_e32 v100, v100, v88
	v_cvt_pk_f16_f32 v86, v82, v86
	v_cvt_pk_f16_f32 v87, v83, v87
	v_cvt_pk_f16_f32 v88, v85, v81
	v_cvt_pk_f16_f32 v89, v84, v80
	global_store_dwordx4 v[96:97], v[86:89], off offset:256 sc1
	s_and_b64 vcc, exec, s[6:7]
	s_cbranch_vccnz .LBB0_1629

; __device__ __forceinline__ unsigned pkh(float lo, float hi) { f32x2 v = {lo, hi}; h16x2 h = __builtin_convertvector(v, h16x2); return __builtin_bit_cast(unsigned, h); }
; __device__ __forceinline__ unsigned pk8(float a, float b, float c, float d) { int w = __builtin_amdgcn_cvt_pk_fp8_f32(a, b, 0, false); w = __builtin_amdgcn_cvt_pk_fp8_f32(c, d, w, true); return (unsigned)w; }
;     __device__ __forceinline__ void operator()(f32x4 (&acc)[2][2][4][2], const Unit& u, const Order& S, int wr, int wc, int fr_, int fq_, LAS unsigned char*, int) const {
;     ...
;                 for (int bj = 0; bj < 2; ++bj) {
;                     const h16x8 bs = *(const h16x8*)(h16 + off + bj * HALF);
;                     f32x4 o0 = acc[ai][bj][m][0] * pre, o1 = acc[ai][bj][m][1] * pre;
; #pragma unroll
;                     for (int e = 0; e < 4; ++e) { o0[e] += (float)bs[e]; o1[e] += (float)bs[4 + e]; }
;                     if (out32) { if (!dry) { __builtin_nontemporal_store(o0, (f32x4*)(out32 + off + bj * HALF)); __builtin_nontemporal_store(o1, (f32x4*)(out32 + off + bj * HALF + 4)); } }
;                     else if (!dry) {
;                         sq += (o0[0] * o0[0] + o0[1] * o0[1]) + (o0[2] * o0[2] + o0[3] * o0[3]) + (o1[0] * o1[0] + o1[1] * o1[1]) + (o1[2] * o1[2] + o1[3] * o1[3]);
;                         u32x4 w; w.x = pkh(o0[0], o0[1]); w.y = pkh(o0[2], o0[3]); w.z = pkh(o1[0], o1[1]); w.w = pkh(o1[2], o1[3]);
;                         *(u32x4*)(h16 + off + bj * HALF) = w;
;                         if (h8) { u32x2 q; q.x = pk8(o0[0] * F8_SA, o0[1] * F8_SA, o0[2] * F8_SA, o0[3] * F8_SA); q.y = pk8(o1[0] * F8_SA, o1[1] * F8_SA, o1[2] * F8_SA, o1[3] * F8_SA); *(u32x2*)(h8 + off + bj * HALF) = q; } }
.LBB0_1631:
	s_andn2_b64 vcc, exec, s[38:39]
	s_nop 0
	v_mov_b32_e32 v84, 0
	s_cbranch_vccnz .LBB0_1633
	v_pk_mul_f32 v[84:85], v[78:79], v[78:79]
	v_pk_mul_f32 v[86:87], v[82:83], v[82:83]
	v_pk_fma_f32 v[84:85], v[74:75], v[74:75], v[84:85]
	v_pk_fma_f32 v[86:87], v[76:77], v[76:77], v[86:87]
	v_add_f32_e32 v84, v84, v85
	v_add_f32_e32 v84, v87, v84
	v_add_f32_e32 v84, v86, v84
	v_cvt_pk_f16_f32 v86, v74, v78
	v_cvt_pk_f16_f32 v87, v75, v79
	v_cvt_pk_f16_f32 v88, v77, v83
	v_cvt_pk_f16_f32 v89, v76, v82
	global_store_dwordx4 v[80:81], v[86:89], off sc1

; __device__ __forceinline__ unsigned pkh(float lo, float hi) { f32x2 v = {lo, hi}; h16x2 h = __builtin_convertvector(v, h16x2); return __builtin_bit_cast(unsigned, h); }
; __device__ __forceinline__ unsigned pk8(float a, float b, float c, float d) { int w = __builtin_amdgcn_cvt_pk_fp8_f32(a, b, 0, false); w = __builtin_amdgcn_cvt_pk_fp8_f32(c, d, w, true); return (unsigned)w; }
;     __device__ __forceinline__ void operator()(f32x4 (&acc)[2][2][4][2], const Unit& u, const Order& S, int wr, int wc, int fr_, int fq_, LAS unsigned char*, int) const {
;     ...
;                 for (int bj = 0; bj < 2; ++bj) {
;                     const h16x8 bs = *(const h16x8*)(h16 + off + bj * HALF);
;                     f32x4 o0 = acc[ai][bj][m][0] * pre, o1 = acc[ai][bj][m][1] * pre;
; #pragma unroll
;                     for (int e = 0; e < 4; ++e) { o0[e] += (float)bs[e]; o1[e] += (float)bs[4 + e]; }
;                     if (out32) { if (!dry) { __builtin_nontemporal_store(o0, (f32x4*)(out32 + off + bj * HALF)); __builtin_nontemporal_store(o1, (f32x4*)(out32 + off + bj * HALF + 4)); } }
;                     else if (!dry) {
;                         sq += (o0[0] * o0[0] + o0[1] * o0[1]) + (o0[2] * o0[2] + o0[3] * o0[3]) + (o1[0] * o1[0] + o1[1] * o1[1]) + (o1[2] * o1[2] + o1[3] * o1[3]);
;                         u32x4 w; w.x = pkh(o0[0], o0[1]); w.y = pkh(o0[2], o0[3]); w.z = pkh(o1[0], o1[1]); w.w = pkh(o1[2], o1[3]);
;                         *(u32x4*)(h16 + off + bj * HALF) = w;
;                         if (h8) { u32x2 q; q.x = pk8(o0[0] * F8_SA, o0[1] * F8_SA, o0[2] * F8_SA, o0[3] * F8_SA); q.y = pk8(o1[0] * F8_SA, o1[1] * F8_SA, o1[2] * F8_SA, o1[3] * F8_SA); *(u32x2*)(h8 + off + bj * HALF) = q; } }
.LBB0_1637:
	v_pk_mul_f32 v[72:73], v[70:71], v[70:71]
	v_pk_mul_f32 v[74:75], v[64:65], v[64:65]
	v_pk_fma_f32 v[72:73], v[66:67], v[66:67], v[72:73]
	v_pk_fma_f32 v[74:75], v[68:69], v[68:69], v[74:75]
	v_add_f32_e32 v72, v72, v73
	v_add_f32_e32 v72, v75, v72
	v_add_f32_e32 v72, v74, v72
	v_add_f32_e32 v84, v84, v72
	v_cvt_pk_f16_f32 v70, v66, v70
	v_cvt_pk_f16_f32 v71, v67, v71
	v_cvt_pk_f16_f32 v72, v69, v65
	v_cvt_pk_f16_f32 v73, v68, v64
	global_store_dwordx4 v[80:81], v[70:73], off offset:256 sc1
	s_and_b64 vcc, exec, s[6:7]
	s_cbranch_vccnz .LBB0_1641

; __device__ __forceinline__ unsigned pkh(float lo, float hi) { f32x2 v = {lo, hi}; h16x2 h = __builtin_convertvector(v, h16x2); return __builtin_bit_cast(unsigned, h); }
; __device__ __forceinline__ unsigned pk8(float a, float b, float c, float d) { int w = __builtin_amdgcn_cvt_pk_fp8_f32(a, b, 0, false); w = __builtin_amdgcn_cvt_pk_fp8_f32(c, d, w, true); return (unsigned)w; }
;     __device__ __forceinline__ void operator()(f32x4 (&acc)[2][2][4][2], const Unit& u, const Order& S, int wr, int wc, int fr_, int fq_, LAS unsigned char*, int) const {
;     ...
;                 for (int bj = 0; bj < 2; ++bj) {
;                     const h16x8 bs = *(const h16x8*)(h16 + off + bj * HALF);
;                     f32x4 o0 = acc[ai][bj][m][0] * pre, o1 = acc[ai][bj][m][1] * pre;
; #pragma unroll
;                     for (int e = 0; e < 4; ++e) { o0[e] += (float)bs[e]; o1[e] += (float)bs[4 + e]; }
;                     if (out32) { if (!dry) { __builtin_nontemporal_store(o0, (f32x4*)(out32 + off + bj * HALF)); __builtin_nontemporal_store(o1, (f32x4*)(out32 + off + bj * HALF + 4)); } }
;                     else if (!dry) {
;                         sq += (o0[0] * o0[0] + o0[1] * o0[1]) + (o0[2] * o0[2] + o0[3] * o0[3]) + (o1[0] * o1[0] + o1[1] * o1[1]) + (o1[2] * o1[2] + o1[3] * o1[3]);
;                         u32x4 w; w.x = pkh(o0[0], o0[1]); w.y = pkh(o0[2], o0[3]); w.z = pkh(o1[0], o1[1]); w.w = pkh(o1[2], o1[3]);
;                         *(u32x4*)(h16 + off + bj * HALF) = w;
;                         if (h8) { u32x2 q; q.x = pk8(o0[0] * F8_SA, o0[1] * F8_SA, o0[2] * F8_SA, o0[3] * F8_SA); q.y = pk8(o1[0] * F8_SA, o1[1] * F8_SA, o1[2] * F8_SA, o1[3] * F8_SA); *(u32x2*)(h8 + off + bj * HALF) = q; } }
.LBB0_1643:
	s_andn2_b64 vcc, exec, s[38:39]
	s_nop 0
	v_mov_b32_e32 v68, 0
	s_cbranch_vccnz .LBB0_1645
	v_pk_mul_f32 v[68:69], v[62:63], v[62:63]
	v_pk_mul_f32 v[70:71], v[66:67], v[66:67]
	v_pk_fma_f32 v[68:69], v[58:59], v[58:59], v[68:69]
	v_pk_fma_f32 v[70:71], v[60:61], v[60:61], v[70:71]
	v_add_f32_e32 v68, v68, v69
	v_add_f32_e32 v68, v71, v68
	v_add_f32_e32 v68, v70, v68
	v_cvt_pk_f16_f32 v70, v58, v62
	v_cvt_pk_f16_f32 v71, v59, v63
	v_cvt_pk_f16_f32 v72, v61, v67
	v_cvt_pk_f16_f32 v73, v60, v66
	global_store_dwordx4 v[64:65], v[70:73], off sc1

; __device__ __forceinline__ unsigned pkh(float lo, float hi) { f32x2 v = {lo, hi}; h16x2 h = __builtin_convertvector(v, h16x2); return __builtin_bit_cast(unsigned, h); }
; __device__ __forceinline__ unsigned pk8(float a, float b, float c, float d) { int w = __builtin_amdgcn_cvt_pk_fp8_f32(a, b, 0, false); w = __builtin_amdgcn_cvt_pk_fp8_f32(c, d, w, true); return (unsigned)w; }
;     __device__ __forceinline__ void operator()(f32x4 (&acc)[2][2][4][2], const Unit& u, const Order& S, int wr, int wc, int fr_, int fq_, LAS unsigned char*, int) const {
;     ...
;                 for (int bj = 0; bj < 2; ++bj) {
;                     const h16x8 bs = *(const h16x8*)(h16 + off + bj * HALF);
;                     f32x4 o0 = acc[ai][bj][m][0] * pre, o1 = acc[ai][bj][m][1] * pre;
; #pragma unroll
;                     for (int e = 0; e < 4; ++e) { o0[e] += (float)bs[e]; o1[e] += (float)bs[4 + e]; }
;                     if (out32) { if (!dry) { __builtin_nontemporal_store(o0, (f32x4*)(out32 + off + bj * HALF)); __builtin_nontemporal_store(o1, (f32x4*)(out32 + off + bj * HALF + 4)); } }
;                     else if (!dry) {
;                         sq += (o0[0] * o0[0] + o0[1] * o0[1]) + (o0[2] * o0[2] + o0[3] * o0[3]) + (o1[0] * o1[0] + o1[1] * o1[1]) + (o1[2] * o1[2] + o1[3] * o1[3]);
;                         u32x4 w; w.x = pkh(o0[0], o0[1]); w.y = pkh(o0[2], o0[3]); w.z = pkh(o1[0], o1[1]); w.w = pkh(o1[2], o1[3]);
;                         *(u32x4*)(h16 + off + bj * HALF) = w;
;                         if (h8) { u32x2 q; q.x = pk8(o0[0] * F8_SA, o0[1] * F8_SA, o0[2] * F8_SA, o0[3] * F8_SA); q.y = pk8(o1[0] * F8_SA, o1[1] * F8_SA, o1[2] * F8_SA, o1[3] * F8_SA); *(u32x2*)(h8 + off + bj * HALF) = q; } }
.LBB0_1649:
	v_pk_mul_f32 v[56:57], v[54:55], v[54:55]
	v_pk_mul_f32 v[58:59], v[48:49], v[48:49]
	v_pk_fma_f32 v[56:57], v[50:51], v[50:51], v[56:57]
	v_pk_fma_f32 v[58:59], v[52:53], v[52:53], v[58:59]
	v_add_f32_e32 v56, v56, v57
	v_add_f32_e32 v56, v59, v56
	v_add_f32_e32 v56, v58, v56
	v_add_f32_e32 v68, v68, v56
	v_cvt_pk_f16_f32 v54, v50, v54
	v_cvt_pk_f16_f32 v55, v51, v55
	v_cvt_pk_f16_f32 v56, v53, v49
	v_cvt_pk_f16_f32 v57, v52, v48
	global_store_dwordx4 v[64:65], v[54:57], off offset:256 sc1
	s_and_b64 vcc, exec, s[6:7]
	s_cbranch_vccnz .LBB0_1653

; __device__ __forceinline__ unsigned pkh(float lo, float hi) { f32x2 v = {lo, hi}; h16x2 h = __builtin_convertvector(v, h16x2); return __builtin_bit_cast(unsigned, h); }
; __device__ __forceinline__ unsigned pk8(float a, float b, float c, float d) { int w = __builtin_amdgcn_cvt_pk_fp8_f32(a, b, 0, false); w = __builtin_amdgcn_cvt_pk_fp8_f32(c, d, w, true); return (unsigned)w; }
;     __device__ __forceinline__ void operator()(f32x4 (&acc)[2][2][4][2], const Unit& u, const Order& S, int wr, int wc, int fr_, int fq_, LAS unsigned char*, int) const {
;     ...
;                 for (int bj = 0; bj < 2; ++bj) {
;                     const h16x8 bs = *(const h16x8*)(h16 + off + bj * HALF);
;                     f32x4 o0 = acc[ai][bj][m][0] * pre, o1 = acc[ai][bj][m][1] * pre;
; #pragma unroll
;                     for (int e = 0; e < 4; ++e) { o0[e] += (float)bs[e]; o1[e] += (float)bs[4 + e]; }
;                     if (out32) { if (!dry) { __builtin_nontemporal_store(o0, (f32x4*)(out32 + off + bj * HALF)); __builtin_nontemporal_store(o1, (f32x4*)(out32 + off + bj * HALF + 4)); } }
;                     else if (!dry) {
;                         sq += (o0[0] * o0[0] + o0[1] * o0[1]) + (o0[2] * o0[2] + o0[3] * o0[3]) + (o1[0] * o1[0] + o1[1] * o1[1]) + (o1[2] * o1[2] + o1[3] * o1[3]);
;                         u32x4 w; w.x = pkh(o0[0], o0[1]); w.y = pkh(o0[2], o0[3]); w.z = pkh(o1[0], o1[1]); w.w = pkh(o1[2], o1[3]);
;                         *(u32x4*)(h16 + off + bj * HALF) = w;
;                         if (h8) { u32x2 q; q.x = pk8(o0[0] * F8_SA, o0[1] * F8_SA, o0[2] * F8_SA, o0[3] * F8_SA); q.y = pk8(o1[0] * F8_SA, o1[1] * F8_SA, o1[2] * F8_SA, o1[3] * F8_SA); *(u32x2*)(h8 + off + bj * HALF) = q; } }
.LBB0_1655:
	s_andn2_b64 vcc, exec, s[38:39]
	s_nop 0
	v_mov_b32_e32 v52, 0
	s_cbranch_vccnz .LBB0_1657
	v_pk_mul_f32 v[52:53], v[46:47], v[46:47]
	v_pk_mul_f32 v[54:55], v[50:51], v[50:51]
	v_pk_fma_f32 v[52:53], v[42:43], v[42:43], v[52:53]
	v_pk_fma_f32 v[54:55], v[44:45], v[44:45], v[54:55]
	v_add_f32_e32 v52, v52, v53
	v_add_f32_e32 v52, v55, v52
	v_add_f32_e32 v52, v54, v52
	v_cvt_pk_f16_f32 v54, v42, v46
	v_cvt_pk_f16_f32 v55, v43, v47
	v_cvt_pk_f16_f32 v56, v45, v51
	v_cvt_pk_f16_f32 v57, v44, v50
	global_store_dwordx4 v[48:49], v[54:57], off sc1

; __device__ __forceinline__ unsigned pkh(float lo, float hi) { f32x2 v = {lo, hi}; h16x2 h = __builtin_convertvector(v, h16x2); return __builtin_bit_cast(unsigned, h); }
; __device__ __forceinline__ unsigned pk8(float a, float b, float c, float d) { int w = __builtin_amdgcn_cvt_pk_fp8_f32(a, b, 0, false); w = __builtin_amdgcn_cvt_pk_fp8_f32(c, d, w, true); return (unsigned)w; }
;     __device__ __forceinline__ void operator()(f32x4 (&acc)[2][2][4][2], const Unit& u, const Order& S, int wr, int wc, int fr_, int fq_, LAS unsigned char*, int) const {
;     ...
;                 for (int bj = 0; bj < 2; ++bj) {
;                     const h16x8 bs = *(const h16x8*)(h16 + off + bj * HALF);
;                     f32x4 o0 = acc[ai][bj][m][0] * pre, o1 = acc[ai][bj][m][1] * pre;
; #pragma unroll
;                     for (int e = 0; e < 4; ++e) { o0[e] += (float)bs[e]; o1[e] += (float)bs[4 + e]; }
;                     if (out32) { if (!dry) { __builtin_nontemporal_store(o0, (f32x4*)(out32 + off + bj * HALF)); __builtin_nontemporal_store(o1, (f32x4*)(out32 + off + bj * HALF + 4)); } }
;                     else if (!dry) {
;                         sq += (o0[0] * o0[0] + o0[1] * o0[1]) + (o0[2] * o0[2] + o0[3] * o0[3]) + (o1[0] * o1[0] + o1[1] * o1[1]) + (o1[2] * o1[2] + o1[3] * o1[3]);
;                         u32x4 w; w.x = pkh(o0[0], o0[1]); w.y = pkh(o0[2], o0[3]); w.z = pkh(o1[0], o1[1]); w.w = pkh(o1[2], o1[3]);
;                         *(u32x4*)(h16 + off + bj * HALF) = w;
;                         if (h8) { u32x2 q; q.x = pk8(o0[0] * F8_SA, o0[1] * F8_SA, o0[2] * F8_SA, o0[3] * F8_SA); q.y = pk8(o1[0] * F8_SA, o1[1] * F8_SA, o1[2] * F8_SA, o1[3] * F8_SA); *(u32x2*)(h8 + off + bj * HALF) = q; } }
.LBB0_1661:
	v_pk_mul_f32 v[40:41], v[38:39], v[38:39]
	v_pk_mul_f32 v[42:43], v[32:33], v[32:33]
	v_pk_fma_f32 v[40:41], v[34:35], v[34:35], v[40:41]
	v_pk_fma_f32 v[42:43], v[36:37], v[36:37], v[42:43]
	v_add_f32_e32 v40, v40, v41
	v_add_f32_e32 v40, v43, v40
	v_add_f32_e32 v40, v42, v40
	v_add_f32_e32 v52, v52, v40
	v_cvt_pk_f16_f32 v38, v34, v38
	v_cvt_pk_f16_f32 v39, v35, v39
	v_cvt_pk_f16_f32 v40, v37, v33
	v_cvt_pk_f16_f32 v41, v36, v32
	global_store_dwordx4 v[48:49], v[38:41], off offset:256 sc1
	s_and_b64 vcc, exec, s[6:7]
	s_cbranch_vccnz .LBB0_1665

; __device__ __forceinline__ unsigned pkh(float lo, float hi) { f32x2 v = {lo, hi}; h16x2 h = __builtin_convertvector(v, h16x2); return __builtin_bit_cast(unsigned, h); }
; __device__ __forceinline__ unsigned pk8(float a, float b, float c, float d) { int w = __builtin_amdgcn_cvt_pk_fp8_f32(a, b, 0, false); w = __builtin_amdgcn_cvt_pk_fp8_f32(c, d, w, true); return (unsigned)w; }
;     __device__ __forceinline__ void operator()(f32x4 (&acc)[2][2][4][2], const Unit& u, const Order& S, int wr, int wc, int fr_, int fq_, LAS unsigned char*, int) const {
;     ...
;                 for (int bj = 0; bj < 2; ++bj) {
;                     const h16x8 bs = *(const h16x8*)(h16 + off + bj * HALF);
;                     f32x4 o0 = acc[ai][bj][m][0] * pre, o1 = acc[ai][bj][m][1] * pre;
; #pragma unroll
;                     for (int e = 0; e < 4; ++e) { o0[e] += (float)bs[e]; o1[e] += (float)bs[4 + e]; }
;                     if (out32) { if (!dry) { __builtin_nontemporal_store(o0, (f32x4*)(out32 + off + bj * HALF)); __builtin_nontemporal_store(o1, (f32x4*)(out32 + off + bj * HALF + 4)); } }
;                     else if (!dry) {
;                         sq += (o0[0] * o0[0] + o0[1] * o0[1]) + (o0[2] * o0[2] + o0[3] * o0[3]) + (o1[0] * o1[0] + o1[1] * o1[1]) + (o1[2] * o1[2] + o1[3] * o1[3]);
;                         u32x4 w; w.x = pkh(o0[0], o0[1]); w.y = pkh(o0[2], o0[3]); w.z = pkh(o1[0], o1[1]); w.w = pkh(o1[2], o1[3]);
;                         *(u32x4*)(h16 + off + bj * HALF) = w;
;                         if (h8) { u32x2 q; q.x = pk8(o0[0] * F8_SA, o0[1] * F8_SA, o0[2] * F8_SA, o0[3] * F8_SA); q.y = pk8(o1[0] * F8_SA, o1[1] * F8_SA, o1[2] * F8_SA, o1[3] * F8_SA); *(u32x2*)(h8 + off + bj * HALF) = q; } }
.LBB0_1667:
	s_andn2_b64 vcc, exec, s[38:39]
	s_nop 0
	v_mov_b32_e32 v36, 0
	s_cbranch_vccnz .LBB0_1669
	v_pk_mul_f32 v[36:37], v[30:31], v[30:31]
	v_pk_mul_f32 v[38:39], v[34:35], v[34:35]
	v_pk_fma_f32 v[36:37], v[26:27], v[26:27], v[36:37]
	v_pk_fma_f32 v[38:39], v[28:29], v[28:29], v[38:39]
	v_add_f32_e32 v36, v36, v37
	v_add_f32_e32 v36, v39, v36
	v_add_f32_e32 v36, v38, v36
	v_cvt_pk_f16_f32 v38, v26, v30
	v_cvt_pk_f16_f32 v39, v27, v31
	v_cvt_pk_f16_f32 v40, v29, v35
	v_cvt_pk_f16_f32 v41, v28, v34
	global_store_dwordx4 v[32:33], v[38:41], off sc1

; __device__ __forceinline__ unsigned pkh(float lo, float hi) { f32x2 v = {lo, hi}; h16x2 h = __builtin_convertvector(v, h16x2); return __builtin_bit_cast(unsigned, h); }
; __device__ __forceinline__ unsigned pk8(float a, float b, float c, float d) { int w = __builtin_amdgcn_cvt_pk_fp8_f32(a, b, 0, false); w = __builtin_amdgcn_cvt_pk_fp8_f32(c, d, w, true); return (unsigned)w; }
;     __device__ __forceinline__ void operator()(f32x4 (&acc)[2][2][4][2], const Unit& u, const Order& S, int wr, int wc, int fr_, int fq_, LAS unsigned char*, int) const {
;     ...
;                 for (int bj = 0; bj < 2; ++bj) {
;                     const h16x8 bs = *(const h16x8*)(h16 + off + bj * HALF);
;                     f32x4 o0 = acc[ai][bj][m][0] * pre, o1 = acc[ai][bj][m][1] * pre;
; #pragma unroll
;                     for (int e = 0; e < 4; ++e) { o0[e] += (float)bs[e]; o1[e] += (float)bs[4 + e]; }
;                     if (out32) { if (!dry) { __builtin_nontemporal_store(o0, (f32x4*)(out32 + off + bj * HALF)); __builtin_nontemporal_store(o1, (f32x4*)(out32 + off + bj * HALF + 4)); } }
;                     else if (!dry) {
;                         sq += (o0[0] * o0[0] + o0[1] * o0[1]) + (o0[2] * o0[2] + o0[3] * o0[3]) + (o1[0] * o1[0] + o1[1] * o1[1]) + (o1[2] * o1[2] + o1[3] * o1[3]);
;                         u32x4 w; w.x = pkh(o0[0], o0[1]); w.y = pkh(o0[2], o0[3]); w.z = pkh(o1[0], o1[1]); w.w = pkh(o1[2], o1[3]);
;                         *(u32x4*)(h16 + off + bj * HALF) = w;
;                         if (h8) { u32x2 q; q.x = pk8(o0[0] * F8_SA, o0[1] * F8_SA, o0[2] * F8_SA, o0[3] * F8_SA); q.y = pk8(o1[0] * F8_SA, o1[1] * F8_SA, o1[2] * F8_SA, o1[3] * F8_SA); *(u32x2*)(h8 + off + bj * HALF) = q; } }
.LBB0_1673:
	v_pk_mul_f32 v[24:25], v[22:23], v[22:23]
	v_pk_mul_f32 v[26:27], v[16:17], v[16:17]
	v_pk_fma_f32 v[24:25], v[18:19], v[18:19], v[24:25]
	v_pk_fma_f32 v[26:27], v[20:21], v[20:21], v[26:27]
	v_add_f32_e32 v24, v24, v25
	v_add_f32_e32 v24, v27, v24
	v_add_f32_e32 v24, v26, v24
	v_add_f32_e32 v36, v36, v24
	v_cvt_pk_f16_f32 v22, v18, v22
	v_cvt_pk_f16_f32 v23, v19, v23
	v_cvt_pk_f16_f32 v24, v21, v17
	v_cvt_pk_f16_f32 v25, v20, v16
	global_store_dwordx4 v[32:33], v[22:25], off offset:256 sc1
	s_and_b64 vcc, exec, s[6:7]
	s_cbranch_vccnz .LBB0_1677

; __device__ __forceinline__ unsigned pkh(float lo, float hi) { f32x2 v = {lo, hi}; h16x2 h = __builtin_convertvector(v, h16x2); return __builtin_bit_cast(unsigned, h); }
; __device__ __forceinline__ unsigned pk8(float a, float b, float c, float d) { int w = __builtin_amdgcn_cvt_pk_fp8_f32(a, b, 0, false); w = __builtin_amdgcn_cvt_pk_fp8_f32(c, d, w, true); return (unsigned)w; }
;     __device__ __forceinline__ void operator()(f32x4 (&acc)[2][2][4][2], const Unit& u, const Order& S, int wr, int wc, int fr_, int fq_, LAS unsigned char*, int) const {
;     ...
;                 for (int bj = 0; bj < 2; ++bj) {
;                     const h16x8 bs = *(const h16x8*)(h16 + off + bj * HALF);
;                     f32x4 o0 = acc[ai][bj][m][0] * pre, o1 = acc[ai][bj][m][1] * pre;
; #pragma unroll
;                     for (int e = 0; e < 4; ++e) { o0[e] += (float)bs[e]; o1[e] += (float)bs[4 + e]; }
;                     if (out32) { if (!dry) { __builtin_nontemporal_store(o0, (f32x4*)(out32 + off + bj * HALF)); __builtin_nontemporal_store(o1, (f32x4*)(out32 + off + bj * HALF + 4)); } }
;                     else if (!dry) {
;                         sq += (o0[0] * o0[0] + o0[1] * o0[1]) + (o0[2] * o0[2] + o0[3] * o0[3]) + (o1[0] * o1[0] + o1[1] * o1[1]) + (o1[2] * o1[2] + o1[3] * o1[3]);
;                         u32x4 w; w.x = pkh(o0[0], o0[1]); w.y = pkh(o0[2], o0[3]); w.z = pkh(o1[0], o1[1]); w.w = pkh(o1[2], o1[3]);
;                         *(u32x4*)(h16 + off + bj * HALF) = w;
;                         if (h8) { u32x2 q; q.x = pk8(o0[0] * F8_SA, o0[1] * F8_SA, o0[2] * F8_SA, o0[3] * F8_SA); q.y = pk8(o1[0] * F8_SA, o1[1] * F8_SA, o1[2] * F8_SA, o1[3] * F8_SA); *(u32x2*)(h8 + off + bj * HALF) = q; } }
.LBB0_1679:
	s_andn2_b64 vcc, exec, s[38:39]
	s_nop 0
	v_mov_b32_e32 v20, 0
	s_cbranch_vccnz .LBB0_1681
	v_pk_mul_f32 v[20:21], v[14:15], v[14:15]
	v_pk_mul_f32 v[22:23], v[18:19], v[18:19]
	v_pk_fma_f32 v[20:21], v[10:11], v[10:11], v[20:21]
	v_pk_fma_f32 v[22:23], v[12:13], v[12:13], v[22:23]
	v_add_f32_e32 v20, v20, v21
	v_add_f32_e32 v20, v23, v20
	v_add_f32_e32 v20, v22, v20
	v_cvt_pk_f16_f32 v22, v10, v14
	v_cvt_pk_f16_f32 v23, v11, v15
	v_cvt_pk_f16_f32 v24, v13, v19
	v_cvt_pk_f16_f32 v25, v12, v18
	global_store_dwordx4 v[16:17], v[22:25], off sc1

; __device__ __forceinline__ unsigned pkh(float lo, float hi) { f32x2 v = {lo, hi}; h16x2 h = __builtin_convertvector(v, h16x2); return __builtin_bit_cast(unsigned, h); }
; __device__ __forceinline__ unsigned pk8(float a, float b, float c, float d) { int w = __builtin_amdgcn_cvt_pk_fp8_f32(a, b, 0, false); w = __builtin_amdgcn_cvt_pk_fp8_f32(c, d, w, true); return (unsigned)w; }
;     __device__ __forceinline__ void operator()(f32x4 (&acc)[2][2][4][2], const Unit& u, const Order& S, int wr, int wc, int fr_, int fq_, LAS unsigned char*, int) const {
;     ...
;                 for (int bj = 0; bj < 2; ++bj) {
;                     const h16x8 bs = *(const h16x8*)(h16 + off + bj * HALF);
;                     f32x4 o0 = acc[ai][bj][m][0] * pre, o1 = acc[ai][bj][m][1] * pre;
; #pragma unroll
;                     for (int e = 0; e < 4; ++e) { o0[e] += (float)bs[e]; o1[e] += (float)bs[4 + e]; }
;                     if (out32) { if (!dry) { __builtin_nontemporal_store(o0, (f32x4*)(out32 + off + bj * HALF)); __builtin_nontemporal_store(o1, (f32x4*)(out32 + off + bj * HALF + 4)); } }
;                     else if (!dry) {
;                         sq += (o0[0] * o0[0] + o0[1] * o0[1]) + (o0[2] * o0[2] + o0[3] * o0[3]) + (o1[0] * o1[0] + o1[1] * o1[1]) + (o1[2] * o1[2] + o1[3] * o1[3]);
;                         u32x4 w; w.x = pkh(o0[0], o0[1]); w.y = pkh(o0[2], o0[3]); w.z = pkh(o1[0], o1[1]); w.w = pkh(o1[2], o1[3]);
;                         *(u32x4*)(h16 + off + bj * HALF) = w;
;                         if (h8) { u32x2 q; q.x = pk8(o0[0] * F8_SA, o0[1] * F8_SA, o0[2] * F8_SA, o0[3] * F8_SA); q.y = pk8(o1[0] * F8_SA, o1[1] * F8_SA, o1[2] * F8_SA, o1[3] * F8_SA); *(u32x2*)(h8 + off + bj * HALF) = q; } }
.LBB0_1686:
	v_pk_mul_f32 v[8:9], v[6:7], v[6:7]
	v_pk_mul_f32 v[10:11], v[0:1], v[0:1]
	v_pk_fma_f32 v[8:9], v[2:3], v[2:3], v[8:9]
	v_pk_fma_f32 v[10:11], v[4:5], v[4:5], v[10:11]
	v_add_f32_e32 v8, v8, v9
	v_add_f32_e32 v8, v11, v8
	v_add_f32_e32 v8, v10, v8
	v_add_f32_e32 v20, v20, v8
	v_cvt_pk_f16_f32 v6, v2, v6
	v_cvt_pk_f16_f32 v7, v3, v7
	v_cvt_pk_f16_f32 v8, v5, v1
	v_cvt_pk_f16_f32 v9, v4, v0
	global_store_dwordx4 v[16:17], v[6:9], off offset:256 sc1
	s_and_b64 vcc, exec, s[6:7]
	s_cbranch_vccnz .LBB0_1684
